# P11 (VALU-issue bound): 7 fewer VALU per token - packed reduction adds and the store base kept in SGPRs (SALU) instead of a per-token VALU add; bit-identical
# speedup vs baseline: 1.0029x; 1.0002x over previous
; DI f2_t cvt8lo(unsigned w) { return __builtin_amdgcn_cvt_pk_f32_fp8(w, false); }
; DI f2_t cvt8hi(unsigned w) { return __builtin_amdgcn_cvt_pk_f32_fp8(w, true); }
; DI void wave_lds_sync() { asm volatile("s_waitcnt lgkmcnt(0)" ::: "memory"); __builtin_amdgcn_wave_barrier(); }
; DI void phase11(const Params& p, char* smem, int rep) {
;     ...
;     for (int t = 0; t < 4; ++t) {
;       const int tok = __builtin_amdgcn_readfirstlane(c * 16 + w * 4 + t);
;       const int i0 = IDS[(size_t)tok * 128 + lane], i1 = IDS[(size_t)tok * 128 + 64 + lane];
;       const float a0 = ACT[(size_t)tok * 128 + lane], a1 = ACT[(size_t)tok * 128 + 64 + lane];
;       wave_lds_sync();
;       lw[(lane & 3) * 32 + (lane >> 2)] = i0; lw[(lane & 3) * 32 + 16 + (lane >> 2)] = i1;
;       lf[(lane & 3) * 32 + (lane >> 2)] = a0; lf[(lane & 3) * 32 + 16 + (lane >> 2)] = a1;
;       wave_lds_sync();
;       f2_t o[8];
; #pragma unroll
;       for (int i = 0; i < 8; ++i) o[i] = f2_t{0.f, 0.f};
;       const unsigned char* vb = V8 + s * 256 + l15 * 16;
; #pragma unroll
;       for (int batch = 0; batch < 2; ++batch) {
;         int ida[16]; float aa[16];
; #pragma unroll
;         for (int q = 0; q < 4; ++q) {
;           const int4 v = *(const int4*)(lw + g * 32 + batch * 16 + q * 4); ida[q * 4] = v.x; ida[q * 4 + 1] = v.y; ida[q * 4 + 2] = v.z; ida[q * 4 + 3] = v.w;
;           const float4 f = *(const float4*)(lf + g * 32 + batch * 16 + q * 4); aa[q * 4] = f.x; aa[q * 4 + 1] = f.y; aa[q * 4 + 2] = f.z; aa[q * 4 + 3] = f.w;
;         }
;         u32x4 rows[16];
; #pragma unroll
;         for (int k = 0; k < 16; ++k) rows[k] = *(const u32x4*)(vb + (size_t)ida[k] * 2048);
; #pragma unroll
;         for (int k = 0; k < 16; ++k) {
;           const f2_t a2 = {aa[k], aa[k]};
; #pragma unroll
;           for (int d = 0; d < 4; ++d) { const unsigned ww = rows[k][d]; o[2 * d] += a2 * cvt8lo(ww); o[2 * d + 1] += a2 * cvt8hi(ww); }
.Lp11_body:
	s_add_i32 s54, s34, 0
	s_lshl_b32 s46, s54, 12
	s_add_i32 s46, s46, s24
	s_add_i32 s55, s34, 1
	s_lshl_b32 s47, s55, 9
	s_add_u32 s42, s6, s47
	s_addc_u32 s43, s7, 0
	s_add_u32 s44, s8, s47
	s_addc_u32 s45, s9, 0
	global_load_dword v10, v3, s[42:43]
	global_load_dword v11, v3, s[42:43] offset:256
	global_load_dword v12, v3, s[44:45]
	global_load_dword v13, v3, s[44:45] offset:256
	s_waitcnt lgkmcnt(0)
	v_lshl_add_u32 v20, v20, 11, v2
	v_lshl_add_u32 v21, v21, 11, v2
	v_lshl_add_u32 v22, v22, 11, v2
	v_lshl_add_u32 v23, v23, 11, v2
	v_lshl_add_u32 v24, v24, 11, v2
	v_lshl_add_u32 v25, v25, 11, v2
	v_lshl_add_u32 v26, v26, 11, v2
	v_lshl_add_u32 v27, v27, 11, v2
	v_lshl_add_u32 v28, v28, 11, v2
	v_lshl_add_u32 v29, v29, 11, v2
	v_lshl_add_u32 v30, v30, 11, v2
	v_lshl_add_u32 v31, v31, 11, v2
	v_lshl_add_u32 v32, v32, 11, v2
	v_lshl_add_u32 v33, v33, 11, v2
	v_lshl_add_u32 v34, v34, 11, v2
	v_lshl_add_u32 v35, v35, 11, v2
	v_lshl_add_u32 v36, v36, 11, v2
	v_lshl_add_u32 v37, v37, 11, v2
	v_lshl_add_u32 v38, v38, 11, v2
	v_lshl_add_u32 v39, v39, 11, v2
	v_lshl_add_u32 v40, v40, 11, v2
	v_lshl_add_u32 v41, v41, 11, v2
	v_lshl_add_u32 v42, v42, 11, v2
	v_lshl_add_u32 v43, v43, 11, v2
	v_lshl_add_u32 v44, v44, 11, v2
	v_lshl_add_u32 v45, v45, 11, v2
	v_lshl_add_u32 v46, v46, 11, v2
	v_lshl_add_u32 v47, v47, 11, v2
	v_lshl_add_u32 v48, v48, 11, v2
	v_lshl_add_u32 v49, v49, 11, v2
	v_lshl_add_u32 v50, v50, 11, v2
	v_lshl_add_u32 v51, v51, 11, v2
	global_load_dwordx4 v[84:87], v20, s[20:21]
	global_load_dwordx4 v[88:91], v21, s[20:21]
	global_load_dwordx4 v[92:95], v22, s[20:21]
	global_load_dwordx4 v[96:99], v23, s[20:21]
	global_load_dwordx4 v[100:103], v24, s[20:21]
	global_load_dwordx4 v[104:107], v25, s[20:21]
	global_load_dwordx4 v[108:111], v26, s[20:21]
	global_load_dwordx4 v[112:115], v27, s[20:21]
	global_load_dwordx4 v[116:119], v28, s[20:21]
	global_load_dwordx4 v[120:123], v29, s[20:21]
	global_load_dwordx4 v[124:127], v30, s[20:21]
	global_load_dwordx4 v[128:131], v31, s[20:21]
	global_load_dwordx4 v[132:135], v32, s[20:21]
	global_load_dwordx4 v[136:139], v33, s[20:21]
	global_load_dwordx4 v[140:143], v34, s[20:21]
	global_load_dwordx4 v[144:147], v35, s[20:21]
	global_load_dwordx4 v[148:151], v36, s[20:21]
	global_load_dwordx4 v[152:155], v37, s[20:21]
	global_load_dwordx4 v[156:159], v38, s[20:21]
	global_load_dwordx4 v[160:163], v39, s[20:21]
	global_load_dwordx4 v[164:167], v40, s[20:21]
	global_load_dwordx4 v[168:171], v41, s[20:21]
	global_load_dwordx4 v[172:175], v42, s[20:21]
	global_load_dwordx4 v[176:179], v43, s[20:21]
	global_load_dwordx4 v[180:183], v44, s[20:21]
	global_load_dwordx4 v[184:187], v45, s[20:21]
	global_load_dwordx4 v[190:193], v46, s[20:21]
	global_load_dwordx4 v[194:197], v47, s[20:21]
	global_load_dwordx4 v[198:201], v48, s[20:21]
	global_load_dwordx4 v[202:205], v49, s[20:21]
	global_load_dwordx4 v[206:209], v50, s[20:21]
	global_load_dwordx4 v[210:213], v51, s[20:21]
	s_waitcnt vmcnt(31)
	v_cvt_pk_f32_fp8_e32 v[232:233], v84
	v_cvt_pk_f32_fp8_sdwa v[234:235], v84 src0_sel:WORD_1
	v_pk_fma_f32 v[216:217], v[52:53], v[232:233], 0 op_sel_hi:[0,1,0]
	v_pk_fma_f32 v[218:219], v[52:53], v[234:235], 0 op_sel_hi:[0,1,0]
	v_cvt_pk_f32_fp8_e32 v[236:237], v85
	v_cvt_pk_f32_fp8_sdwa v[238:239], v85 src0_sel:WORD_1
	v_pk_fma_f32 v[220:221], v[52:53], v[236:237], 0 op_sel_hi:[0,1,0]
	v_pk_fma_f32 v[222:223], v[52:53], v[238:239], 0 op_sel_hi:[0,1,0]
	v_cvt_pk_f32_fp8_e32 v[232:233], v86
	v_cvt_pk_f32_fp8_sdwa v[234:235], v86 src0_sel:WORD_1
	v_pk_fma_f32 v[224:225], v[52:53], v[232:233], 0 op_sel_hi:[0,1,0]
	v_pk_fma_f32 v[226:227], v[52:53], v[234:235], 0 op_sel_hi:[0,1,0]
	v_cvt_pk_f32_fp8_e32 v[236:237], v87
	v_cvt_pk_f32_fp8_sdwa v[238:239], v87 src0_sel:WORD_1
	v_pk_fma_f32 v[228:229], v[52:53], v[236:237], 0 op_sel_hi:[0,1,0]
	v_pk_fma_f32 v[230:231], v[52:53], v[238:239], 0 op_sel_hi:[0,1,0]
	s_waitcnt vmcnt(30)
	v_cvt_pk_f32_fp8_e32 v[232:233], v88
	v_cvt_pk_f32_fp8_sdwa v[234:235], v88 src0_sel:WORD_1
	v_pk_fma_f32 v[216:217], v[52:53], v[232:233], v[216:217] op_sel:[1,0,0]
	v_pk_fma_f32 v[218:219], v[52:53], v[234:235], v[218:219] op_sel:[1,0,0]
	v_cvt_pk_f32_fp8_e32 v[236:237], v89
	v_cvt_pk_f32_fp8_sdwa v[238:239], v89 src0_sel:WORD_1
	v_pk_fma_f32 v[220:221], v[52:53], v[236:237], v[220:221] op_sel:[1,0,0]
	v_pk_fma_f32 v[222:223], v[52:53], v[238:239], v[222:223] op_sel:[1,0,0]
	v_cvt_pk_f32_fp8_e32 v[232:233], v90
	v_cvt_pk_f32_fp8_sdwa v[234:235], v90 src0_sel:WORD_1
	v_pk_fma_f32 v[224:225], v[52:53], v[232:233], v[224:225] op_sel:[1,0,0]
	v_pk_fma_f32 v[226:227], v[52:53], v[234:235], v[226:227] op_sel:[1,0,0]
	v_cvt_pk_f32_fp8_e32 v[236:237], v91
	v_cvt_pk_f32_fp8_sdwa v[238:239], v91 src0_sel:WORD_1
	v_pk_fma_f32 v[228:229], v[52:53], v[236:237], v[228:229] op_sel:[1,0,0]
	v_pk_fma_f32 v[230:231], v[52:53], v[238:239], v[230:231] op_sel:[1,0,0]
	s_waitcnt vmcnt(29)
	v_cvt_pk_f32_fp8_e32 v[232:233], v92
	v_cvt_pk_f32_fp8_sdwa v[234:235], v92 src0_sel:WORD_1
	v_pk_fma_f32 v[216:217], v[54:55], v[232:233], v[216:217] op_sel_hi:[0,1,1]
	v_pk_fma_f32 v[218:219], v[54:55], v[234:235], v[218:219] op_sel_hi:[0,1,1]
	v_cvt_pk_f32_fp8_e32 v[236:237], v93
	v_cvt_pk_f32_fp8_sdwa v[238:239], v93 src0_sel:WORD_1
	v_pk_fma_f32 v[220:221], v[54:55], v[236:237], v[220:221] op_sel_hi:[0,1,1]
	v_pk_fma_f32 v[222:223], v[54:55], v[238:239], v[222:223] op_sel_hi:[0,1,1]
	v_cvt_pk_f32_fp8_e32 v[232:233], v94
	v_cvt_pk_f32_fp8_sdwa v[234:235], v94 src0_sel:WORD_1
	v_pk_fma_f32 v[224:225], v[54:55], v[232:233], v[224:225] op_sel_hi:[0,1,1]
	v_pk_fma_f32 v[226:227], v[54:55], v[234:235], v[226:227] op_sel_hi:[0,1,1]
	v_cvt_pk_f32_fp8_e32 v[236:237], v95
	v_cvt_pk_f32_fp8_sdwa v[238:239], v95 src0_sel:WORD_1
	v_pk_fma_f32 v[228:229], v[54:55], v[236:237], v[228:229] op_sel_hi:[0,1,1]
	v_pk_fma_f32 v[230:231], v[54:55], v[238:239], v[230:231] op_sel_hi:[0,1,1]
	s_waitcnt vmcnt(28)
; DI f2_t cvt8lo(unsigned w) { return __builtin_amdgcn_cvt_pk_f32_fp8(w, false); }
; DI f2_t cvt8hi(unsigned w) { return __builtin_amdgcn_cvt_pk_f32_fp8(w, true); }
; DI void phase11(const Params& p, char* smem, int rep) {
;     ...
; #pragma unroll
;         for (int k = 0; k < 16; ++k) {
;           const f2_t a2 = {aa[k], aa[k]};
; #pragma unroll
;           for (int d = 0; d < 4; ++d) { const unsigned ww = rows[k][d]; o[2 * d] += a2 * cvt8lo(ww); o[2 * d + 1] += a2 * cvt8hi(ww); }
	v_cvt_pk_f32_fp8_e32 v[232:233], v96
	v_cvt_pk_f32_fp8_sdwa v[234:235], v96 src0_sel:WORD_1
	v_pk_fma_f32 v[216:217], v[54:55], v[232:233], v[216:217] op_sel:[1,0,0]
	v_pk_fma_f32 v[218:219], v[54:55], v[234:235], v[218:219] op_sel:[1,0,0]
	v_cvt_pk_f32_fp8_e32 v[236:237], v97
	v_cvt_pk_f32_fp8_sdwa v[238:239], v97 src0_sel:WORD_1
	v_pk_fma_f32 v[220:221], v[54:55], v[236:237], v[220:221] op_sel:[1,0,0]
	v_pk_fma_f32 v[222:223], v[54:55], v[238:239], v[222:223] op_sel:[1,0,0]
	v_cvt_pk_f32_fp8_e32 v[232:233], v98
	v_cvt_pk_f32_fp8_sdwa v[234:235], v98 src0_sel:WORD_1
	v_pk_fma_f32 v[224:225], v[54:55], v[232:233], v[224:225] op_sel:[1,0,0]
	v_pk_fma_f32 v[226:227], v[54:55], v[234:235], v[226:227] op_sel:[1,0,0]
	v_cvt_pk_f32_fp8_e32 v[236:237], v99
	v_cvt_pk_f32_fp8_sdwa v[238:239], v99 src0_sel:WORD_1
	v_pk_fma_f32 v[228:229], v[54:55], v[236:237], v[228:229] op_sel:[1,0,0]
	v_pk_fma_f32 v[230:231], v[54:55], v[238:239], v[230:231] op_sel:[1,0,0]
	s_waitcnt vmcnt(27)
	v_cvt_pk_f32_fp8_e32 v[232:233], v100
	v_cvt_pk_f32_fp8_sdwa v[234:235], v100 src0_sel:WORD_1
	v_pk_fma_f32 v[216:217], v[56:57], v[232:233], v[216:217] op_sel_hi:[0,1,1]
	v_pk_fma_f32 v[218:219], v[56:57], v[234:235], v[218:219] op_sel_hi:[0,1,1]
	v_cvt_pk_f32_fp8_e32 v[236:237], v101
	v_cvt_pk_f32_fp8_sdwa v[238:239], v101 src0_sel:WORD_1
	v_pk_fma_f32 v[220:221], v[56:57], v[236:237], v[220:221] op_sel_hi:[0,1,1]
	v_pk_fma_f32 v[222:223], v[56:57], v[238:239], v[222:223] op_sel_hi:[0,1,1]
	v_cvt_pk_f32_fp8_e32 v[232:233], v102
	v_cvt_pk_f32_fp8_sdwa v[234:235], v102 src0_sel:WORD_1
	v_pk_fma_f32 v[224:225], v[56:57], v[232:233], v[224:225] op_sel_hi:[0,1,1]
	v_pk_fma_f32 v[226:227], v[56:57], v[234:235], v[226:227] op_sel_hi:[0,1,1]
	v_cvt_pk_f32_fp8_e32 v[236:237], v103
	v_cvt_pk_f32_fp8_sdwa v[238:239], v103 src0_sel:WORD_1
	v_pk_fma_f32 v[228:229], v[56:57], v[236:237], v[228:229] op_sel_hi:[0,1,1]
	v_pk_fma_f32 v[230:231], v[56:57], v[238:239], v[230:231] op_sel_hi:[0,1,1]
	s_waitcnt vmcnt(26)
	v_cvt_pk_f32_fp8_e32 v[232:233], v104
	v_cvt_pk_f32_fp8_sdwa v[234:235], v104 src0_sel:WORD_1
	v_pk_fma_f32 v[216:217], v[56:57], v[232:233], v[216:217] op_sel:[1,0,0]
	v_pk_fma_f32 v[218:219], v[56:57], v[234:235], v[218:219] op_sel:[1,0,0]
	v_cvt_pk_f32_fp8_e32 v[236:237], v105
	v_cvt_pk_f32_fp8_sdwa v[238:239], v105 src0_sel:WORD_1
	v_pk_fma_f32 v[220:221], v[56:57], v[236:237], v[220:221] op_sel:[1,0,0]
	v_pk_fma_f32 v[222:223], v[56:57], v[238:239], v[222:223] op_sel:[1,0,0]
	v_cvt_pk_f32_fp8_e32 v[232:233], v106
	v_cvt_pk_f32_fp8_sdwa v[234:235], v106 src0_sel:WORD_1
	v_pk_fma_f32 v[224:225], v[56:57], v[232:233], v[224:225] op_sel:[1,0,0]
	v_pk_fma_f32 v[226:227], v[56:57], v[234:235], v[226:227] op_sel:[1,0,0]
	v_cvt_pk_f32_fp8_e32 v[236:237], v107
	v_cvt_pk_f32_fp8_sdwa v[238:239], v107 src0_sel:WORD_1
	v_pk_fma_f32 v[228:229], v[56:57], v[236:237], v[228:229] op_sel:[1,0,0]
	v_pk_fma_f32 v[230:231], v[56:57], v[238:239], v[230:231] op_sel:[1,0,0]
	s_waitcnt vmcnt(25)
	v_cvt_pk_f32_fp8_e32 v[232:233], v108
	v_cvt_pk_f32_fp8_sdwa v[234:235], v108 src0_sel:WORD_1
	v_pk_fma_f32 v[216:217], v[58:59], v[232:233], v[216:217] op_sel_hi:[0,1,1]
	v_pk_fma_f32 v[218:219], v[58:59], v[234:235], v[218:219] op_sel_hi:[0,1,1]
	v_cvt_pk_f32_fp8_e32 v[236:237], v109
	v_cvt_pk_f32_fp8_sdwa v[238:239], v109 src0_sel:WORD_1
	v_pk_fma_f32 v[220:221], v[58:59], v[236:237], v[220:221] op_sel_hi:[0,1,1]
	v_pk_fma_f32 v[222:223], v[58:59], v[238:239], v[222:223] op_sel_hi:[0,1,1]
	v_cvt_pk_f32_fp8_e32 v[232:233], v110
	v_cvt_pk_f32_fp8_sdwa v[234:235], v110 src0_sel:WORD_1
	v_pk_fma_f32 v[224:225], v[58:59], v[232:233], v[224:225] op_sel_hi:[0,1,1]
	v_pk_fma_f32 v[226:227], v[58:59], v[234:235], v[226:227] op_sel_hi:[0,1,1]
	v_cvt_pk_f32_fp8_e32 v[236:237], v111
	v_cvt_pk_f32_fp8_sdwa v[238:239], v111 src0_sel:WORD_1
	v_pk_fma_f32 v[228:229], v[58:59], v[236:237], v[228:229] op_sel_hi:[0,1,1]
	v_pk_fma_f32 v[230:231], v[58:59], v[238:239], v[230:231] op_sel_hi:[0,1,1]
	s_waitcnt vmcnt(24)
	v_cvt_pk_f32_fp8_e32 v[232:233], v112
	v_cvt_pk_f32_fp8_sdwa v[234:235], v112 src0_sel:WORD_1
	v_pk_fma_f32 v[216:217], v[58:59], v[232:233], v[216:217] op_sel:[1,0,0]
	v_pk_fma_f32 v[218:219], v[58:59], v[234:235], v[218:219] op_sel:[1,0,0]
	v_cvt_pk_f32_fp8_e32 v[236:237], v113
	v_cvt_pk_f32_fp8_sdwa v[238:239], v113 src0_sel:WORD_1
	v_pk_fma_f32 v[220:221], v[58:59], v[236:237], v[220:221] op_sel:[1,0,0]
	v_pk_fma_f32 v[222:223], v[58:59], v[238:239], v[222:223] op_sel:[1,0,0]
	v_cvt_pk_f32_fp8_e32 v[232:233], v114
	v_cvt_pk_f32_fp8_sdwa v[234:235], v114 src0_sel:WORD_1
	v_pk_fma_f32 v[224:225], v[58:59], v[232:233], v[224:225] op_sel:[1,0,0]
	v_pk_fma_f32 v[226:227], v[58:59], v[234:235], v[226:227] op_sel:[1,0,0]
	v_cvt_pk_f32_fp8_e32 v[236:237], v115
	v_cvt_pk_f32_fp8_sdwa v[238:239], v115 src0_sel:WORD_1
	v_pk_fma_f32 v[228:229], v[58:59], v[236:237], v[228:229] op_sel:[1,0,0]
	v_pk_fma_f32 v[230:231], v[58:59], v[238:239], v[230:231] op_sel:[1,0,0]
	s_waitcnt vmcnt(23)
	v_cvt_pk_f32_fp8_e32 v[232:233], v116
	v_cvt_pk_f32_fp8_sdwa v[234:235], v116 src0_sel:WORD_1
	v_pk_fma_f32 v[216:217], v[60:61], v[232:233], v[216:217] op_sel_hi:[0,1,1]
	v_pk_fma_f32 v[218:219], v[60:61], v[234:235], v[218:219] op_sel_hi:[0,1,1]
	v_cvt_pk_f32_fp8_e32 v[236:237], v117
	v_cvt_pk_f32_fp8_sdwa v[238:239], v117 src0_sel:WORD_1
	v_pk_fma_f32 v[220:221], v[60:61], v[236:237], v[220:221] op_sel_hi:[0,1,1]
	v_pk_fma_f32 v[222:223], v[60:61], v[238:239], v[222:223] op_sel_hi:[0,1,1]
	v_cvt_pk_f32_fp8_e32 v[232:233], v118
	v_cvt_pk_f32_fp8_sdwa v[234:235], v118 src0_sel:WORD_1
	v_pk_fma_f32 v[224:225], v[60:61], v[232:233], v[224:225] op_sel_hi:[0,1,1]
	v_pk_fma_f32 v[226:227], v[60:61], v[234:235], v[226:227] op_sel_hi:[0,1,1]
	v_cvt_pk_f32_fp8_e32 v[236:237], v119
	v_cvt_pk_f32_fp8_sdwa v[238:239], v119 src0_sel:WORD_1
	v_pk_fma_f32 v[228:229], v[60:61], v[236:237], v[228:229] op_sel_hi:[0,1,1]
	v_pk_fma_f32 v[230:231], v[60:61], v[238:239], v[230:231] op_sel_hi:[0,1,1]
	s_waitcnt vmcnt(22)
; DI f2_t cvt8lo(unsigned w) { return __builtin_amdgcn_cvt_pk_f32_fp8(w, false); }
; DI f2_t cvt8hi(unsigned w) { return __builtin_amdgcn_cvt_pk_f32_fp8(w, true); }
; DI void phase11(const Params& p, char* smem, int rep) {
;     ...
; #pragma unroll
;         for (int k = 0; k < 16; ++k) {
;           const f2_t a2 = {aa[k], aa[k]};
; #pragma unroll
;           for (int d = 0; d < 4; ++d) { const unsigned ww = rows[k][d]; o[2 * d] += a2 * cvt8lo(ww); o[2 * d + 1] += a2 * cvt8hi(ww); }
	v_cvt_pk_f32_fp8_e32 v[232:233], v120
	v_cvt_pk_f32_fp8_sdwa v[234:235], v120 src0_sel:WORD_1
	v_pk_fma_f32 v[216:217], v[60:61], v[232:233], v[216:217] op_sel:[1,0,0]
	v_pk_fma_f32 v[218:219], v[60:61], v[234:235], v[218:219] op_sel:[1,0,0]
	v_cvt_pk_f32_fp8_e32 v[236:237], v121
	v_cvt_pk_f32_fp8_sdwa v[238:239], v121 src0_sel:WORD_1
	v_pk_fma_f32 v[220:221], v[60:61], v[236:237], v[220:221] op_sel:[1,0,0]
	v_pk_fma_f32 v[222:223], v[60:61], v[238:239], v[222:223] op_sel:[1,0,0]
	v_cvt_pk_f32_fp8_e32 v[232:233], v122
	v_cvt_pk_f32_fp8_sdwa v[234:235], v122 src0_sel:WORD_1
	v_pk_fma_f32 v[224:225], v[60:61], v[232:233], v[224:225] op_sel:[1,0,0]
	v_pk_fma_f32 v[226:227], v[60:61], v[234:235], v[226:227] op_sel:[1,0,0]
	v_cvt_pk_f32_fp8_e32 v[236:237], v123
	v_cvt_pk_f32_fp8_sdwa v[238:239], v123 src0_sel:WORD_1
	v_pk_fma_f32 v[228:229], v[60:61], v[236:237], v[228:229] op_sel:[1,0,0]
	v_pk_fma_f32 v[230:231], v[60:61], v[238:239], v[230:231] op_sel:[1,0,0]
	s_waitcnt vmcnt(21)
	v_cvt_pk_f32_fp8_e32 v[232:233], v124
	v_cvt_pk_f32_fp8_sdwa v[234:235], v124 src0_sel:WORD_1
	v_pk_fma_f32 v[216:217], v[62:63], v[232:233], v[216:217] op_sel_hi:[0,1,1]
	v_pk_fma_f32 v[218:219], v[62:63], v[234:235], v[218:219] op_sel_hi:[0,1,1]
	v_cvt_pk_f32_fp8_e32 v[236:237], v125
	v_cvt_pk_f32_fp8_sdwa v[238:239], v125 src0_sel:WORD_1
	v_pk_fma_f32 v[220:221], v[62:63], v[236:237], v[220:221] op_sel_hi:[0,1,1]
	v_pk_fma_f32 v[222:223], v[62:63], v[238:239], v[222:223] op_sel_hi:[0,1,1]
	v_cvt_pk_f32_fp8_e32 v[232:233], v126
	v_cvt_pk_f32_fp8_sdwa v[234:235], v126 src0_sel:WORD_1
	v_pk_fma_f32 v[224:225], v[62:63], v[232:233], v[224:225] op_sel_hi:[0,1,1]
	v_pk_fma_f32 v[226:227], v[62:63], v[234:235], v[226:227] op_sel_hi:[0,1,1]
	v_cvt_pk_f32_fp8_e32 v[236:237], v127
	v_cvt_pk_f32_fp8_sdwa v[238:239], v127 src0_sel:WORD_1
	v_pk_fma_f32 v[228:229], v[62:63], v[236:237], v[228:229] op_sel_hi:[0,1,1]
	v_pk_fma_f32 v[230:231], v[62:63], v[238:239], v[230:231] op_sel_hi:[0,1,1]
	s_waitcnt vmcnt(20)
	v_cvt_pk_f32_fp8_e32 v[232:233], v128
	v_cvt_pk_f32_fp8_sdwa v[234:235], v128 src0_sel:WORD_1
	v_pk_fma_f32 v[216:217], v[62:63], v[232:233], v[216:217] op_sel:[1,0,0]
	v_pk_fma_f32 v[218:219], v[62:63], v[234:235], v[218:219] op_sel:[1,0,0]
	v_cvt_pk_f32_fp8_e32 v[236:237], v129
	v_cvt_pk_f32_fp8_sdwa v[238:239], v129 src0_sel:WORD_1
	v_pk_fma_f32 v[220:221], v[62:63], v[236:237], v[220:221] op_sel:[1,0,0]
	v_pk_fma_f32 v[222:223], v[62:63], v[238:239], v[222:223] op_sel:[1,0,0]
	v_cvt_pk_f32_fp8_e32 v[232:233], v130
	v_cvt_pk_f32_fp8_sdwa v[234:235], v130 src0_sel:WORD_1
	v_pk_fma_f32 v[224:225], v[62:63], v[232:233], v[224:225] op_sel:[1,0,0]
	v_pk_fma_f32 v[226:227], v[62:63], v[234:235], v[226:227] op_sel:[1,0,0]
	v_cvt_pk_f32_fp8_e32 v[236:237], v131
	v_cvt_pk_f32_fp8_sdwa v[238:239], v131 src0_sel:WORD_1
	v_pk_fma_f32 v[228:229], v[62:63], v[236:237], v[228:229] op_sel:[1,0,0]
	v_pk_fma_f32 v[230:231], v[62:63], v[238:239], v[230:231] op_sel:[1,0,0]
	s_waitcnt vmcnt(19)
	v_cvt_pk_f32_fp8_e32 v[232:233], v132
	v_cvt_pk_f32_fp8_sdwa v[234:235], v132 src0_sel:WORD_1
	v_pk_fma_f32 v[216:217], v[64:65], v[232:233], v[216:217] op_sel_hi:[0,1,1]
	v_pk_fma_f32 v[218:219], v[64:65], v[234:235], v[218:219] op_sel_hi:[0,1,1]
	v_cvt_pk_f32_fp8_e32 v[236:237], v133
	v_cvt_pk_f32_fp8_sdwa v[238:239], v133 src0_sel:WORD_1
	v_pk_fma_f32 v[220:221], v[64:65], v[236:237], v[220:221] op_sel_hi:[0,1,1]
	v_pk_fma_f32 v[222:223], v[64:65], v[238:239], v[222:223] op_sel_hi:[0,1,1]
	v_cvt_pk_f32_fp8_e32 v[232:233], v134
	v_cvt_pk_f32_fp8_sdwa v[234:235], v134 src0_sel:WORD_1
	v_pk_fma_f32 v[224:225], v[64:65], v[232:233], v[224:225] op_sel_hi:[0,1,1]
	v_pk_fma_f32 v[226:227], v[64:65], v[234:235], v[226:227] op_sel_hi:[0,1,1]
	v_cvt_pk_f32_fp8_e32 v[236:237], v135
	v_cvt_pk_f32_fp8_sdwa v[238:239], v135 src0_sel:WORD_1
	v_pk_fma_f32 v[228:229], v[64:65], v[236:237], v[228:229] op_sel_hi:[0,1,1]
	v_pk_fma_f32 v[230:231], v[64:65], v[238:239], v[230:231] op_sel_hi:[0,1,1]
	s_waitcnt vmcnt(18)
	v_cvt_pk_f32_fp8_e32 v[232:233], v136
	v_cvt_pk_f32_fp8_sdwa v[234:235], v136 src0_sel:WORD_1
	v_pk_fma_f32 v[216:217], v[64:65], v[232:233], v[216:217] op_sel:[1,0,0]
	v_pk_fma_f32 v[218:219], v[64:65], v[234:235], v[218:219] op_sel:[1,0,0]
	v_cvt_pk_f32_fp8_e32 v[236:237], v137
	v_cvt_pk_f32_fp8_sdwa v[238:239], v137 src0_sel:WORD_1
	v_pk_fma_f32 v[220:221], v[64:65], v[236:237], v[220:221] op_sel:[1,0,0]
	v_pk_fma_f32 v[222:223], v[64:65], v[238:239], v[222:223] op_sel:[1,0,0]
	v_cvt_pk_f32_fp8_e32 v[232:233], v138
	v_cvt_pk_f32_fp8_sdwa v[234:235], v138 src0_sel:WORD_1
	v_pk_fma_f32 v[224:225], v[64:65], v[232:233], v[224:225] op_sel:[1,0,0]
	v_pk_fma_f32 v[226:227], v[64:65], v[234:235], v[226:227] op_sel:[1,0,0]
	v_cvt_pk_f32_fp8_e32 v[236:237], v139
	v_cvt_pk_f32_fp8_sdwa v[238:239], v139 src0_sel:WORD_1
	v_pk_fma_f32 v[228:229], v[64:65], v[236:237], v[228:229] op_sel:[1,0,0]
	v_pk_fma_f32 v[230:231], v[64:65], v[238:239], v[230:231] op_sel:[1,0,0]
	s_waitcnt vmcnt(17)
	v_cvt_pk_f32_fp8_e32 v[232:233], v140
	v_cvt_pk_f32_fp8_sdwa v[234:235], v140 src0_sel:WORD_1
	v_pk_fma_f32 v[216:217], v[66:67], v[232:233], v[216:217] op_sel_hi:[0,1,1]
	v_pk_fma_f32 v[218:219], v[66:67], v[234:235], v[218:219] op_sel_hi:[0,1,1]
	v_cvt_pk_f32_fp8_e32 v[236:237], v141
	v_cvt_pk_f32_fp8_sdwa v[238:239], v141 src0_sel:WORD_1
	v_pk_fma_f32 v[220:221], v[66:67], v[236:237], v[220:221] op_sel_hi:[0,1,1]
	v_pk_fma_f32 v[222:223], v[66:67], v[238:239], v[222:223] op_sel_hi:[0,1,1]
	v_cvt_pk_f32_fp8_e32 v[232:233], v142
	v_cvt_pk_f32_fp8_sdwa v[234:235], v142 src0_sel:WORD_1
	v_pk_fma_f32 v[224:225], v[66:67], v[232:233], v[224:225] op_sel_hi:[0,1,1]
	v_pk_fma_f32 v[226:227], v[66:67], v[234:235], v[226:227] op_sel_hi:[0,1,1]
	v_cvt_pk_f32_fp8_e32 v[236:237], v143
	v_cvt_pk_f32_fp8_sdwa v[238:239], v143 src0_sel:WORD_1
	v_pk_fma_f32 v[228:229], v[66:67], v[236:237], v[228:229] op_sel_hi:[0,1,1]
	v_pk_fma_f32 v[230:231], v[66:67], v[238:239], v[230:231] op_sel_hi:[0,1,1]
	s_waitcnt vmcnt(16)
; DI f2_t cvt8lo(unsigned w) { return __builtin_amdgcn_cvt_pk_f32_fp8(w, false); }
; DI f2_t cvt8hi(unsigned w) { return __builtin_amdgcn_cvt_pk_f32_fp8(w, true); }
; DI void wave_lds_sync() { asm volatile("s_waitcnt lgkmcnt(0)" ::: "memory"); __builtin_amdgcn_wave_barrier(); }
; DI void phase11(const Params& p, char* smem, int rep) {
;     ...
;       const int tok = __builtin_amdgcn_readfirstlane(c * 16 + w * 4 + t);
;       const int i0 = IDS[(size_t)tok * 128 + lane], i1 = IDS[(size_t)tok * 128 + 64 + lane];
;       const float a0 = ACT[(size_t)tok * 128 + lane], a1 = ACT[(size_t)tok * 128 + 64 + lane];
;       wave_lds_sync();
;       lw[(lane & 3) * 32 + (lane >> 2)] = i0; lw[(lane & 3) * 32 + 16 + (lane >> 2)] = i1;
;       lf[(lane & 3) * 32 + (lane >> 2)] = a0; lf[(lane & 3) * 32 + 16 + (lane >> 2)] = a1;
;       wave_lds_sync();
;     ...
; #pragma unroll
;         for (int k = 0; k < 16; ++k) {
;           const f2_t a2 = {aa[k], aa[k]};
; #pragma unroll
;           for (int d = 0; d < 4; ++d) { const unsigned ww = rows[k][d]; o[2 * d] += a2 * cvt8lo(ww); o[2 * d + 1] += a2 * cvt8hi(ww); }
	v_cvt_pk_f32_fp8_e32 v[232:233], v144
	v_cvt_pk_f32_fp8_sdwa v[234:235], v144 src0_sel:WORD_1
	v_pk_fma_f32 v[216:217], v[66:67], v[232:233], v[216:217] op_sel:[1,0,0]
	v_pk_fma_f32 v[218:219], v[66:67], v[234:235], v[218:219] op_sel:[1,0,0]
	v_cvt_pk_f32_fp8_e32 v[236:237], v145
	v_cvt_pk_f32_fp8_sdwa v[238:239], v145 src0_sel:WORD_1
	v_pk_fma_f32 v[220:221], v[66:67], v[236:237], v[220:221] op_sel:[1,0,0]
	v_pk_fma_f32 v[222:223], v[66:67], v[238:239], v[222:223] op_sel:[1,0,0]
	v_cvt_pk_f32_fp8_e32 v[232:233], v146
	v_cvt_pk_f32_fp8_sdwa v[234:235], v146 src0_sel:WORD_1
	v_pk_fma_f32 v[224:225], v[66:67], v[232:233], v[224:225] op_sel:[1,0,0]
	v_pk_fma_f32 v[226:227], v[66:67], v[234:235], v[226:227] op_sel:[1,0,0]
	v_cvt_pk_f32_fp8_e32 v[236:237], v147
	v_cvt_pk_f32_fp8_sdwa v[238:239], v147 src0_sel:WORD_1
	v_pk_fma_f32 v[228:229], v[66:67], v[236:237], v[228:229] op_sel:[1,0,0]
	v_pk_fma_f32 v[230:231], v[66:67], v[238:239], v[230:231] op_sel:[1,0,0]
	ds_write2_b32 v5, v10, v11 offset0:4 offset1:20
	ds_write2_b32 v5, v12, v13 offset0:132 offset1:148
	s_waitcnt lgkmcnt(0)
	ds_read_b128 v[20:23], v6 offset:16
	ds_read_b128 v[24:27], v6 offset:32
	ds_read_b128 v[28:31], v6 offset:48
	ds_read_b128 v[32:35], v6 offset:64
	ds_read_b128 v[36:39], v6 offset:80
	ds_read_b128 v[40:43], v6 offset:96
	ds_read_b128 v[44:47], v6 offset:112
	ds_read_b128 v[48:51], v6 offset:128
	s_waitcnt vmcnt(15)
	v_cvt_pk_f32_fp8_e32 v[232:233], v148
	v_cvt_pk_f32_fp8_sdwa v[234:235], v148 src0_sel:WORD_1
	v_pk_fma_f32 v[216:217], v[68:69], v[232:233], v[216:217] op_sel_hi:[0,1,1]
	v_pk_fma_f32 v[218:219], v[68:69], v[234:235], v[218:219] op_sel_hi:[0,1,1]
	v_cvt_pk_f32_fp8_e32 v[236:237], v149
	v_cvt_pk_f32_fp8_sdwa v[238:239], v149 src0_sel:WORD_1
	v_pk_fma_f32 v[220:221], v[68:69], v[236:237], v[220:221] op_sel_hi:[0,1,1]
	v_pk_fma_f32 v[222:223], v[68:69], v[238:239], v[222:223] op_sel_hi:[0,1,1]
	v_cvt_pk_f32_fp8_e32 v[232:233], v150
	v_cvt_pk_f32_fp8_sdwa v[234:235], v150 src0_sel:WORD_1
	v_pk_fma_f32 v[224:225], v[68:69], v[232:233], v[224:225] op_sel_hi:[0,1,1]
	v_pk_fma_f32 v[226:227], v[68:69], v[234:235], v[226:227] op_sel_hi:[0,1,1]
	v_cvt_pk_f32_fp8_e32 v[236:237], v151
	v_cvt_pk_f32_fp8_sdwa v[238:239], v151 src0_sel:WORD_1
	v_pk_fma_f32 v[228:229], v[68:69], v[236:237], v[228:229] op_sel_hi:[0,1,1]
	v_pk_fma_f32 v[230:231], v[68:69], v[238:239], v[230:231] op_sel_hi:[0,1,1]
	s_waitcnt vmcnt(14)
	v_cvt_pk_f32_fp8_e32 v[232:233], v152
	v_cvt_pk_f32_fp8_sdwa v[234:235], v152 src0_sel:WORD_1
	v_pk_fma_f32 v[216:217], v[68:69], v[232:233], v[216:217] op_sel:[1,0,0]
	v_pk_fma_f32 v[218:219], v[68:69], v[234:235], v[218:219] op_sel:[1,0,0]
	v_cvt_pk_f32_fp8_e32 v[236:237], v153
	v_cvt_pk_f32_fp8_sdwa v[238:239], v153 src0_sel:WORD_1
	v_pk_fma_f32 v[220:221], v[68:69], v[236:237], v[220:221] op_sel:[1,0,0]
	v_pk_fma_f32 v[222:223], v[68:69], v[238:239], v[222:223] op_sel:[1,0,0]
	v_cvt_pk_f32_fp8_e32 v[232:233], v154
	v_cvt_pk_f32_fp8_sdwa v[234:235], v154 src0_sel:WORD_1
	v_pk_fma_f32 v[224:225], v[68:69], v[232:233], v[224:225] op_sel:[1,0,0]
	v_pk_fma_f32 v[226:227], v[68:69], v[234:235], v[226:227] op_sel:[1,0,0]
	v_cvt_pk_f32_fp8_e32 v[236:237], v155
	v_cvt_pk_f32_fp8_sdwa v[238:239], v155 src0_sel:WORD_1
	v_pk_fma_f32 v[228:229], v[68:69], v[236:237], v[228:229] op_sel:[1,0,0]
	v_pk_fma_f32 v[230:231], v[68:69], v[238:239], v[230:231] op_sel:[1,0,0]
	s_waitcnt vmcnt(13)
	v_cvt_pk_f32_fp8_e32 v[232:233], v156
	v_cvt_pk_f32_fp8_sdwa v[234:235], v156 src0_sel:WORD_1
	v_pk_fma_f32 v[216:217], v[70:71], v[232:233], v[216:217] op_sel_hi:[0,1,1]
	v_pk_fma_f32 v[218:219], v[70:71], v[234:235], v[218:219] op_sel_hi:[0,1,1]
	v_cvt_pk_f32_fp8_e32 v[236:237], v157
	v_cvt_pk_f32_fp8_sdwa v[238:239], v157 src0_sel:WORD_1
	v_pk_fma_f32 v[220:221], v[70:71], v[236:237], v[220:221] op_sel_hi:[0,1,1]
	v_pk_fma_f32 v[222:223], v[70:71], v[238:239], v[222:223] op_sel_hi:[0,1,1]
	v_cvt_pk_f32_fp8_e32 v[232:233], v158
	v_cvt_pk_f32_fp8_sdwa v[234:235], v158 src0_sel:WORD_1
	v_pk_fma_f32 v[224:225], v[70:71], v[232:233], v[224:225] op_sel_hi:[0,1,1]
	v_pk_fma_f32 v[226:227], v[70:71], v[234:235], v[226:227] op_sel_hi:[0,1,1]
	v_cvt_pk_f32_fp8_e32 v[236:237], v159
	v_cvt_pk_f32_fp8_sdwa v[238:239], v159 src0_sel:WORD_1
	v_pk_fma_f32 v[228:229], v[70:71], v[236:237], v[228:229] op_sel_hi:[0,1,1]
	v_pk_fma_f32 v[230:231], v[70:71], v[238:239], v[230:231] op_sel_hi:[0,1,1]
	s_waitcnt vmcnt(12)
	v_cvt_pk_f32_fp8_e32 v[232:233], v160
	v_cvt_pk_f32_fp8_sdwa v[234:235], v160 src0_sel:WORD_1
	v_pk_fma_f32 v[216:217], v[70:71], v[232:233], v[216:217] op_sel:[1,0,0]
	v_pk_fma_f32 v[218:219], v[70:71], v[234:235], v[218:219] op_sel:[1,0,0]
	v_cvt_pk_f32_fp8_e32 v[236:237], v161
	v_cvt_pk_f32_fp8_sdwa v[238:239], v161 src0_sel:WORD_1
	v_pk_fma_f32 v[220:221], v[70:71], v[236:237], v[220:221] op_sel:[1,0,0]
	v_pk_fma_f32 v[222:223], v[70:71], v[238:239], v[222:223] op_sel:[1,0,0]
	v_cvt_pk_f32_fp8_e32 v[232:233], v162
	v_cvt_pk_f32_fp8_sdwa v[234:235], v162 src0_sel:WORD_1
	v_pk_fma_f32 v[224:225], v[70:71], v[232:233], v[224:225] op_sel:[1,0,0]
	v_pk_fma_f32 v[226:227], v[70:71], v[234:235], v[226:227] op_sel:[1,0,0]
	v_cvt_pk_f32_fp8_e32 v[236:237], v163
	v_cvt_pk_f32_fp8_sdwa v[238:239], v163 src0_sel:WORD_1
	v_pk_fma_f32 v[228:229], v[70:71], v[236:237], v[228:229] op_sel:[1,0,0]
	v_pk_fma_f32 v[230:231], v[70:71], v[238:239], v[230:231] op_sel:[1,0,0]
	s_waitcnt vmcnt(11)
; DI f2_t cvt8lo(unsigned w) { return __builtin_amdgcn_cvt_pk_f32_fp8(w, false); }
; DI f2_t cvt8hi(unsigned w) { return __builtin_amdgcn_cvt_pk_f32_fp8(w, true); }
; DI void phase11(const Params& p, char* smem, int rep) {
;     ...
; #pragma unroll
;         for (int k = 0; k < 16; ++k) {
;           const f2_t a2 = {aa[k], aa[k]};
; #pragma unroll
;           for (int d = 0; d < 4; ++d) { const unsigned ww = rows[k][d]; o[2 * d] += a2 * cvt8lo(ww); o[2 * d + 1] += a2 * cvt8hi(ww); }
	v_cvt_pk_f32_fp8_e32 v[232:233], v164
	v_cvt_pk_f32_fp8_sdwa v[234:235], v164 src0_sel:WORD_1
	v_pk_fma_f32 v[216:217], v[72:73], v[232:233], v[216:217] op_sel_hi:[0,1,1]
	v_pk_fma_f32 v[218:219], v[72:73], v[234:235], v[218:219] op_sel_hi:[0,1,1]
	v_cvt_pk_f32_fp8_e32 v[236:237], v165
	v_cvt_pk_f32_fp8_sdwa v[238:239], v165 src0_sel:WORD_1
	v_pk_fma_f32 v[220:221], v[72:73], v[236:237], v[220:221] op_sel_hi:[0,1,1]
	v_pk_fma_f32 v[222:223], v[72:73], v[238:239], v[222:223] op_sel_hi:[0,1,1]
	v_cvt_pk_f32_fp8_e32 v[232:233], v166
	v_cvt_pk_f32_fp8_sdwa v[234:235], v166 src0_sel:WORD_1
	v_pk_fma_f32 v[224:225], v[72:73], v[232:233], v[224:225] op_sel_hi:[0,1,1]
	v_pk_fma_f32 v[226:227], v[72:73], v[234:235], v[226:227] op_sel_hi:[0,1,1]
	v_cvt_pk_f32_fp8_e32 v[236:237], v167
	v_cvt_pk_f32_fp8_sdwa v[238:239], v167 src0_sel:WORD_1
	v_pk_fma_f32 v[228:229], v[72:73], v[236:237], v[228:229] op_sel_hi:[0,1,1]
	v_pk_fma_f32 v[230:231], v[72:73], v[238:239], v[230:231] op_sel_hi:[0,1,1]
	s_waitcnt vmcnt(10)
	v_cvt_pk_f32_fp8_e32 v[232:233], v168
	v_cvt_pk_f32_fp8_sdwa v[234:235], v168 src0_sel:WORD_1
	v_pk_fma_f32 v[216:217], v[72:73], v[232:233], v[216:217] op_sel:[1,0,0]
	v_pk_fma_f32 v[218:219], v[72:73], v[234:235], v[218:219] op_sel:[1,0,0]
	v_cvt_pk_f32_fp8_e32 v[236:237], v169
	v_cvt_pk_f32_fp8_sdwa v[238:239], v169 src0_sel:WORD_1
	v_pk_fma_f32 v[220:221], v[72:73], v[236:237], v[220:221] op_sel:[1,0,0]
	v_pk_fma_f32 v[222:223], v[72:73], v[238:239], v[222:223] op_sel:[1,0,0]
	v_cvt_pk_f32_fp8_e32 v[232:233], v170
	v_cvt_pk_f32_fp8_sdwa v[234:235], v170 src0_sel:WORD_1
	v_pk_fma_f32 v[224:225], v[72:73], v[232:233], v[224:225] op_sel:[1,0,0]
	v_pk_fma_f32 v[226:227], v[72:73], v[234:235], v[226:227] op_sel:[1,0,0]
	v_cvt_pk_f32_fp8_e32 v[236:237], v171
	v_cvt_pk_f32_fp8_sdwa v[238:239], v171 src0_sel:WORD_1
	v_pk_fma_f32 v[228:229], v[72:73], v[236:237], v[228:229] op_sel:[1,0,0]
	v_pk_fma_f32 v[230:231], v[72:73], v[238:239], v[230:231] op_sel:[1,0,0]
	s_waitcnt vmcnt(9)
	v_cvt_pk_f32_fp8_e32 v[232:233], v172
	v_cvt_pk_f32_fp8_sdwa v[234:235], v172 src0_sel:WORD_1
	v_pk_fma_f32 v[216:217], v[74:75], v[232:233], v[216:217] op_sel_hi:[0,1,1]
	v_pk_fma_f32 v[218:219], v[74:75], v[234:235], v[218:219] op_sel_hi:[0,1,1]
	v_cvt_pk_f32_fp8_e32 v[236:237], v173
	v_cvt_pk_f32_fp8_sdwa v[238:239], v173 src0_sel:WORD_1
	v_pk_fma_f32 v[220:221], v[74:75], v[236:237], v[220:221] op_sel_hi:[0,1,1]
	v_pk_fma_f32 v[222:223], v[74:75], v[238:239], v[222:223] op_sel_hi:[0,1,1]
	v_cvt_pk_f32_fp8_e32 v[232:233], v174
	v_cvt_pk_f32_fp8_sdwa v[234:235], v174 src0_sel:WORD_1
	v_pk_fma_f32 v[224:225], v[74:75], v[232:233], v[224:225] op_sel_hi:[0,1,1]
	v_pk_fma_f32 v[226:227], v[74:75], v[234:235], v[226:227] op_sel_hi:[0,1,1]
	v_cvt_pk_f32_fp8_e32 v[236:237], v175
	v_cvt_pk_f32_fp8_sdwa v[238:239], v175 src0_sel:WORD_1
	v_pk_fma_f32 v[228:229], v[74:75], v[236:237], v[228:229] op_sel_hi:[0,1,1]
	v_pk_fma_f32 v[230:231], v[74:75], v[238:239], v[230:231] op_sel_hi:[0,1,1]
	s_waitcnt vmcnt(8)
	v_cvt_pk_f32_fp8_e32 v[232:233], v176
	v_cvt_pk_f32_fp8_sdwa v[234:235], v176 src0_sel:WORD_1
	v_pk_fma_f32 v[216:217], v[74:75], v[232:233], v[216:217] op_sel:[1,0,0]
	v_pk_fma_f32 v[218:219], v[74:75], v[234:235], v[218:219] op_sel:[1,0,0]
	v_cvt_pk_f32_fp8_e32 v[236:237], v177
	v_cvt_pk_f32_fp8_sdwa v[238:239], v177 src0_sel:WORD_1
	v_pk_fma_f32 v[220:221], v[74:75], v[236:237], v[220:221] op_sel:[1,0,0]
	v_pk_fma_f32 v[222:223], v[74:75], v[238:239], v[222:223] op_sel:[1,0,0]
	v_cvt_pk_f32_fp8_e32 v[232:233], v178
	v_cvt_pk_f32_fp8_sdwa v[234:235], v178 src0_sel:WORD_1
	v_pk_fma_f32 v[224:225], v[74:75], v[232:233], v[224:225] op_sel:[1,0,0]
	v_pk_fma_f32 v[226:227], v[74:75], v[234:235], v[226:227] op_sel:[1,0,0]
	v_cvt_pk_f32_fp8_e32 v[236:237], v179
	v_cvt_pk_f32_fp8_sdwa v[238:239], v179 src0_sel:WORD_1
	v_pk_fma_f32 v[228:229], v[74:75], v[236:237], v[228:229] op_sel:[1,0,0]
	v_pk_fma_f32 v[230:231], v[74:75], v[238:239], v[230:231] op_sel:[1,0,0]
	s_waitcnt vmcnt(7)
	v_cvt_pk_f32_fp8_e32 v[232:233], v180
	v_cvt_pk_f32_fp8_sdwa v[234:235], v180 src0_sel:WORD_1
	v_pk_fma_f32 v[216:217], v[76:77], v[232:233], v[216:217] op_sel_hi:[0,1,1]
	v_pk_fma_f32 v[218:219], v[76:77], v[234:235], v[218:219] op_sel_hi:[0,1,1]
	v_cvt_pk_f32_fp8_e32 v[236:237], v181
	v_cvt_pk_f32_fp8_sdwa v[238:239], v181 src0_sel:WORD_1
	v_pk_fma_f32 v[220:221], v[76:77], v[236:237], v[220:221] op_sel_hi:[0,1,1]
	v_pk_fma_f32 v[222:223], v[76:77], v[238:239], v[222:223] op_sel_hi:[0,1,1]
	v_cvt_pk_f32_fp8_e32 v[232:233], v182
	v_cvt_pk_f32_fp8_sdwa v[234:235], v182 src0_sel:WORD_1
	v_pk_fma_f32 v[224:225], v[76:77], v[232:233], v[224:225] op_sel_hi:[0,1,1]
	v_pk_fma_f32 v[226:227], v[76:77], v[234:235], v[226:227] op_sel_hi:[0,1,1]
	v_cvt_pk_f32_fp8_e32 v[236:237], v183
	v_cvt_pk_f32_fp8_sdwa v[238:239], v183 src0_sel:WORD_1
	v_pk_fma_f32 v[228:229], v[76:77], v[236:237], v[228:229] op_sel_hi:[0,1,1]
	v_pk_fma_f32 v[230:231], v[76:77], v[238:239], v[230:231] op_sel_hi:[0,1,1]
	s_waitcnt vmcnt(6)
	v_cvt_pk_f32_fp8_e32 v[232:233], v184
	v_cvt_pk_f32_fp8_sdwa v[234:235], v184 src0_sel:WORD_1
	v_pk_fma_f32 v[216:217], v[76:77], v[232:233], v[216:217] op_sel:[1,0,0]
	v_pk_fma_f32 v[218:219], v[76:77], v[234:235], v[218:219] op_sel:[1,0,0]
	v_cvt_pk_f32_fp8_e32 v[236:237], v185
	v_cvt_pk_f32_fp8_sdwa v[238:239], v185 src0_sel:WORD_1
	v_pk_fma_f32 v[220:221], v[76:77], v[236:237], v[220:221] op_sel:[1,0,0]
	v_pk_fma_f32 v[222:223], v[76:77], v[238:239], v[222:223] op_sel:[1,0,0]
	v_cvt_pk_f32_fp8_e32 v[232:233], v186
	v_cvt_pk_f32_fp8_sdwa v[234:235], v186 src0_sel:WORD_1
	v_pk_fma_f32 v[224:225], v[76:77], v[232:233], v[224:225] op_sel:[1,0,0]
	v_pk_fma_f32 v[226:227], v[76:77], v[234:235], v[226:227] op_sel:[1,0,0]
	v_cvt_pk_f32_fp8_e32 v[236:237], v187
	v_cvt_pk_f32_fp8_sdwa v[238:239], v187 src0_sel:WORD_1
	v_pk_fma_f32 v[228:229], v[76:77], v[236:237], v[228:229] op_sel:[1,0,0]
	v_pk_fma_f32 v[230:231], v[76:77], v[238:239], v[230:231] op_sel:[1,0,0]
	s_waitcnt vmcnt(5)
; DI f2_t cvt8lo(unsigned w) { return __builtin_amdgcn_cvt_pk_f32_fp8(w, false); }
; DI f2_t cvt8hi(unsigned w) { return __builtin_amdgcn_cvt_pk_f32_fp8(w, true); }
; DI void phase11(const Params& p, char* smem, int rep) {
;     ...
; #pragma unroll
;         for (int k = 0; k < 16; ++k) {
;           const f2_t a2 = {aa[k], aa[k]};
; #pragma unroll
;           for (int d = 0; d < 4; ++d) { const unsigned ww = rows[k][d]; o[2 * d] += a2 * cvt8lo(ww); o[2 * d + 1] += a2 * cvt8hi(ww); }
	v_cvt_pk_f32_fp8_e32 v[232:233], v190
	v_cvt_pk_f32_fp8_sdwa v[234:235], v190 src0_sel:WORD_1
	v_pk_fma_f32 v[216:217], v[78:79], v[232:233], v[216:217] op_sel_hi:[0,1,1]
	v_pk_fma_f32 v[218:219], v[78:79], v[234:235], v[218:219] op_sel_hi:[0,1,1]
	v_cvt_pk_f32_fp8_e32 v[236:237], v191
	v_cvt_pk_f32_fp8_sdwa v[238:239], v191 src0_sel:WORD_1
	v_pk_fma_f32 v[220:221], v[78:79], v[236:237], v[220:221] op_sel_hi:[0,1,1]
	v_pk_fma_f32 v[222:223], v[78:79], v[238:239], v[222:223] op_sel_hi:[0,1,1]
	v_cvt_pk_f32_fp8_e32 v[232:233], v192
	v_cvt_pk_f32_fp8_sdwa v[234:235], v192 src0_sel:WORD_1
	v_pk_fma_f32 v[224:225], v[78:79], v[232:233], v[224:225] op_sel_hi:[0,1,1]
	v_pk_fma_f32 v[226:227], v[78:79], v[234:235], v[226:227] op_sel_hi:[0,1,1]
	v_cvt_pk_f32_fp8_e32 v[236:237], v193
	v_cvt_pk_f32_fp8_sdwa v[238:239], v193 src0_sel:WORD_1
	v_pk_fma_f32 v[228:229], v[78:79], v[236:237], v[228:229] op_sel_hi:[0,1,1]
	v_pk_fma_f32 v[230:231], v[78:79], v[238:239], v[230:231] op_sel_hi:[0,1,1]
	s_waitcnt vmcnt(4)
	v_cvt_pk_f32_fp8_e32 v[232:233], v194
	v_cvt_pk_f32_fp8_sdwa v[234:235], v194 src0_sel:WORD_1
	v_pk_fma_f32 v[216:217], v[78:79], v[232:233], v[216:217] op_sel:[1,0,0]
	v_pk_fma_f32 v[218:219], v[78:79], v[234:235], v[218:219] op_sel:[1,0,0]
	v_cvt_pk_f32_fp8_e32 v[236:237], v195
	v_cvt_pk_f32_fp8_sdwa v[238:239], v195 src0_sel:WORD_1
	v_pk_fma_f32 v[220:221], v[78:79], v[236:237], v[220:221] op_sel:[1,0,0]
	v_pk_fma_f32 v[222:223], v[78:79], v[238:239], v[222:223] op_sel:[1,0,0]
	v_cvt_pk_f32_fp8_e32 v[232:233], v196
	v_cvt_pk_f32_fp8_sdwa v[234:235], v196 src0_sel:WORD_1
	v_pk_fma_f32 v[224:225], v[78:79], v[232:233], v[224:225] op_sel:[1,0,0]
	v_pk_fma_f32 v[226:227], v[78:79], v[234:235], v[226:227] op_sel:[1,0,0]
	v_cvt_pk_f32_fp8_e32 v[236:237], v197
	v_cvt_pk_f32_fp8_sdwa v[238:239], v197 src0_sel:WORD_1
	v_pk_fma_f32 v[228:229], v[78:79], v[236:237], v[228:229] op_sel:[1,0,0]
	v_pk_fma_f32 v[230:231], v[78:79], v[238:239], v[230:231] op_sel:[1,0,0]
	s_waitcnt vmcnt(3)
	v_cvt_pk_f32_fp8_e32 v[232:233], v198
	v_cvt_pk_f32_fp8_sdwa v[234:235], v198 src0_sel:WORD_1
	v_pk_fma_f32 v[216:217], v[80:81], v[232:233], v[216:217] op_sel_hi:[0,1,1]
	v_pk_fma_f32 v[218:219], v[80:81], v[234:235], v[218:219] op_sel_hi:[0,1,1]
	v_cvt_pk_f32_fp8_e32 v[236:237], v199
	v_cvt_pk_f32_fp8_sdwa v[238:239], v199 src0_sel:WORD_1
	v_pk_fma_f32 v[220:221], v[80:81], v[236:237], v[220:221] op_sel_hi:[0,1,1]
	v_pk_fma_f32 v[222:223], v[80:81], v[238:239], v[222:223] op_sel_hi:[0,1,1]
	v_cvt_pk_f32_fp8_e32 v[232:233], v200
	v_cvt_pk_f32_fp8_sdwa v[234:235], v200 src0_sel:WORD_1
	v_pk_fma_f32 v[224:225], v[80:81], v[232:233], v[224:225] op_sel_hi:[0,1,1]
	v_pk_fma_f32 v[226:227], v[80:81], v[234:235], v[226:227] op_sel_hi:[0,1,1]
	v_cvt_pk_f32_fp8_e32 v[236:237], v201
	v_cvt_pk_f32_fp8_sdwa v[238:239], v201 src0_sel:WORD_1
	v_pk_fma_f32 v[228:229], v[80:81], v[236:237], v[228:229] op_sel_hi:[0,1,1]
	v_pk_fma_f32 v[230:231], v[80:81], v[238:239], v[230:231] op_sel_hi:[0,1,1]
	s_waitcnt vmcnt(2)
	v_cvt_pk_f32_fp8_e32 v[232:233], v202
	v_cvt_pk_f32_fp8_sdwa v[234:235], v202 src0_sel:WORD_1
	v_pk_fma_f32 v[216:217], v[80:81], v[232:233], v[216:217] op_sel:[1,0,0]
	v_pk_fma_f32 v[218:219], v[80:81], v[234:235], v[218:219] op_sel:[1,0,0]
	v_cvt_pk_f32_fp8_e32 v[236:237], v203
	v_cvt_pk_f32_fp8_sdwa v[238:239], v203 src0_sel:WORD_1
	v_pk_fma_f32 v[220:221], v[80:81], v[236:237], v[220:221] op_sel:[1,0,0]
	v_pk_fma_f32 v[222:223], v[80:81], v[238:239], v[222:223] op_sel:[1,0,0]
	v_cvt_pk_f32_fp8_e32 v[232:233], v204
	v_cvt_pk_f32_fp8_sdwa v[234:235], v204 src0_sel:WORD_1
	v_pk_fma_f32 v[224:225], v[80:81], v[232:233], v[224:225] op_sel:[1,0,0]
	v_pk_fma_f32 v[226:227], v[80:81], v[234:235], v[226:227] op_sel:[1,0,0]
	v_cvt_pk_f32_fp8_e32 v[236:237], v205
	v_cvt_pk_f32_fp8_sdwa v[238:239], v205 src0_sel:WORD_1
	v_pk_fma_f32 v[228:229], v[80:81], v[236:237], v[228:229] op_sel:[1,0,0]
	v_pk_fma_f32 v[230:231], v[80:81], v[238:239], v[230:231] op_sel:[1,0,0]
	s_waitcnt vmcnt(1)
	v_cvt_pk_f32_fp8_e32 v[232:233], v206
	v_cvt_pk_f32_fp8_sdwa v[234:235], v206 src0_sel:WORD_1
	v_pk_fma_f32 v[216:217], v[82:83], v[232:233], v[216:217] op_sel_hi:[0,1,1]
	v_pk_fma_f32 v[218:219], v[82:83], v[234:235], v[218:219] op_sel_hi:[0,1,1]
	v_cvt_pk_f32_fp8_e32 v[236:237], v207
	v_cvt_pk_f32_fp8_sdwa v[238:239], v207 src0_sel:WORD_1
	v_pk_fma_f32 v[220:221], v[82:83], v[236:237], v[220:221] op_sel_hi:[0,1,1]
	v_pk_fma_f32 v[222:223], v[82:83], v[238:239], v[222:223] op_sel_hi:[0,1,1]
	v_cvt_pk_f32_fp8_e32 v[232:233], v208
	v_cvt_pk_f32_fp8_sdwa v[234:235], v208 src0_sel:WORD_1
	v_pk_fma_f32 v[224:225], v[82:83], v[232:233], v[224:225] op_sel_hi:[0,1,1]
	v_pk_fma_f32 v[226:227], v[82:83], v[234:235], v[226:227] op_sel_hi:[0,1,1]
	v_cvt_pk_f32_fp8_e32 v[236:237], v209
	v_cvt_pk_f32_fp8_sdwa v[238:239], v209 src0_sel:WORD_1
	v_pk_fma_f32 v[228:229], v[82:83], v[236:237], v[228:229] op_sel_hi:[0,1,1]
	v_pk_fma_f32 v[230:231], v[82:83], v[238:239], v[230:231] op_sel_hi:[0,1,1]
	s_waitcnt vmcnt(0)
; DI unsigned pk2(float a, float b) { f2_t v = {a, b}; bf2_t r = __builtin_convertvector(v, bf2_t); return __builtin_bit_cast(unsigned, r); }
; DI f2_t cvt8lo(unsigned w) { return __builtin_amdgcn_cvt_pk_f32_fp8(w, false); }
; DI f2_t cvt8hi(unsigned w) { return __builtin_amdgcn_cvt_pk_f32_fp8(w, true); }
; DI void phase11(const Params& p, char* smem, int rep) {
;     ...
;         for (int k = 0; k < 16; ++k) {
;           const f2_t a2 = {aa[k], aa[k]};
; #pragma unroll
;           for (int d = 0; d < 4; ++d) { const unsigned ww = rows[k][d]; o[2 * d] += a2 * cvt8lo(ww); o[2 * d + 1] += a2 * cvt8hi(ww); }
;         }
;       }
;       float ov[16];
; #pragma unroll
;       for (int d = 0; d < 4; ++d) { ov[4 * d] = o[2 * d].x; ov[4 * d + 1] = o[2 * d].y; ov[4 * d + 2] = o[2 * d + 1].x; ov[4 * d + 3] = o[2 * d + 1].y; }
;       float q8[8], q4[4];
; #pragma unroll
;       for (int k = 0; k < 8; ++k) q8[k] = (b5 ? ov[8 + k] : ov[k]) + __shfl_xor(b5 ? ov[k] : ov[8 + k], 32);
; #pragma unroll
;       for (int k = 0; k < 4; ++k) q4[k] = (b4 ? q8[4 + k] : q8[k]) + __shfl_xor(b4 ? q8[k] : q8[4 + k], 16);
;       *(uint2*)(OUTP + (size_t)tok * D_ + s * 256 + l15 * 16 + 8 * b5 + 4 * b4) = make_uint2(pk2(q4[0], q4[1]), pk2(q4[2], q4[3]));
	v_cvt_pk_f32_fp8_e32 v[232:233], v210
	v_cvt_pk_f32_fp8_sdwa v[234:235], v210 src0_sel:WORD_1
	v_pk_fma_f32 v[216:217], v[82:83], v[232:233], v[216:217] op_sel:[1,0,0]
	v_pk_fma_f32 v[218:219], v[82:83], v[234:235], v[218:219] op_sel:[1,0,0]
	v_cvt_pk_f32_fp8_e32 v[236:237], v211
	v_cvt_pk_f32_fp8_sdwa v[238:239], v211 src0_sel:WORD_1
	v_pk_fma_f32 v[220:221], v[82:83], v[236:237], v[220:221] op_sel:[1,0,0]
	v_pk_fma_f32 v[222:223], v[82:83], v[238:239], v[222:223] op_sel:[1,0,0]
	v_cvt_pk_f32_fp8_e32 v[232:233], v212
	v_cvt_pk_f32_fp8_sdwa v[234:235], v212 src0_sel:WORD_1
	v_pk_fma_f32 v[224:225], v[82:83], v[232:233], v[224:225] op_sel:[1,0,0]
	v_pk_fma_f32 v[226:227], v[82:83], v[234:235], v[226:227] op_sel:[1,0,0]
	v_cvt_pk_f32_fp8_e32 v[236:237], v213
	v_cvt_pk_f32_fp8_sdwa v[238:239], v213 src0_sel:WORD_1
	v_pk_fma_f32 v[228:229], v[82:83], v[236:237], v[228:229] op_sel:[1,0,0]
	v_pk_fma_f32 v[230:231], v[82:83], v[238:239], v[230:231] op_sel:[1,0,0]
	ds_read_b128 v[52:55], v6 offset:528
	ds_read_b128 v[56:59], v6 offset:544
	ds_read_b128 v[60:63], v6 offset:560
	ds_read_b128 v[64:67], v6 offset:576
	ds_read_b128 v[68:71], v6 offset:592
	ds_read_b128 v[72:75], v6 offset:608
	ds_read_b128 v[76:79], v6 offset:624
	ds_read_b128 v[80:83], v6 offset:640
	s_add_u32 s56, s14, s46
	s_addc_u32 s57, s15, 0
	s_nop 0
	v_permlane32_swap_b32_e32 v216, v224
	v_permlane32_swap_b32_e32 v217, v225
	v_permlane32_swap_b32_e32 v218, v226
	v_permlane32_swap_b32_e32 v219, v227
	v_permlane32_swap_b32_e32 v220, v228
	v_permlane32_swap_b32_e32 v221, v229
	v_permlane32_swap_b32_e32 v222, v230
	v_permlane32_swap_b32_e32 v223, v231
	v_pk_add_f32 v[216:217], v[216:217], v[224:225]
	v_pk_add_f32 v[218:219], v[218:219], v[226:227]
	v_pk_add_f32 v[220:221], v[220:221], v[228:229]
	v_pk_add_f32 v[222:223], v[222:223], v[230:231]
	s_nop 1
	v_permlane16_swap_b32_e32 v216, v220
	v_permlane16_swap_b32_e32 v217, v221
	v_permlane16_swap_b32_e32 v218, v222
	v_permlane16_swap_b32_e32 v219, v223
	v_pk_add_f32 v[216:217], v[216:217], v[220:221]
	v_pk_add_f32 v[218:219], v[218:219], v[222:223]
	v_cvt_pk_bf16_f32 v232, v216, v217
	v_cvt_pk_bf16_f32 v233, v218, v219
	global_store_dwordx2 v4, v[232:233], s[56:57]
	s_add_i32 s54, s34, 1
	s_lshl_b32 s46, s54, 12
	s_add_i32 s46, s46, s24
	s_add_i32 s55, s34, 2
	s_lshl_b32 s47, s55, 9
	s_add_u32 s42, s6, s47
	s_addc_u32 s43, s7, 0
	s_add_u32 s44, s8, s47
	s_addc_u32 s45, s9, 0
	global_load_dword v10, v3, s[42:43]
	global_load_dword v11, v3, s[42:43] offset:256
	global_load_dword v12, v3, s[44:45]
	global_load_dword v13, v3, s[44:45] offset:256
	s_waitcnt lgkmcnt(0)
	v_lshl_add_u32 v20, v20, 11, v2
	v_lshl_add_u32 v21, v21, 11, v2
	v_lshl_add_u32 v22, v22, 11, v2
	v_lshl_add_u32 v23, v23, 11, v2
	v_lshl_add_u32 v24, v24, 11, v2
	v_lshl_add_u32 v25, v25, 11, v2
	v_lshl_add_u32 v26, v26, 11, v2
	v_lshl_add_u32 v27, v27, 11, v2
	v_lshl_add_u32 v28, v28, 11, v2
	v_lshl_add_u32 v29, v29, 11, v2
	v_lshl_add_u32 v30, v30, 11, v2
	v_lshl_add_u32 v31, v31, 11, v2
	v_lshl_add_u32 v32, v32, 11, v2
	v_lshl_add_u32 v33, v33, 11, v2
	v_lshl_add_u32 v34, v34, 11, v2
	v_lshl_add_u32 v35, v35, 11, v2
	v_lshl_add_u32 v36, v36, 11, v2
	v_lshl_add_u32 v37, v37, 11, v2
	v_lshl_add_u32 v38, v38, 11, v2
	v_lshl_add_u32 v39, v39, 11, v2
	v_lshl_add_u32 v40, v40, 11, v2
	v_lshl_add_u32 v41, v41, 11, v2
	v_lshl_add_u32 v42, v42, 11, v2
	v_lshl_add_u32 v43, v43, 11, v2
	v_lshl_add_u32 v44, v44, 11, v2
	v_lshl_add_u32 v45, v45, 11, v2
	v_lshl_add_u32 v46, v46, 11, v2
	v_lshl_add_u32 v47, v47, 11, v2
	v_lshl_add_u32 v48, v48, 11, v2
	v_lshl_add_u32 v49, v49, 11, v2
	v_lshl_add_u32 v50, v50, 11, v2
	v_lshl_add_u32 v51, v51, 11, v2
	global_load_dwordx4 v[84:87], v20, s[20:21]
	global_load_dwordx4 v[88:91], v21, s[20:21]
	global_load_dwordx4 v[92:95], v22, s[20:21]
	global_load_dwordx4 v[96:99], v23, s[20:21]
	global_load_dwordx4 v[100:103], v24, s[20:21]
	global_load_dwordx4 v[104:107], v25, s[20:21]
	global_load_dwordx4 v[108:111], v26, s[20:21]
	global_load_dwordx4 v[112:115], v27, s[20:21]
	global_load_dwordx4 v[116:119], v28, s[20:21]
	global_load_dwordx4 v[120:123], v29, s[20:21]
	global_load_dwordx4 v[124:127], v30, s[20:21]
	global_load_dwordx4 v[128:131], v31, s[20:21]
	global_load_dwordx4 v[132:135], v32, s[20:21]
	global_load_dwordx4 v[136:139], v33, s[20:21]
	global_load_dwordx4 v[140:143], v34, s[20:21]
	global_load_dwordx4 v[144:147], v35, s[20:21]
	global_load_dwordx4 v[148:151], v36, s[20:21]
	global_load_dwordx4 v[152:155], v37, s[20:21]
	global_load_dwordx4 v[156:159], v38, s[20:21]
	global_load_dwordx4 v[160:163], v39, s[20:21]
	global_load_dwordx4 v[164:167], v40, s[20:21]
	global_load_dwordx4 v[168:171], v41, s[20:21]
	global_load_dwordx4 v[172:175], v42, s[20:21]
	global_load_dwordx4 v[176:179], v43, s[20:21]
	global_load_dwordx4 v[180:183], v44, s[20:21]
	global_load_dwordx4 v[184:187], v45, s[20:21]
	global_load_dwordx4 v[190:193], v46, s[20:21]
	global_load_dwordx4 v[194:197], v47, s[20:21]
	global_load_dwordx4 v[198:201], v48, s[20:21]
	global_load_dwordx4 v[202:205], v49, s[20:21]
	global_load_dwordx4 v[206:209], v50, s[20:21]
	global_load_dwordx4 v[210:213], v51, s[20:21]
	s_waitcnt vmcnt(31)
; DI f2_t cvt8lo(unsigned w) { return __builtin_amdgcn_cvt_pk_f32_fp8(w, false); }
; DI f2_t cvt8hi(unsigned w) { return __builtin_amdgcn_cvt_pk_f32_fp8(w, true); }
; DI void phase11(const Params& p, char* smem, int rep) {
;     ...
; #pragma unroll
;         for (int k = 0; k < 16; ++k) {
;           const f2_t a2 = {aa[k], aa[k]};
; #pragma unroll
;           for (int d = 0; d < 4; ++d) { const unsigned ww = rows[k][d]; o[2 * d] += a2 * cvt8lo(ww); o[2 * d + 1] += a2 * cvt8hi(ww); }
	v_cvt_pk_f32_fp8_e32 v[232:233], v84
	v_cvt_pk_f32_fp8_sdwa v[234:235], v84 src0_sel:WORD_1
	v_pk_fma_f32 v[216:217], v[52:53], v[232:233], 0 op_sel_hi:[0,1,0]
	v_pk_fma_f32 v[218:219], v[52:53], v[234:235], 0 op_sel_hi:[0,1,0]
	v_cvt_pk_f32_fp8_e32 v[236:237], v85
	v_cvt_pk_f32_fp8_sdwa v[238:239], v85 src0_sel:WORD_1
	v_pk_fma_f32 v[220:221], v[52:53], v[236:237], 0 op_sel_hi:[0,1,0]
	v_pk_fma_f32 v[222:223], v[52:53], v[238:239], 0 op_sel_hi:[0,1,0]
	v_cvt_pk_f32_fp8_e32 v[232:233], v86
	v_cvt_pk_f32_fp8_sdwa v[234:235], v86 src0_sel:WORD_1
	v_pk_fma_f32 v[224:225], v[52:53], v[232:233], 0 op_sel_hi:[0,1,0]
	v_pk_fma_f32 v[226:227], v[52:53], v[234:235], 0 op_sel_hi:[0,1,0]
	v_cvt_pk_f32_fp8_e32 v[236:237], v87
	v_cvt_pk_f32_fp8_sdwa v[238:239], v87 src0_sel:WORD_1
	v_pk_fma_f32 v[228:229], v[52:53], v[236:237], 0 op_sel_hi:[0,1,0]
	v_pk_fma_f32 v[230:231], v[52:53], v[238:239], 0 op_sel_hi:[0,1,0]
	s_waitcnt vmcnt(30)
	v_cvt_pk_f32_fp8_e32 v[232:233], v88
	v_cvt_pk_f32_fp8_sdwa v[234:235], v88 src0_sel:WORD_1
	v_pk_fma_f32 v[216:217], v[52:53], v[232:233], v[216:217] op_sel:[1,0,0]
	v_pk_fma_f32 v[218:219], v[52:53], v[234:235], v[218:219] op_sel:[1,0,0]
	v_cvt_pk_f32_fp8_e32 v[236:237], v89
	v_cvt_pk_f32_fp8_sdwa v[238:239], v89 src0_sel:WORD_1
	v_pk_fma_f32 v[220:221], v[52:53], v[236:237], v[220:221] op_sel:[1,0,0]
	v_pk_fma_f32 v[222:223], v[52:53], v[238:239], v[222:223] op_sel:[1,0,0]
	v_cvt_pk_f32_fp8_e32 v[232:233], v90
	v_cvt_pk_f32_fp8_sdwa v[234:235], v90 src0_sel:WORD_1
	v_pk_fma_f32 v[224:225], v[52:53], v[232:233], v[224:225] op_sel:[1,0,0]
	v_pk_fma_f32 v[226:227], v[52:53], v[234:235], v[226:227] op_sel:[1,0,0]
	v_cvt_pk_f32_fp8_e32 v[236:237], v91
	v_cvt_pk_f32_fp8_sdwa v[238:239], v91 src0_sel:WORD_1
	v_pk_fma_f32 v[228:229], v[52:53], v[236:237], v[228:229] op_sel:[1,0,0]
	v_pk_fma_f32 v[230:231], v[52:53], v[238:239], v[230:231] op_sel:[1,0,0]
	s_waitcnt vmcnt(29)
	v_cvt_pk_f32_fp8_e32 v[232:233], v92
	v_cvt_pk_f32_fp8_sdwa v[234:235], v92 src0_sel:WORD_1
	v_pk_fma_f32 v[216:217], v[54:55], v[232:233], v[216:217] op_sel_hi:[0,1,1]
	v_pk_fma_f32 v[218:219], v[54:55], v[234:235], v[218:219] op_sel_hi:[0,1,1]
	v_cvt_pk_f32_fp8_e32 v[236:237], v93
	v_cvt_pk_f32_fp8_sdwa v[238:239], v93 src0_sel:WORD_1
	v_pk_fma_f32 v[220:221], v[54:55], v[236:237], v[220:221] op_sel_hi:[0,1,1]
	v_pk_fma_f32 v[222:223], v[54:55], v[238:239], v[222:223] op_sel_hi:[0,1,1]
	v_cvt_pk_f32_fp8_e32 v[232:233], v94
	v_cvt_pk_f32_fp8_sdwa v[234:235], v94 src0_sel:WORD_1
	v_pk_fma_f32 v[224:225], v[54:55], v[232:233], v[224:225] op_sel_hi:[0,1,1]
	v_pk_fma_f32 v[226:227], v[54:55], v[234:235], v[226:227] op_sel_hi:[0,1,1]
	v_cvt_pk_f32_fp8_e32 v[236:237], v95
	v_cvt_pk_f32_fp8_sdwa v[238:239], v95 src0_sel:WORD_1
	v_pk_fma_f32 v[228:229], v[54:55], v[236:237], v[228:229] op_sel_hi:[0,1,1]
	v_pk_fma_f32 v[230:231], v[54:55], v[238:239], v[230:231] op_sel_hi:[0,1,1]
	s_waitcnt vmcnt(28)
	v_cvt_pk_f32_fp8_e32 v[232:233], v96
	v_cvt_pk_f32_fp8_sdwa v[234:235], v96 src0_sel:WORD_1
	v_pk_fma_f32 v[216:217], v[54:55], v[232:233], v[216:217] op_sel:[1,0,0]
	v_pk_fma_f32 v[218:219], v[54:55], v[234:235], v[218:219] op_sel:[1,0,0]
	v_cvt_pk_f32_fp8_e32 v[236:237], v97
	v_cvt_pk_f32_fp8_sdwa v[238:239], v97 src0_sel:WORD_1
	v_pk_fma_f32 v[220:221], v[54:55], v[236:237], v[220:221] op_sel:[1,0,0]
	v_pk_fma_f32 v[222:223], v[54:55], v[238:239], v[222:223] op_sel:[1,0,0]
	v_cvt_pk_f32_fp8_e32 v[232:233], v98
	v_cvt_pk_f32_fp8_sdwa v[234:235], v98 src0_sel:WORD_1
	v_pk_fma_f32 v[224:225], v[54:55], v[232:233], v[224:225] op_sel:[1,0,0]
	v_pk_fma_f32 v[226:227], v[54:55], v[234:235], v[226:227] op_sel:[1,0,0]
	v_cvt_pk_f32_fp8_e32 v[236:237], v99
	v_cvt_pk_f32_fp8_sdwa v[238:239], v99 src0_sel:WORD_1
	v_pk_fma_f32 v[228:229], v[54:55], v[236:237], v[228:229] op_sel:[1,0,0]
	v_pk_fma_f32 v[230:231], v[54:55], v[238:239], v[230:231] op_sel:[1,0,0]
	s_waitcnt vmcnt(27)
	v_cvt_pk_f32_fp8_e32 v[232:233], v100
	v_cvt_pk_f32_fp8_sdwa v[234:235], v100 src0_sel:WORD_1
	v_pk_fma_f32 v[216:217], v[56:57], v[232:233], v[216:217] op_sel_hi:[0,1,1]
	v_pk_fma_f32 v[218:219], v[56:57], v[234:235], v[218:219] op_sel_hi:[0,1,1]
	v_cvt_pk_f32_fp8_e32 v[236:237], v101
	v_cvt_pk_f32_fp8_sdwa v[238:239], v101 src0_sel:WORD_1
	v_pk_fma_f32 v[220:221], v[56:57], v[236:237], v[220:221] op_sel_hi:[0,1,1]
	v_pk_fma_f32 v[222:223], v[56:57], v[238:239], v[222:223] op_sel_hi:[0,1,1]
	v_cvt_pk_f32_fp8_e32 v[232:233], v102
	v_cvt_pk_f32_fp8_sdwa v[234:235], v102 src0_sel:WORD_1
	v_pk_fma_f32 v[224:225], v[56:57], v[232:233], v[224:225] op_sel_hi:[0,1,1]
	v_pk_fma_f32 v[226:227], v[56:57], v[234:235], v[226:227] op_sel_hi:[0,1,1]
	v_cvt_pk_f32_fp8_e32 v[236:237], v103
	v_cvt_pk_f32_fp8_sdwa v[238:239], v103 src0_sel:WORD_1
	v_pk_fma_f32 v[228:229], v[56:57], v[236:237], v[228:229] op_sel_hi:[0,1,1]
	v_pk_fma_f32 v[230:231], v[56:57], v[238:239], v[230:231] op_sel_hi:[0,1,1]
	s_waitcnt vmcnt(26)
	v_cvt_pk_f32_fp8_e32 v[232:233], v104
	v_cvt_pk_f32_fp8_sdwa v[234:235], v104 src0_sel:WORD_1
	v_pk_fma_f32 v[216:217], v[56:57], v[232:233], v[216:217] op_sel:[1,0,0]
	v_pk_fma_f32 v[218:219], v[56:57], v[234:235], v[218:219] op_sel:[1,0,0]
	v_cvt_pk_f32_fp8_e32 v[236:237], v105
	v_cvt_pk_f32_fp8_sdwa v[238:239], v105 src0_sel:WORD_1
	v_pk_fma_f32 v[220:221], v[56:57], v[236:237], v[220:221] op_sel:[1,0,0]
	v_pk_fma_f32 v[222:223], v[56:57], v[238:239], v[222:223] op_sel:[1,0,0]
	v_cvt_pk_f32_fp8_e32 v[232:233], v106
	v_cvt_pk_f32_fp8_sdwa v[234:235], v106 src0_sel:WORD_1
	v_pk_fma_f32 v[224:225], v[56:57], v[232:233], v[224:225] op_sel:[1,0,0]
	v_pk_fma_f32 v[226:227], v[56:57], v[234:235], v[226:227] op_sel:[1,0,0]
	v_cvt_pk_f32_fp8_e32 v[236:237], v107
	v_cvt_pk_f32_fp8_sdwa v[238:239], v107 src0_sel:WORD_1
	v_pk_fma_f32 v[228:229], v[56:57], v[236:237], v[228:229] op_sel:[1,0,0]
	v_pk_fma_f32 v[230:231], v[56:57], v[238:239], v[230:231] op_sel:[1,0,0]
	s_waitcnt vmcnt(25)
; DI f2_t cvt8lo(unsigned w) { return __builtin_amdgcn_cvt_pk_f32_fp8(w, false); }
; DI f2_t cvt8hi(unsigned w) { return __builtin_amdgcn_cvt_pk_f32_fp8(w, true); }
; DI void phase11(const Params& p, char* smem, int rep) {
;     ...
; #pragma unroll
;         for (int k = 0; k < 16; ++k) {
;           const f2_t a2 = {aa[k], aa[k]};
; #pragma unroll
;           for (int d = 0; d < 4; ++d) { const unsigned ww = rows[k][d]; o[2 * d] += a2 * cvt8lo(ww); o[2 * d + 1] += a2 * cvt8hi(ww); }
	v_cvt_pk_f32_fp8_e32 v[232:233], v108
	v_cvt_pk_f32_fp8_sdwa v[234:235], v108 src0_sel:WORD_1
	v_pk_fma_f32 v[216:217], v[58:59], v[232:233], v[216:217] op_sel_hi:[0,1,1]
	v_pk_fma_f32 v[218:219], v[58:59], v[234:235], v[218:219] op_sel_hi:[0,1,1]
	v_cvt_pk_f32_fp8_e32 v[236:237], v109
	v_cvt_pk_f32_fp8_sdwa v[238:239], v109 src0_sel:WORD_1
	v_pk_fma_f32 v[220:221], v[58:59], v[236:237], v[220:221] op_sel_hi:[0,1,1]
	v_pk_fma_f32 v[222:223], v[58:59], v[238:239], v[222:223] op_sel_hi:[0,1,1]
	v_cvt_pk_f32_fp8_e32 v[232:233], v110
	v_cvt_pk_f32_fp8_sdwa v[234:235], v110 src0_sel:WORD_1
	v_pk_fma_f32 v[224:225], v[58:59], v[232:233], v[224:225] op_sel_hi:[0,1,1]
	v_pk_fma_f32 v[226:227], v[58:59], v[234:235], v[226:227] op_sel_hi:[0,1,1]
	v_cvt_pk_f32_fp8_e32 v[236:237], v111
	v_cvt_pk_f32_fp8_sdwa v[238:239], v111 src0_sel:WORD_1
	v_pk_fma_f32 v[228:229], v[58:59], v[236:237], v[228:229] op_sel_hi:[0,1,1]
	v_pk_fma_f32 v[230:231], v[58:59], v[238:239], v[230:231] op_sel_hi:[0,1,1]
	s_waitcnt vmcnt(24)
	v_cvt_pk_f32_fp8_e32 v[232:233], v112
	v_cvt_pk_f32_fp8_sdwa v[234:235], v112 src0_sel:WORD_1
	v_pk_fma_f32 v[216:217], v[58:59], v[232:233], v[216:217] op_sel:[1,0,0]
	v_pk_fma_f32 v[218:219], v[58:59], v[234:235], v[218:219] op_sel:[1,0,0]
	v_cvt_pk_f32_fp8_e32 v[236:237], v113
	v_cvt_pk_f32_fp8_sdwa v[238:239], v113 src0_sel:WORD_1
	v_pk_fma_f32 v[220:221], v[58:59], v[236:237], v[220:221] op_sel:[1,0,0]
	v_pk_fma_f32 v[222:223], v[58:59], v[238:239], v[222:223] op_sel:[1,0,0]
	v_cvt_pk_f32_fp8_e32 v[232:233], v114
	v_cvt_pk_f32_fp8_sdwa v[234:235], v114 src0_sel:WORD_1
	v_pk_fma_f32 v[224:225], v[58:59], v[232:233], v[224:225] op_sel:[1,0,0]
	v_pk_fma_f32 v[226:227], v[58:59], v[234:235], v[226:227] op_sel:[1,0,0]
	v_cvt_pk_f32_fp8_e32 v[236:237], v115
	v_cvt_pk_f32_fp8_sdwa v[238:239], v115 src0_sel:WORD_1
	v_pk_fma_f32 v[228:229], v[58:59], v[236:237], v[228:229] op_sel:[1,0,0]
	v_pk_fma_f32 v[230:231], v[58:59], v[238:239], v[230:231] op_sel:[1,0,0]
	s_waitcnt vmcnt(23)
	v_cvt_pk_f32_fp8_e32 v[232:233], v116
	v_cvt_pk_f32_fp8_sdwa v[234:235], v116 src0_sel:WORD_1
	v_pk_fma_f32 v[216:217], v[60:61], v[232:233], v[216:217] op_sel_hi:[0,1,1]
	v_pk_fma_f32 v[218:219], v[60:61], v[234:235], v[218:219] op_sel_hi:[0,1,1]
	v_cvt_pk_f32_fp8_e32 v[236:237], v117
	v_cvt_pk_f32_fp8_sdwa v[238:239], v117 src0_sel:WORD_1
	v_pk_fma_f32 v[220:221], v[60:61], v[236:237], v[220:221] op_sel_hi:[0,1,1]
	v_pk_fma_f32 v[222:223], v[60:61], v[238:239], v[222:223] op_sel_hi:[0,1,1]
	v_cvt_pk_f32_fp8_e32 v[232:233], v118
	v_cvt_pk_f32_fp8_sdwa v[234:235], v118 src0_sel:WORD_1
	v_pk_fma_f32 v[224:225], v[60:61], v[232:233], v[224:225] op_sel_hi:[0,1,1]
	v_pk_fma_f32 v[226:227], v[60:61], v[234:235], v[226:227] op_sel_hi:[0,1,1]
	v_cvt_pk_f32_fp8_e32 v[236:237], v119
	v_cvt_pk_f32_fp8_sdwa v[238:239], v119 src0_sel:WORD_1
	v_pk_fma_f32 v[228:229], v[60:61], v[236:237], v[228:229] op_sel_hi:[0,1,1]
	v_pk_fma_f32 v[230:231], v[60:61], v[238:239], v[230:231] op_sel_hi:[0,1,1]
	s_waitcnt vmcnt(22)
	v_cvt_pk_f32_fp8_e32 v[232:233], v120
	v_cvt_pk_f32_fp8_sdwa v[234:235], v120 src0_sel:WORD_1
	v_pk_fma_f32 v[216:217], v[60:61], v[232:233], v[216:217] op_sel:[1,0,0]
	v_pk_fma_f32 v[218:219], v[60:61], v[234:235], v[218:219] op_sel:[1,0,0]
	v_cvt_pk_f32_fp8_e32 v[236:237], v121
	v_cvt_pk_f32_fp8_sdwa v[238:239], v121 src0_sel:WORD_1
	v_pk_fma_f32 v[220:221], v[60:61], v[236:237], v[220:221] op_sel:[1,0,0]
	v_pk_fma_f32 v[222:223], v[60:61], v[238:239], v[222:223] op_sel:[1,0,0]
	v_cvt_pk_f32_fp8_e32 v[232:233], v122
	v_cvt_pk_f32_fp8_sdwa v[234:235], v122 src0_sel:WORD_1
	v_pk_fma_f32 v[224:225], v[60:61], v[232:233], v[224:225] op_sel:[1,0,0]
	v_pk_fma_f32 v[226:227], v[60:61], v[234:235], v[226:227] op_sel:[1,0,0]
	v_cvt_pk_f32_fp8_e32 v[236:237], v123
	v_cvt_pk_f32_fp8_sdwa v[238:239], v123 src0_sel:WORD_1
	v_pk_fma_f32 v[228:229], v[60:61], v[236:237], v[228:229] op_sel:[1,0,0]
	v_pk_fma_f32 v[230:231], v[60:61], v[238:239], v[230:231] op_sel:[1,0,0]
	s_waitcnt vmcnt(21)
	v_cvt_pk_f32_fp8_e32 v[232:233], v124
	v_cvt_pk_f32_fp8_sdwa v[234:235], v124 src0_sel:WORD_1
	v_pk_fma_f32 v[216:217], v[62:63], v[232:233], v[216:217] op_sel_hi:[0,1,1]
	v_pk_fma_f32 v[218:219], v[62:63], v[234:235], v[218:219] op_sel_hi:[0,1,1]
	v_cvt_pk_f32_fp8_e32 v[236:237], v125
	v_cvt_pk_f32_fp8_sdwa v[238:239], v125 src0_sel:WORD_1
	v_pk_fma_f32 v[220:221], v[62:63], v[236:237], v[220:221] op_sel_hi:[0,1,1]
	v_pk_fma_f32 v[222:223], v[62:63], v[238:239], v[222:223] op_sel_hi:[0,1,1]
	v_cvt_pk_f32_fp8_e32 v[232:233], v126
	v_cvt_pk_f32_fp8_sdwa v[234:235], v126 src0_sel:WORD_1
	v_pk_fma_f32 v[224:225], v[62:63], v[232:233], v[224:225] op_sel_hi:[0,1,1]
	v_pk_fma_f32 v[226:227], v[62:63], v[234:235], v[226:227] op_sel_hi:[0,1,1]
	v_cvt_pk_f32_fp8_e32 v[236:237], v127
	v_cvt_pk_f32_fp8_sdwa v[238:239], v127 src0_sel:WORD_1
	v_pk_fma_f32 v[228:229], v[62:63], v[236:237], v[228:229] op_sel_hi:[0,1,1]
	v_pk_fma_f32 v[230:231], v[62:63], v[238:239], v[230:231] op_sel_hi:[0,1,1]
	s_waitcnt vmcnt(20)
	v_cvt_pk_f32_fp8_e32 v[232:233], v128
	v_cvt_pk_f32_fp8_sdwa v[234:235], v128 src0_sel:WORD_1
	v_pk_fma_f32 v[216:217], v[62:63], v[232:233], v[216:217] op_sel:[1,0,0]
	v_pk_fma_f32 v[218:219], v[62:63], v[234:235], v[218:219] op_sel:[1,0,0]
	v_cvt_pk_f32_fp8_e32 v[236:237], v129
	v_cvt_pk_f32_fp8_sdwa v[238:239], v129 src0_sel:WORD_1
	v_pk_fma_f32 v[220:221], v[62:63], v[236:237], v[220:221] op_sel:[1,0,0]
	v_pk_fma_f32 v[222:223], v[62:63], v[238:239], v[222:223] op_sel:[1,0,0]
	v_cvt_pk_f32_fp8_e32 v[232:233], v130
	v_cvt_pk_f32_fp8_sdwa v[234:235], v130 src0_sel:WORD_1
	v_pk_fma_f32 v[224:225], v[62:63], v[232:233], v[224:225] op_sel:[1,0,0]
	v_pk_fma_f32 v[226:227], v[62:63], v[234:235], v[226:227] op_sel:[1,0,0]
	v_cvt_pk_f32_fp8_e32 v[236:237], v131
	v_cvt_pk_f32_fp8_sdwa v[238:239], v131 src0_sel:WORD_1
	v_pk_fma_f32 v[228:229], v[62:63], v[236:237], v[228:229] op_sel:[1,0,0]
	v_pk_fma_f32 v[230:231], v[62:63], v[238:239], v[230:231] op_sel:[1,0,0]
	s_waitcnt vmcnt(19)
; DI f2_t cvt8lo(unsigned w) { return __builtin_amdgcn_cvt_pk_f32_fp8(w, false); }
; DI f2_t cvt8hi(unsigned w) { return __builtin_amdgcn_cvt_pk_f32_fp8(w, true); }
; DI void wave_lds_sync() { asm volatile("s_waitcnt lgkmcnt(0)" ::: "memory"); __builtin_amdgcn_wave_barrier(); }
; DI void phase11(const Params& p, char* smem, int rep) {
;     ...
;       const int tok = __builtin_amdgcn_readfirstlane(c * 16 + w * 4 + t);
;       const int i0 = IDS[(size_t)tok * 128 + lane], i1 = IDS[(size_t)tok * 128 + 64 + lane];
;       const float a0 = ACT[(size_t)tok * 128 + lane], a1 = ACT[(size_t)tok * 128 + 64 + lane];
;       wave_lds_sync();
;       lw[(lane & 3) * 32 + (lane >> 2)] = i0; lw[(lane & 3) * 32 + 16 + (lane >> 2)] = i1;
;       lf[(lane & 3) * 32 + (lane >> 2)] = a0; lf[(lane & 3) * 32 + 16 + (lane >> 2)] = a1;
;       wave_lds_sync();
;     ...
; #pragma unroll
;         for (int k = 0; k < 16; ++k) {
;           const f2_t a2 = {aa[k], aa[k]};
; #pragma unroll
;           for (int d = 0; d < 4; ++d) { const unsigned ww = rows[k][d]; o[2 * d] += a2 * cvt8lo(ww); o[2 * d + 1] += a2 * cvt8hi(ww); }
	v_cvt_pk_f32_fp8_e32 v[232:233], v132
	v_cvt_pk_f32_fp8_sdwa v[234:235], v132 src0_sel:WORD_1
	v_pk_fma_f32 v[216:217], v[64:65], v[232:233], v[216:217] op_sel_hi:[0,1,1]
	v_pk_fma_f32 v[218:219], v[64:65], v[234:235], v[218:219] op_sel_hi:[0,1,1]
	v_cvt_pk_f32_fp8_e32 v[236:237], v133
	v_cvt_pk_f32_fp8_sdwa v[238:239], v133 src0_sel:WORD_1
	v_pk_fma_f32 v[220:221], v[64:65], v[236:237], v[220:221] op_sel_hi:[0,1,1]
	v_pk_fma_f32 v[222:223], v[64:65], v[238:239], v[222:223] op_sel_hi:[0,1,1]
	v_cvt_pk_f32_fp8_e32 v[232:233], v134
	v_cvt_pk_f32_fp8_sdwa v[234:235], v134 src0_sel:WORD_1
	v_pk_fma_f32 v[224:225], v[64:65], v[232:233], v[224:225] op_sel_hi:[0,1,1]
	v_pk_fma_f32 v[226:227], v[64:65], v[234:235], v[226:227] op_sel_hi:[0,1,1]
	v_cvt_pk_f32_fp8_e32 v[236:237], v135
	v_cvt_pk_f32_fp8_sdwa v[238:239], v135 src0_sel:WORD_1
	v_pk_fma_f32 v[228:229], v[64:65], v[236:237], v[228:229] op_sel_hi:[0,1,1]
	v_pk_fma_f32 v[230:231], v[64:65], v[238:239], v[230:231] op_sel_hi:[0,1,1]
	s_waitcnt vmcnt(18)
	v_cvt_pk_f32_fp8_e32 v[232:233], v136
	v_cvt_pk_f32_fp8_sdwa v[234:235], v136 src0_sel:WORD_1
	v_pk_fma_f32 v[216:217], v[64:65], v[232:233], v[216:217] op_sel:[1,0,0]
	v_pk_fma_f32 v[218:219], v[64:65], v[234:235], v[218:219] op_sel:[1,0,0]
	v_cvt_pk_f32_fp8_e32 v[236:237], v137
	v_cvt_pk_f32_fp8_sdwa v[238:239], v137 src0_sel:WORD_1
	v_pk_fma_f32 v[220:221], v[64:65], v[236:237], v[220:221] op_sel:[1,0,0]
	v_pk_fma_f32 v[222:223], v[64:65], v[238:239], v[222:223] op_sel:[1,0,0]
	v_cvt_pk_f32_fp8_e32 v[232:233], v138
	v_cvt_pk_f32_fp8_sdwa v[234:235], v138 src0_sel:WORD_1
	v_pk_fma_f32 v[224:225], v[64:65], v[232:233], v[224:225] op_sel:[1,0,0]
	v_pk_fma_f32 v[226:227], v[64:65], v[234:235], v[226:227] op_sel:[1,0,0]
	v_cvt_pk_f32_fp8_e32 v[236:237], v139
	v_cvt_pk_f32_fp8_sdwa v[238:239], v139 src0_sel:WORD_1
	v_pk_fma_f32 v[228:229], v[64:65], v[236:237], v[228:229] op_sel:[1,0,0]
	v_pk_fma_f32 v[230:231], v[64:65], v[238:239], v[230:231] op_sel:[1,0,0]
	s_waitcnt vmcnt(17)
	v_cvt_pk_f32_fp8_e32 v[232:233], v140
	v_cvt_pk_f32_fp8_sdwa v[234:235], v140 src0_sel:WORD_1
	v_pk_fma_f32 v[216:217], v[66:67], v[232:233], v[216:217] op_sel_hi:[0,1,1]
	v_pk_fma_f32 v[218:219], v[66:67], v[234:235], v[218:219] op_sel_hi:[0,1,1]
	v_cvt_pk_f32_fp8_e32 v[236:237], v141
	v_cvt_pk_f32_fp8_sdwa v[238:239], v141 src0_sel:WORD_1
	v_pk_fma_f32 v[220:221], v[66:67], v[236:237], v[220:221] op_sel_hi:[0,1,1]
	v_pk_fma_f32 v[222:223], v[66:67], v[238:239], v[222:223] op_sel_hi:[0,1,1]
	v_cvt_pk_f32_fp8_e32 v[232:233], v142
	v_cvt_pk_f32_fp8_sdwa v[234:235], v142 src0_sel:WORD_1
	v_pk_fma_f32 v[224:225], v[66:67], v[232:233], v[224:225] op_sel_hi:[0,1,1]
	v_pk_fma_f32 v[226:227], v[66:67], v[234:235], v[226:227] op_sel_hi:[0,1,1]
	v_cvt_pk_f32_fp8_e32 v[236:237], v143
	v_cvt_pk_f32_fp8_sdwa v[238:239], v143 src0_sel:WORD_1
	v_pk_fma_f32 v[228:229], v[66:67], v[236:237], v[228:229] op_sel_hi:[0,1,1]
	v_pk_fma_f32 v[230:231], v[66:67], v[238:239], v[230:231] op_sel_hi:[0,1,1]
	s_waitcnt vmcnt(16)
	v_cvt_pk_f32_fp8_e32 v[232:233], v144
	v_cvt_pk_f32_fp8_sdwa v[234:235], v144 src0_sel:WORD_1
	v_pk_fma_f32 v[216:217], v[66:67], v[232:233], v[216:217] op_sel:[1,0,0]
	v_pk_fma_f32 v[218:219], v[66:67], v[234:235], v[218:219] op_sel:[1,0,0]
	v_cvt_pk_f32_fp8_e32 v[236:237], v145
	v_cvt_pk_f32_fp8_sdwa v[238:239], v145 src0_sel:WORD_1
	v_pk_fma_f32 v[220:221], v[66:67], v[236:237], v[220:221] op_sel:[1,0,0]
	v_pk_fma_f32 v[222:223], v[66:67], v[238:239], v[222:223] op_sel:[1,0,0]
	v_cvt_pk_f32_fp8_e32 v[232:233], v146
	v_cvt_pk_f32_fp8_sdwa v[234:235], v146 src0_sel:WORD_1
	v_pk_fma_f32 v[224:225], v[66:67], v[232:233], v[224:225] op_sel:[1,0,0]
	v_pk_fma_f32 v[226:227], v[66:67], v[234:235], v[226:227] op_sel:[1,0,0]
	v_cvt_pk_f32_fp8_e32 v[236:237], v147
	v_cvt_pk_f32_fp8_sdwa v[238:239], v147 src0_sel:WORD_1
	v_pk_fma_f32 v[228:229], v[66:67], v[236:237], v[228:229] op_sel:[1,0,0]
	v_pk_fma_f32 v[230:231], v[66:67], v[238:239], v[230:231] op_sel:[1,0,0]
	ds_write2_b32 v5, v10, v11 offset0:4 offset1:20
	ds_write2_b32 v5, v12, v13 offset0:132 offset1:148
	s_waitcnt lgkmcnt(0)
	ds_read_b128 v[20:23], v6 offset:16
	ds_read_b128 v[24:27], v6 offset:32
	ds_read_b128 v[28:31], v6 offset:48
	ds_read_b128 v[32:35], v6 offset:64
	ds_read_b128 v[36:39], v6 offset:80
	ds_read_b128 v[40:43], v6 offset:96
	ds_read_b128 v[44:47], v6 offset:112
	ds_read_b128 v[48:51], v6 offset:128
	s_waitcnt vmcnt(15)
	v_cvt_pk_f32_fp8_e32 v[232:233], v148
	v_cvt_pk_f32_fp8_sdwa v[234:235], v148 src0_sel:WORD_1
	v_pk_fma_f32 v[216:217], v[68:69], v[232:233], v[216:217] op_sel_hi:[0,1,1]
	v_pk_fma_f32 v[218:219], v[68:69], v[234:235], v[218:219] op_sel_hi:[0,1,1]
	v_cvt_pk_f32_fp8_e32 v[236:237], v149
	v_cvt_pk_f32_fp8_sdwa v[238:239], v149 src0_sel:WORD_1
	v_pk_fma_f32 v[220:221], v[68:69], v[236:237], v[220:221] op_sel_hi:[0,1,1]
	v_pk_fma_f32 v[222:223], v[68:69], v[238:239], v[222:223] op_sel_hi:[0,1,1]
	v_cvt_pk_f32_fp8_e32 v[232:233], v150
	v_cvt_pk_f32_fp8_sdwa v[234:235], v150 src0_sel:WORD_1
	v_pk_fma_f32 v[224:225], v[68:69], v[232:233], v[224:225] op_sel_hi:[0,1,1]
	v_pk_fma_f32 v[226:227], v[68:69], v[234:235], v[226:227] op_sel_hi:[0,1,1]
	v_cvt_pk_f32_fp8_e32 v[236:237], v151
	v_cvt_pk_f32_fp8_sdwa v[238:239], v151 src0_sel:WORD_1
	v_pk_fma_f32 v[228:229], v[68:69], v[236:237], v[228:229] op_sel_hi:[0,1,1]
	v_pk_fma_f32 v[230:231], v[68:69], v[238:239], v[230:231] op_sel_hi:[0,1,1]
	s_waitcnt vmcnt(14)
; DI f2_t cvt8lo(unsigned w) { return __builtin_amdgcn_cvt_pk_f32_fp8(w, false); }
; DI f2_t cvt8hi(unsigned w) { return __builtin_amdgcn_cvt_pk_f32_fp8(w, true); }
; DI void phase11(const Params& p, char* smem, int rep) {
;     ...
; #pragma unroll
;         for (int k = 0; k < 16; ++k) {
;           const f2_t a2 = {aa[k], aa[k]};
; #pragma unroll
;           for (int d = 0; d < 4; ++d) { const unsigned ww = rows[k][d]; o[2 * d] += a2 * cvt8lo(ww); o[2 * d + 1] += a2 * cvt8hi(ww); }
	v_cvt_pk_f32_fp8_e32 v[232:233], v152
	v_cvt_pk_f32_fp8_sdwa v[234:235], v152 src0_sel:WORD_1
	v_pk_fma_f32 v[216:217], v[68:69], v[232:233], v[216:217] op_sel:[1,0,0]
	v_pk_fma_f32 v[218:219], v[68:69], v[234:235], v[218:219] op_sel:[1,0,0]
	v_cvt_pk_f32_fp8_e32 v[236:237], v153
	v_cvt_pk_f32_fp8_sdwa v[238:239], v153 src0_sel:WORD_1
	v_pk_fma_f32 v[220:221], v[68:69], v[236:237], v[220:221] op_sel:[1,0,0]
	v_pk_fma_f32 v[222:223], v[68:69], v[238:239], v[222:223] op_sel:[1,0,0]
	v_cvt_pk_f32_fp8_e32 v[232:233], v154
	v_cvt_pk_f32_fp8_sdwa v[234:235], v154 src0_sel:WORD_1
	v_pk_fma_f32 v[224:225], v[68:69], v[232:233], v[224:225] op_sel:[1,0,0]
	v_pk_fma_f32 v[226:227], v[68:69], v[234:235], v[226:227] op_sel:[1,0,0]
	v_cvt_pk_f32_fp8_e32 v[236:237], v155
	v_cvt_pk_f32_fp8_sdwa v[238:239], v155 src0_sel:WORD_1
	v_pk_fma_f32 v[228:229], v[68:69], v[236:237], v[228:229] op_sel:[1,0,0]
	v_pk_fma_f32 v[230:231], v[68:69], v[238:239], v[230:231] op_sel:[1,0,0]
	s_waitcnt vmcnt(13)
	v_cvt_pk_f32_fp8_e32 v[232:233], v156
	v_cvt_pk_f32_fp8_sdwa v[234:235], v156 src0_sel:WORD_1
	v_pk_fma_f32 v[216:217], v[70:71], v[232:233], v[216:217] op_sel_hi:[0,1,1]
	v_pk_fma_f32 v[218:219], v[70:71], v[234:235], v[218:219] op_sel_hi:[0,1,1]
	v_cvt_pk_f32_fp8_e32 v[236:237], v157
	v_cvt_pk_f32_fp8_sdwa v[238:239], v157 src0_sel:WORD_1
	v_pk_fma_f32 v[220:221], v[70:71], v[236:237], v[220:221] op_sel_hi:[0,1,1]
	v_pk_fma_f32 v[222:223], v[70:71], v[238:239], v[222:223] op_sel_hi:[0,1,1]
	v_cvt_pk_f32_fp8_e32 v[232:233], v158
	v_cvt_pk_f32_fp8_sdwa v[234:235], v158 src0_sel:WORD_1
	v_pk_fma_f32 v[224:225], v[70:71], v[232:233], v[224:225] op_sel_hi:[0,1,1]
	v_pk_fma_f32 v[226:227], v[70:71], v[234:235], v[226:227] op_sel_hi:[0,1,1]
	v_cvt_pk_f32_fp8_e32 v[236:237], v159
	v_cvt_pk_f32_fp8_sdwa v[238:239], v159 src0_sel:WORD_1
	v_pk_fma_f32 v[228:229], v[70:71], v[236:237], v[228:229] op_sel_hi:[0,1,1]
	v_pk_fma_f32 v[230:231], v[70:71], v[238:239], v[230:231] op_sel_hi:[0,1,1]
	s_waitcnt vmcnt(12)
	v_cvt_pk_f32_fp8_e32 v[232:233], v160
	v_cvt_pk_f32_fp8_sdwa v[234:235], v160 src0_sel:WORD_1
	v_pk_fma_f32 v[216:217], v[70:71], v[232:233], v[216:217] op_sel:[1,0,0]
	v_pk_fma_f32 v[218:219], v[70:71], v[234:235], v[218:219] op_sel:[1,0,0]
	v_cvt_pk_f32_fp8_e32 v[236:237], v161
	v_cvt_pk_f32_fp8_sdwa v[238:239], v161 src0_sel:WORD_1
	v_pk_fma_f32 v[220:221], v[70:71], v[236:237], v[220:221] op_sel:[1,0,0]
	v_pk_fma_f32 v[222:223], v[70:71], v[238:239], v[222:223] op_sel:[1,0,0]
	v_cvt_pk_f32_fp8_e32 v[232:233], v162
	v_cvt_pk_f32_fp8_sdwa v[234:235], v162 src0_sel:WORD_1
	v_pk_fma_f32 v[224:225], v[70:71], v[232:233], v[224:225] op_sel:[1,0,0]
	v_pk_fma_f32 v[226:227], v[70:71], v[234:235], v[226:227] op_sel:[1,0,0]
	v_cvt_pk_f32_fp8_e32 v[236:237], v163
	v_cvt_pk_f32_fp8_sdwa v[238:239], v163 src0_sel:WORD_1
	v_pk_fma_f32 v[228:229], v[70:71], v[236:237], v[228:229] op_sel:[1,0,0]
	v_pk_fma_f32 v[230:231], v[70:71], v[238:239], v[230:231] op_sel:[1,0,0]
	s_waitcnt vmcnt(11)
	v_cvt_pk_f32_fp8_e32 v[232:233], v164
	v_cvt_pk_f32_fp8_sdwa v[234:235], v164 src0_sel:WORD_1
	v_pk_fma_f32 v[216:217], v[72:73], v[232:233], v[216:217] op_sel_hi:[0,1,1]
	v_pk_fma_f32 v[218:219], v[72:73], v[234:235], v[218:219] op_sel_hi:[0,1,1]
	v_cvt_pk_f32_fp8_e32 v[236:237], v165
	v_cvt_pk_f32_fp8_sdwa v[238:239], v165 src0_sel:WORD_1
	v_pk_fma_f32 v[220:221], v[72:73], v[236:237], v[220:221] op_sel_hi:[0,1,1]
	v_pk_fma_f32 v[222:223], v[72:73], v[238:239], v[222:223] op_sel_hi:[0,1,1]
	v_cvt_pk_f32_fp8_e32 v[232:233], v166
	v_cvt_pk_f32_fp8_sdwa v[234:235], v166 src0_sel:WORD_1
	v_pk_fma_f32 v[224:225], v[72:73], v[232:233], v[224:225] op_sel_hi:[0,1,1]
	v_pk_fma_f32 v[226:227], v[72:73], v[234:235], v[226:227] op_sel_hi:[0,1,1]
	v_cvt_pk_f32_fp8_e32 v[236:237], v167
	v_cvt_pk_f32_fp8_sdwa v[238:239], v167 src0_sel:WORD_1
	v_pk_fma_f32 v[228:229], v[72:73], v[236:237], v[228:229] op_sel_hi:[0,1,1]
	v_pk_fma_f32 v[230:231], v[72:73], v[238:239], v[230:231] op_sel_hi:[0,1,1]
	s_waitcnt vmcnt(10)
	v_cvt_pk_f32_fp8_e32 v[232:233], v168
	v_cvt_pk_f32_fp8_sdwa v[234:235], v168 src0_sel:WORD_1
	v_pk_fma_f32 v[216:217], v[72:73], v[232:233], v[216:217] op_sel:[1,0,0]
	v_pk_fma_f32 v[218:219], v[72:73], v[234:235], v[218:219] op_sel:[1,0,0]
	v_cvt_pk_f32_fp8_e32 v[236:237], v169
	v_cvt_pk_f32_fp8_sdwa v[238:239], v169 src0_sel:WORD_1
	v_pk_fma_f32 v[220:221], v[72:73], v[236:237], v[220:221] op_sel:[1,0,0]
	v_pk_fma_f32 v[222:223], v[72:73], v[238:239], v[222:223] op_sel:[1,0,0]
	v_cvt_pk_f32_fp8_e32 v[232:233], v170
	v_cvt_pk_f32_fp8_sdwa v[234:235], v170 src0_sel:WORD_1
	v_pk_fma_f32 v[224:225], v[72:73], v[232:233], v[224:225] op_sel:[1,0,0]
	v_pk_fma_f32 v[226:227], v[72:73], v[234:235], v[226:227] op_sel:[1,0,0]
	v_cvt_pk_f32_fp8_e32 v[236:237], v171
	v_cvt_pk_f32_fp8_sdwa v[238:239], v171 src0_sel:WORD_1
	v_pk_fma_f32 v[228:229], v[72:73], v[236:237], v[228:229] op_sel:[1,0,0]
	v_pk_fma_f32 v[230:231], v[72:73], v[238:239], v[230:231] op_sel:[1,0,0]
	s_waitcnt vmcnt(9)
	v_cvt_pk_f32_fp8_e32 v[232:233], v172
	v_cvt_pk_f32_fp8_sdwa v[234:235], v172 src0_sel:WORD_1
	v_pk_fma_f32 v[216:217], v[74:75], v[232:233], v[216:217] op_sel_hi:[0,1,1]
	v_pk_fma_f32 v[218:219], v[74:75], v[234:235], v[218:219] op_sel_hi:[0,1,1]
	v_cvt_pk_f32_fp8_e32 v[236:237], v173
	v_cvt_pk_f32_fp8_sdwa v[238:239], v173 src0_sel:WORD_1
	v_pk_fma_f32 v[220:221], v[74:75], v[236:237], v[220:221] op_sel_hi:[0,1,1]
	v_pk_fma_f32 v[222:223], v[74:75], v[238:239], v[222:223] op_sel_hi:[0,1,1]
	v_cvt_pk_f32_fp8_e32 v[232:233], v174
	v_cvt_pk_f32_fp8_sdwa v[234:235], v174 src0_sel:WORD_1
	v_pk_fma_f32 v[224:225], v[74:75], v[232:233], v[224:225] op_sel_hi:[0,1,1]
	v_pk_fma_f32 v[226:227], v[74:75], v[234:235], v[226:227] op_sel_hi:[0,1,1]
	v_cvt_pk_f32_fp8_e32 v[236:237], v175
	v_cvt_pk_f32_fp8_sdwa v[238:239], v175 src0_sel:WORD_1
	v_pk_fma_f32 v[228:229], v[74:75], v[236:237], v[228:229] op_sel_hi:[0,1,1]
	v_pk_fma_f32 v[230:231], v[74:75], v[238:239], v[230:231] op_sel_hi:[0,1,1]
	s_waitcnt vmcnt(8)
; DI f2_t cvt8lo(unsigned w) { return __builtin_amdgcn_cvt_pk_f32_fp8(w, false); }
; DI f2_t cvt8hi(unsigned w) { return __builtin_amdgcn_cvt_pk_f32_fp8(w, true); }
; DI void phase11(const Params& p, char* smem, int rep) {
;     ...
; #pragma unroll
;         for (int k = 0; k < 16; ++k) {
;           const f2_t a2 = {aa[k], aa[k]};
; #pragma unroll
;           for (int d = 0; d < 4; ++d) { const unsigned ww = rows[k][d]; o[2 * d] += a2 * cvt8lo(ww); o[2 * d + 1] += a2 * cvt8hi(ww); }
	v_cvt_pk_f32_fp8_e32 v[232:233], v176
	v_cvt_pk_f32_fp8_sdwa v[234:235], v176 src0_sel:WORD_1
	v_pk_fma_f32 v[216:217], v[74:75], v[232:233], v[216:217] op_sel:[1,0,0]
	v_pk_fma_f32 v[218:219], v[74:75], v[234:235], v[218:219] op_sel:[1,0,0]
	v_cvt_pk_f32_fp8_e32 v[236:237], v177
	v_cvt_pk_f32_fp8_sdwa v[238:239], v177 src0_sel:WORD_1
	v_pk_fma_f32 v[220:221], v[74:75], v[236:237], v[220:221] op_sel:[1,0,0]
	v_pk_fma_f32 v[222:223], v[74:75], v[238:239], v[222:223] op_sel:[1,0,0]
	v_cvt_pk_f32_fp8_e32 v[232:233], v178
	v_cvt_pk_f32_fp8_sdwa v[234:235], v178 src0_sel:WORD_1
	v_pk_fma_f32 v[224:225], v[74:75], v[232:233], v[224:225] op_sel:[1,0,0]
	v_pk_fma_f32 v[226:227], v[74:75], v[234:235], v[226:227] op_sel:[1,0,0]
	v_cvt_pk_f32_fp8_e32 v[236:237], v179
	v_cvt_pk_f32_fp8_sdwa v[238:239], v179 src0_sel:WORD_1
	v_pk_fma_f32 v[228:229], v[74:75], v[236:237], v[228:229] op_sel:[1,0,0]
	v_pk_fma_f32 v[230:231], v[74:75], v[238:239], v[230:231] op_sel:[1,0,0]
	s_waitcnt vmcnt(7)
	v_cvt_pk_f32_fp8_e32 v[232:233], v180
	v_cvt_pk_f32_fp8_sdwa v[234:235], v180 src0_sel:WORD_1
	v_pk_fma_f32 v[216:217], v[76:77], v[232:233], v[216:217] op_sel_hi:[0,1,1]
	v_pk_fma_f32 v[218:219], v[76:77], v[234:235], v[218:219] op_sel_hi:[0,1,1]
	v_cvt_pk_f32_fp8_e32 v[236:237], v181
	v_cvt_pk_f32_fp8_sdwa v[238:239], v181 src0_sel:WORD_1
	v_pk_fma_f32 v[220:221], v[76:77], v[236:237], v[220:221] op_sel_hi:[0,1,1]
	v_pk_fma_f32 v[222:223], v[76:77], v[238:239], v[222:223] op_sel_hi:[0,1,1]
	v_cvt_pk_f32_fp8_e32 v[232:233], v182
	v_cvt_pk_f32_fp8_sdwa v[234:235], v182 src0_sel:WORD_1
	v_pk_fma_f32 v[224:225], v[76:77], v[232:233], v[224:225] op_sel_hi:[0,1,1]
	v_pk_fma_f32 v[226:227], v[76:77], v[234:235], v[226:227] op_sel_hi:[0,1,1]
	v_cvt_pk_f32_fp8_e32 v[236:237], v183
	v_cvt_pk_f32_fp8_sdwa v[238:239], v183 src0_sel:WORD_1
	v_pk_fma_f32 v[228:229], v[76:77], v[236:237], v[228:229] op_sel_hi:[0,1,1]
	v_pk_fma_f32 v[230:231], v[76:77], v[238:239], v[230:231] op_sel_hi:[0,1,1]
	s_waitcnt vmcnt(6)
	v_cvt_pk_f32_fp8_e32 v[232:233], v184
	v_cvt_pk_f32_fp8_sdwa v[234:235], v184 src0_sel:WORD_1
	v_pk_fma_f32 v[216:217], v[76:77], v[232:233], v[216:217] op_sel:[1,0,0]
	v_pk_fma_f32 v[218:219], v[76:77], v[234:235], v[218:219] op_sel:[1,0,0]
	v_cvt_pk_f32_fp8_e32 v[236:237], v185
	v_cvt_pk_f32_fp8_sdwa v[238:239], v185 src0_sel:WORD_1
	v_pk_fma_f32 v[220:221], v[76:77], v[236:237], v[220:221] op_sel:[1,0,0]
	v_pk_fma_f32 v[222:223], v[76:77], v[238:239], v[222:223] op_sel:[1,0,0]
	v_cvt_pk_f32_fp8_e32 v[232:233], v186
	v_cvt_pk_f32_fp8_sdwa v[234:235], v186 src0_sel:WORD_1
	v_pk_fma_f32 v[224:225], v[76:77], v[232:233], v[224:225] op_sel:[1,0,0]
	v_pk_fma_f32 v[226:227], v[76:77], v[234:235], v[226:227] op_sel:[1,0,0]
	v_cvt_pk_f32_fp8_e32 v[236:237], v187
	v_cvt_pk_f32_fp8_sdwa v[238:239], v187 src0_sel:WORD_1
	v_pk_fma_f32 v[228:229], v[76:77], v[236:237], v[228:229] op_sel:[1,0,0]
	v_pk_fma_f32 v[230:231], v[76:77], v[238:239], v[230:231] op_sel:[1,0,0]
	s_waitcnt vmcnt(5)
	v_cvt_pk_f32_fp8_e32 v[232:233], v190
	v_cvt_pk_f32_fp8_sdwa v[234:235], v190 src0_sel:WORD_1
	v_pk_fma_f32 v[216:217], v[78:79], v[232:233], v[216:217] op_sel_hi:[0,1,1]
	v_pk_fma_f32 v[218:219], v[78:79], v[234:235], v[218:219] op_sel_hi:[0,1,1]
	v_cvt_pk_f32_fp8_e32 v[236:237], v191
	v_cvt_pk_f32_fp8_sdwa v[238:239], v191 src0_sel:WORD_1
	v_pk_fma_f32 v[220:221], v[78:79], v[236:237], v[220:221] op_sel_hi:[0,1,1]
	v_pk_fma_f32 v[222:223], v[78:79], v[238:239], v[222:223] op_sel_hi:[0,1,1]
	v_cvt_pk_f32_fp8_e32 v[232:233], v192
	v_cvt_pk_f32_fp8_sdwa v[234:235], v192 src0_sel:WORD_1
	v_pk_fma_f32 v[224:225], v[78:79], v[232:233], v[224:225] op_sel_hi:[0,1,1]
	v_pk_fma_f32 v[226:227], v[78:79], v[234:235], v[226:227] op_sel_hi:[0,1,1]
	v_cvt_pk_f32_fp8_e32 v[236:237], v193
	v_cvt_pk_f32_fp8_sdwa v[238:239], v193 src0_sel:WORD_1
	v_pk_fma_f32 v[228:229], v[78:79], v[236:237], v[228:229] op_sel_hi:[0,1,1]
	v_pk_fma_f32 v[230:231], v[78:79], v[238:239], v[230:231] op_sel_hi:[0,1,1]
	s_waitcnt vmcnt(4)
	v_cvt_pk_f32_fp8_e32 v[232:233], v194
	v_cvt_pk_f32_fp8_sdwa v[234:235], v194 src0_sel:WORD_1
	v_pk_fma_f32 v[216:217], v[78:79], v[232:233], v[216:217] op_sel:[1,0,0]
	v_pk_fma_f32 v[218:219], v[78:79], v[234:235], v[218:219] op_sel:[1,0,0]
	v_cvt_pk_f32_fp8_e32 v[236:237], v195
	v_cvt_pk_f32_fp8_sdwa v[238:239], v195 src0_sel:WORD_1
	v_pk_fma_f32 v[220:221], v[78:79], v[236:237], v[220:221] op_sel:[1,0,0]
	v_pk_fma_f32 v[222:223], v[78:79], v[238:239], v[222:223] op_sel:[1,0,0]
	v_cvt_pk_f32_fp8_e32 v[232:233], v196
	v_cvt_pk_f32_fp8_sdwa v[234:235], v196 src0_sel:WORD_1
	v_pk_fma_f32 v[224:225], v[78:79], v[232:233], v[224:225] op_sel:[1,0,0]
	v_pk_fma_f32 v[226:227], v[78:79], v[234:235], v[226:227] op_sel:[1,0,0]
	v_cvt_pk_f32_fp8_e32 v[236:237], v197
	v_cvt_pk_f32_fp8_sdwa v[238:239], v197 src0_sel:WORD_1
	v_pk_fma_f32 v[228:229], v[78:79], v[236:237], v[228:229] op_sel:[1,0,0]
	v_pk_fma_f32 v[230:231], v[78:79], v[238:239], v[230:231] op_sel:[1,0,0]
	s_waitcnt vmcnt(3)
	v_cvt_pk_f32_fp8_e32 v[232:233], v198
	v_cvt_pk_f32_fp8_sdwa v[234:235], v198 src0_sel:WORD_1
	v_pk_fma_f32 v[216:217], v[80:81], v[232:233], v[216:217] op_sel_hi:[0,1,1]
	v_pk_fma_f32 v[218:219], v[80:81], v[234:235], v[218:219] op_sel_hi:[0,1,1]
	v_cvt_pk_f32_fp8_e32 v[236:237], v199
	v_cvt_pk_f32_fp8_sdwa v[238:239], v199 src0_sel:WORD_1
	v_pk_fma_f32 v[220:221], v[80:81], v[236:237], v[220:221] op_sel_hi:[0,1,1]
	v_pk_fma_f32 v[222:223], v[80:81], v[238:239], v[222:223] op_sel_hi:[0,1,1]
	v_cvt_pk_f32_fp8_e32 v[232:233], v200
	v_cvt_pk_f32_fp8_sdwa v[234:235], v200 src0_sel:WORD_1
	v_pk_fma_f32 v[224:225], v[80:81], v[232:233], v[224:225] op_sel_hi:[0,1,1]
	v_pk_fma_f32 v[226:227], v[80:81], v[234:235], v[226:227] op_sel_hi:[0,1,1]
	v_cvt_pk_f32_fp8_e32 v[236:237], v201
	v_cvt_pk_f32_fp8_sdwa v[238:239], v201 src0_sel:WORD_1
	v_pk_fma_f32 v[228:229], v[80:81], v[236:237], v[228:229] op_sel_hi:[0,1,1]
	v_pk_fma_f32 v[230:231], v[80:81], v[238:239], v[230:231] op_sel_hi:[0,1,1]
	s_waitcnt vmcnt(2)
; DI unsigned pk2(float a, float b) { f2_t v = {a, b}; bf2_t r = __builtin_convertvector(v, bf2_t); return __builtin_bit_cast(unsigned, r); }
; DI f2_t cvt8lo(unsigned w) { return __builtin_amdgcn_cvt_pk_f32_fp8(w, false); }
; DI f2_t cvt8hi(unsigned w) { return __builtin_amdgcn_cvt_pk_f32_fp8(w, true); }
; DI void phase11(const Params& p, char* smem, int rep) {
;     ...
;       const int tok = __builtin_amdgcn_readfirstlane(c * 16 + w * 4 + t);
;       const int i0 = IDS[(size_t)tok * 128 + lane], i1 = IDS[(size_t)tok * 128 + 64 + lane];
;     ...
;         for (int k = 0; k < 16; ++k) {
;           const f2_t a2 = {aa[k], aa[k]};
; #pragma unroll
;           for (int d = 0; d < 4; ++d) { const unsigned ww = rows[k][d]; o[2 * d] += a2 * cvt8lo(ww); o[2 * d + 1] += a2 * cvt8hi(ww); }
;         }
;       }
;       float ov[16];
; #pragma unroll
;       for (int d = 0; d < 4; ++d) { ov[4 * d] = o[2 * d].x; ov[4 * d + 1] = o[2 * d].y; ov[4 * d + 2] = o[2 * d + 1].x; ov[4 * d + 3] = o[2 * d + 1].y; }
;       float q8[8], q4[4];
; #pragma unroll
;       for (int k = 0; k < 8; ++k) q8[k] = (b5 ? ov[8 + k] : ov[k]) + __shfl_xor(b5 ? ov[k] : ov[8 + k], 32);
; #pragma unroll
;       for (int k = 0; k < 4; ++k) q4[k] = (b4 ? q8[4 + k] : q8[k]) + __shfl_xor(b4 ? q8[k] : q8[4 + k], 16);
;       *(uint2*)(OUTP + (size_t)tok * D_ + s * 256 + l15 * 16 + 8 * b5 + 4 * b4) = make_uint2(pk2(q4[0], q4[1]), pk2(q4[2], q4[3]));
	v_cvt_pk_f32_fp8_e32 v[232:233], v202
	v_cvt_pk_f32_fp8_sdwa v[234:235], v202 src0_sel:WORD_1
	v_pk_fma_f32 v[216:217], v[80:81], v[232:233], v[216:217] op_sel:[1,0,0]
	v_pk_fma_f32 v[218:219], v[80:81], v[234:235], v[218:219] op_sel:[1,0,0]
	v_cvt_pk_f32_fp8_e32 v[236:237], v203
	v_cvt_pk_f32_fp8_sdwa v[238:239], v203 src0_sel:WORD_1
	v_pk_fma_f32 v[220:221], v[80:81], v[236:237], v[220:221] op_sel:[1,0,0]
	v_pk_fma_f32 v[222:223], v[80:81], v[238:239], v[222:223] op_sel:[1,0,0]
	v_cvt_pk_f32_fp8_e32 v[232:233], v204
	v_cvt_pk_f32_fp8_sdwa v[234:235], v204 src0_sel:WORD_1
	v_pk_fma_f32 v[224:225], v[80:81], v[232:233], v[224:225] op_sel:[1,0,0]
	v_pk_fma_f32 v[226:227], v[80:81], v[234:235], v[226:227] op_sel:[1,0,0]
	v_cvt_pk_f32_fp8_e32 v[236:237], v205
	v_cvt_pk_f32_fp8_sdwa v[238:239], v205 src0_sel:WORD_1
	v_pk_fma_f32 v[228:229], v[80:81], v[236:237], v[228:229] op_sel:[1,0,0]
	v_pk_fma_f32 v[230:231], v[80:81], v[238:239], v[230:231] op_sel:[1,0,0]
	s_waitcnt vmcnt(1)
	v_cvt_pk_f32_fp8_e32 v[232:233], v206
	v_cvt_pk_f32_fp8_sdwa v[234:235], v206 src0_sel:WORD_1
	v_pk_fma_f32 v[216:217], v[82:83], v[232:233], v[216:217] op_sel_hi:[0,1,1]
	v_pk_fma_f32 v[218:219], v[82:83], v[234:235], v[218:219] op_sel_hi:[0,1,1]
	v_cvt_pk_f32_fp8_e32 v[236:237], v207
	v_cvt_pk_f32_fp8_sdwa v[238:239], v207 src0_sel:WORD_1
	v_pk_fma_f32 v[220:221], v[82:83], v[236:237], v[220:221] op_sel_hi:[0,1,1]
	v_pk_fma_f32 v[222:223], v[82:83], v[238:239], v[222:223] op_sel_hi:[0,1,1]
	v_cvt_pk_f32_fp8_e32 v[232:233], v208
	v_cvt_pk_f32_fp8_sdwa v[234:235], v208 src0_sel:WORD_1
	v_pk_fma_f32 v[224:225], v[82:83], v[232:233], v[224:225] op_sel_hi:[0,1,1]
	v_pk_fma_f32 v[226:227], v[82:83], v[234:235], v[226:227] op_sel_hi:[0,1,1]
	v_cvt_pk_f32_fp8_e32 v[236:237], v209
	v_cvt_pk_f32_fp8_sdwa v[238:239], v209 src0_sel:WORD_1
	v_pk_fma_f32 v[228:229], v[82:83], v[236:237], v[228:229] op_sel_hi:[0,1,1]
	v_pk_fma_f32 v[230:231], v[82:83], v[238:239], v[230:231] op_sel_hi:[0,1,1]
	s_waitcnt vmcnt(0)
	v_cvt_pk_f32_fp8_e32 v[232:233], v210
	v_cvt_pk_f32_fp8_sdwa v[234:235], v210 src0_sel:WORD_1
	v_pk_fma_f32 v[216:217], v[82:83], v[232:233], v[216:217] op_sel:[1,0,0]
	v_pk_fma_f32 v[218:219], v[82:83], v[234:235], v[218:219] op_sel:[1,0,0]
	v_cvt_pk_f32_fp8_e32 v[236:237], v211
	v_cvt_pk_f32_fp8_sdwa v[238:239], v211 src0_sel:WORD_1
	v_pk_fma_f32 v[220:221], v[82:83], v[236:237], v[220:221] op_sel:[1,0,0]
	v_pk_fma_f32 v[222:223], v[82:83], v[238:239], v[222:223] op_sel:[1,0,0]
	v_cvt_pk_f32_fp8_e32 v[232:233], v212
	v_cvt_pk_f32_fp8_sdwa v[234:235], v212 src0_sel:WORD_1
	v_pk_fma_f32 v[224:225], v[82:83], v[232:233], v[224:225] op_sel:[1,0,0]
	v_pk_fma_f32 v[226:227], v[82:83], v[234:235], v[226:227] op_sel:[1,0,0]
	v_cvt_pk_f32_fp8_e32 v[236:237], v213
	v_cvt_pk_f32_fp8_sdwa v[238:239], v213 src0_sel:WORD_1
	v_pk_fma_f32 v[228:229], v[82:83], v[236:237], v[228:229] op_sel:[1,0,0]
	v_pk_fma_f32 v[230:231], v[82:83], v[238:239], v[230:231] op_sel:[1,0,0]
	ds_read_b128 v[52:55], v6 offset:528
	ds_read_b128 v[56:59], v6 offset:544
	ds_read_b128 v[60:63], v6 offset:560
	ds_read_b128 v[64:67], v6 offset:576
	ds_read_b128 v[68:71], v6 offset:592
	ds_read_b128 v[72:75], v6 offset:608
	ds_read_b128 v[76:79], v6 offset:624
	ds_read_b128 v[80:83], v6 offset:640
	s_add_u32 s56, s14, s46
	s_addc_u32 s57, s15, 0
	s_nop 0
	v_permlane32_swap_b32_e32 v216, v224
	v_permlane32_swap_b32_e32 v217, v225
	v_permlane32_swap_b32_e32 v218, v226
	v_permlane32_swap_b32_e32 v219, v227
	v_permlane32_swap_b32_e32 v220, v228
	v_permlane32_swap_b32_e32 v221, v229
	v_permlane32_swap_b32_e32 v222, v230
	v_permlane32_swap_b32_e32 v223, v231
	v_pk_add_f32 v[216:217], v[216:217], v[224:225]
	v_pk_add_f32 v[218:219], v[218:219], v[226:227]
	v_pk_add_f32 v[220:221], v[220:221], v[228:229]
	v_pk_add_f32 v[222:223], v[222:223], v[230:231]
	s_nop 1
	v_permlane16_swap_b32_e32 v216, v220
	v_permlane16_swap_b32_e32 v217, v221
	v_permlane16_swap_b32_e32 v218, v222
	v_permlane16_swap_b32_e32 v219, v223
	v_pk_add_f32 v[216:217], v[216:217], v[220:221]
	v_pk_add_f32 v[218:219], v[218:219], v[222:223]
	v_cvt_pk_bf16_f32 v232, v216, v217
	v_cvt_pk_bf16_f32 v233, v218, v219
	global_store_dwordx2 v4, v[232:233], s[56:57]
	s_add_i32 s54, s34, 2
	s_lshl_b32 s46, s54, 12
	s_add_i32 s46, s46, s24
	s_add_i32 s55, s34, 3
	s_lshl_b32 s47, s55, 9
	s_add_u32 s42, s6, s47
	s_addc_u32 s43, s7, 0
	s_add_u32 s44, s8, s47
	s_addc_u32 s45, s9, 0
	global_load_dword v10, v3, s[42:43]
	global_load_dword v11, v3, s[42:43] offset:256
	global_load_dword v12, v3, s[44:45]
	global_load_dword v13, v3, s[44:45] offset:256
	s_waitcnt lgkmcnt(0)
; DI f2_t cvt8lo(unsigned w) { return __builtin_amdgcn_cvt_pk_f32_fp8(w, false); }
; DI f2_t cvt8hi(unsigned w) { return __builtin_amdgcn_cvt_pk_f32_fp8(w, true); }
; DI void phase11(const Params& p, char* smem, int rep) {
;     ...
;         for (int k = 0; k < 16; ++k) rows[k] = *(const u32x4*)(vb + (size_t)ida[k] * 2048);
; #pragma unroll
;         for (int k = 0; k < 16; ++k) {
;           const f2_t a2 = {aa[k], aa[k]};
; #pragma unroll
;           for (int d = 0; d < 4; ++d) { const unsigned ww = rows[k][d]; o[2 * d] += a2 * cvt8lo(ww); o[2 * d + 1] += a2 * cvt8hi(ww); }
	v_lshl_add_u32 v20, v20, 11, v2
	v_lshl_add_u32 v21, v21, 11, v2
	v_lshl_add_u32 v22, v22, 11, v2
	v_lshl_add_u32 v23, v23, 11, v2
	v_lshl_add_u32 v24, v24, 11, v2
	v_lshl_add_u32 v25, v25, 11, v2
	v_lshl_add_u32 v26, v26, 11, v2
	v_lshl_add_u32 v27, v27, 11, v2
	v_lshl_add_u32 v28, v28, 11, v2
	v_lshl_add_u32 v29, v29, 11, v2
	v_lshl_add_u32 v30, v30, 11, v2
	v_lshl_add_u32 v31, v31, 11, v2
	v_lshl_add_u32 v32, v32, 11, v2
	v_lshl_add_u32 v33, v33, 11, v2
	v_lshl_add_u32 v34, v34, 11, v2
	v_lshl_add_u32 v35, v35, 11, v2
	v_lshl_add_u32 v36, v36, 11, v2
	v_lshl_add_u32 v37, v37, 11, v2
	v_lshl_add_u32 v38, v38, 11, v2
	v_lshl_add_u32 v39, v39, 11, v2
	v_lshl_add_u32 v40, v40, 11, v2
	v_lshl_add_u32 v41, v41, 11, v2
	v_lshl_add_u32 v42, v42, 11, v2
	v_lshl_add_u32 v43, v43, 11, v2
	v_lshl_add_u32 v44, v44, 11, v2
	v_lshl_add_u32 v45, v45, 11, v2
	v_lshl_add_u32 v46, v46, 11, v2
	v_lshl_add_u32 v47, v47, 11, v2
	v_lshl_add_u32 v48, v48, 11, v2
	v_lshl_add_u32 v49, v49, 11, v2
	v_lshl_add_u32 v50, v50, 11, v2
	v_lshl_add_u32 v51, v51, 11, v2
	global_load_dwordx4 v[84:87], v20, s[20:21]
	global_load_dwordx4 v[88:91], v21, s[20:21]
	global_load_dwordx4 v[92:95], v22, s[20:21]
	global_load_dwordx4 v[96:99], v23, s[20:21]
	global_load_dwordx4 v[100:103], v24, s[20:21]
	global_load_dwordx4 v[104:107], v25, s[20:21]
	global_load_dwordx4 v[108:111], v26, s[20:21]
	global_load_dwordx4 v[112:115], v27, s[20:21]
	global_load_dwordx4 v[116:119], v28, s[20:21]
	global_load_dwordx4 v[120:123], v29, s[20:21]
	global_load_dwordx4 v[124:127], v30, s[20:21]
	global_load_dwordx4 v[128:131], v31, s[20:21]
	global_load_dwordx4 v[132:135], v32, s[20:21]
	global_load_dwordx4 v[136:139], v33, s[20:21]
	global_load_dwordx4 v[140:143], v34, s[20:21]
	global_load_dwordx4 v[144:147], v35, s[20:21]
	global_load_dwordx4 v[148:151], v36, s[20:21]
	global_load_dwordx4 v[152:155], v37, s[20:21]
	global_load_dwordx4 v[156:159], v38, s[20:21]
	global_load_dwordx4 v[160:163], v39, s[20:21]
	global_load_dwordx4 v[164:167], v40, s[20:21]
	global_load_dwordx4 v[168:171], v41, s[20:21]
	global_load_dwordx4 v[172:175], v42, s[20:21]
	global_load_dwordx4 v[176:179], v43, s[20:21]
	global_load_dwordx4 v[180:183], v44, s[20:21]
	global_load_dwordx4 v[184:187], v45, s[20:21]
	global_load_dwordx4 v[190:193], v46, s[20:21]
	global_load_dwordx4 v[194:197], v47, s[20:21]
	global_load_dwordx4 v[198:201], v48, s[20:21]
	global_load_dwordx4 v[202:205], v49, s[20:21]
	global_load_dwordx4 v[206:209], v50, s[20:21]
	global_load_dwordx4 v[210:213], v51, s[20:21]
	s_waitcnt vmcnt(31)
	v_cvt_pk_f32_fp8_e32 v[232:233], v84
	v_cvt_pk_f32_fp8_sdwa v[234:235], v84 src0_sel:WORD_1
	v_pk_fma_f32 v[216:217], v[52:53], v[232:233], 0 op_sel_hi:[0,1,0]
	v_pk_fma_f32 v[218:219], v[52:53], v[234:235], 0 op_sel_hi:[0,1,0]
	v_cvt_pk_f32_fp8_e32 v[236:237], v85
	v_cvt_pk_f32_fp8_sdwa v[238:239], v85 src0_sel:WORD_1
	v_pk_fma_f32 v[220:221], v[52:53], v[236:237], 0 op_sel_hi:[0,1,0]
	v_pk_fma_f32 v[222:223], v[52:53], v[238:239], 0 op_sel_hi:[0,1,0]
	v_cvt_pk_f32_fp8_e32 v[232:233], v86
	v_cvt_pk_f32_fp8_sdwa v[234:235], v86 src0_sel:WORD_1
	v_pk_fma_f32 v[224:225], v[52:53], v[232:233], 0 op_sel_hi:[0,1,0]
	v_pk_fma_f32 v[226:227], v[52:53], v[234:235], 0 op_sel_hi:[0,1,0]
	v_cvt_pk_f32_fp8_e32 v[236:237], v87
	v_cvt_pk_f32_fp8_sdwa v[238:239], v87 src0_sel:WORD_1
	v_pk_fma_f32 v[228:229], v[52:53], v[236:237], 0 op_sel_hi:[0,1,0]
	v_pk_fma_f32 v[230:231], v[52:53], v[238:239], 0 op_sel_hi:[0,1,0]
	s_waitcnt vmcnt(30)
	v_cvt_pk_f32_fp8_e32 v[232:233], v88
	v_cvt_pk_f32_fp8_sdwa v[234:235], v88 src0_sel:WORD_1
	v_pk_fma_f32 v[216:217], v[52:53], v[232:233], v[216:217] op_sel:[1,0,0]
	v_pk_fma_f32 v[218:219], v[52:53], v[234:235], v[218:219] op_sel:[1,0,0]
	v_cvt_pk_f32_fp8_e32 v[236:237], v89
	v_cvt_pk_f32_fp8_sdwa v[238:239], v89 src0_sel:WORD_1
	v_pk_fma_f32 v[220:221], v[52:53], v[236:237], v[220:221] op_sel:[1,0,0]
	v_pk_fma_f32 v[222:223], v[52:53], v[238:239], v[222:223] op_sel:[1,0,0]
	v_cvt_pk_f32_fp8_e32 v[232:233], v90
	v_cvt_pk_f32_fp8_sdwa v[234:235], v90 src0_sel:WORD_1
	v_pk_fma_f32 v[224:225], v[52:53], v[232:233], v[224:225] op_sel:[1,0,0]
	v_pk_fma_f32 v[226:227], v[52:53], v[234:235], v[226:227] op_sel:[1,0,0]
	v_cvt_pk_f32_fp8_e32 v[236:237], v91
	v_cvt_pk_f32_fp8_sdwa v[238:239], v91 src0_sel:WORD_1
	v_pk_fma_f32 v[228:229], v[52:53], v[236:237], v[228:229] op_sel:[1,0,0]
	v_pk_fma_f32 v[230:231], v[52:53], v[238:239], v[230:231] op_sel:[1,0,0]
	s_waitcnt vmcnt(29)
	v_cvt_pk_f32_fp8_e32 v[232:233], v92
	v_cvt_pk_f32_fp8_sdwa v[234:235], v92 src0_sel:WORD_1
	v_pk_fma_f32 v[216:217], v[54:55], v[232:233], v[216:217] op_sel_hi:[0,1,1]
	v_pk_fma_f32 v[218:219], v[54:55], v[234:235], v[218:219] op_sel_hi:[0,1,1]
	v_cvt_pk_f32_fp8_e32 v[236:237], v93
	v_cvt_pk_f32_fp8_sdwa v[238:239], v93 src0_sel:WORD_1
	v_pk_fma_f32 v[220:221], v[54:55], v[236:237], v[220:221] op_sel_hi:[0,1,1]
	v_pk_fma_f32 v[222:223], v[54:55], v[238:239], v[222:223] op_sel_hi:[0,1,1]
	v_cvt_pk_f32_fp8_e32 v[232:233], v94
	v_cvt_pk_f32_fp8_sdwa v[234:235], v94 src0_sel:WORD_1
	v_pk_fma_f32 v[224:225], v[54:55], v[232:233], v[224:225] op_sel_hi:[0,1,1]
	v_pk_fma_f32 v[226:227], v[54:55], v[234:235], v[226:227] op_sel_hi:[0,1,1]
	v_cvt_pk_f32_fp8_e32 v[236:237], v95
	v_cvt_pk_f32_fp8_sdwa v[238:239], v95 src0_sel:WORD_1
	v_pk_fma_f32 v[228:229], v[54:55], v[236:237], v[228:229] op_sel_hi:[0,1,1]
	v_pk_fma_f32 v[230:231], v[54:55], v[238:239], v[230:231] op_sel_hi:[0,1,1]
	s_waitcnt vmcnt(28)
; DI f2_t cvt8lo(unsigned w) { return __builtin_amdgcn_cvt_pk_f32_fp8(w, false); }
; DI f2_t cvt8hi(unsigned w) { return __builtin_amdgcn_cvt_pk_f32_fp8(w, true); }
; DI void phase11(const Params& p, char* smem, int rep) {
;     ...
; #pragma unroll
;         for (int k = 0; k < 16; ++k) {
;           const f2_t a2 = {aa[k], aa[k]};
; #pragma unroll
;           for (int d = 0; d < 4; ++d) { const unsigned ww = rows[k][d]; o[2 * d] += a2 * cvt8lo(ww); o[2 * d + 1] += a2 * cvt8hi(ww); }
	v_cvt_pk_f32_fp8_e32 v[232:233], v96
	v_cvt_pk_f32_fp8_sdwa v[234:235], v96 src0_sel:WORD_1
	v_pk_fma_f32 v[216:217], v[54:55], v[232:233], v[216:217] op_sel:[1,0,0]
	v_pk_fma_f32 v[218:219], v[54:55], v[234:235], v[218:219] op_sel:[1,0,0]
	v_cvt_pk_f32_fp8_e32 v[236:237], v97
	v_cvt_pk_f32_fp8_sdwa v[238:239], v97 src0_sel:WORD_1
	v_pk_fma_f32 v[220:221], v[54:55], v[236:237], v[220:221] op_sel:[1,0,0]
	v_pk_fma_f32 v[222:223], v[54:55], v[238:239], v[222:223] op_sel:[1,0,0]
	v_cvt_pk_f32_fp8_e32 v[232:233], v98
	v_cvt_pk_f32_fp8_sdwa v[234:235], v98 src0_sel:WORD_1
	v_pk_fma_f32 v[224:225], v[54:55], v[232:233], v[224:225] op_sel:[1,0,0]
	v_pk_fma_f32 v[226:227], v[54:55], v[234:235], v[226:227] op_sel:[1,0,0]
	v_cvt_pk_f32_fp8_e32 v[236:237], v99
	v_cvt_pk_f32_fp8_sdwa v[238:239], v99 src0_sel:WORD_1
	v_pk_fma_f32 v[228:229], v[54:55], v[236:237], v[228:229] op_sel:[1,0,0]
	v_pk_fma_f32 v[230:231], v[54:55], v[238:239], v[230:231] op_sel:[1,0,0]
	s_waitcnt vmcnt(27)
	v_cvt_pk_f32_fp8_e32 v[232:233], v100
	v_cvt_pk_f32_fp8_sdwa v[234:235], v100 src0_sel:WORD_1
	v_pk_fma_f32 v[216:217], v[56:57], v[232:233], v[216:217] op_sel_hi:[0,1,1]
	v_pk_fma_f32 v[218:219], v[56:57], v[234:235], v[218:219] op_sel_hi:[0,1,1]
	v_cvt_pk_f32_fp8_e32 v[236:237], v101
	v_cvt_pk_f32_fp8_sdwa v[238:239], v101 src0_sel:WORD_1
	v_pk_fma_f32 v[220:221], v[56:57], v[236:237], v[220:221] op_sel_hi:[0,1,1]
	v_pk_fma_f32 v[222:223], v[56:57], v[238:239], v[222:223] op_sel_hi:[0,1,1]
	v_cvt_pk_f32_fp8_e32 v[232:233], v102
	v_cvt_pk_f32_fp8_sdwa v[234:235], v102 src0_sel:WORD_1
	v_pk_fma_f32 v[224:225], v[56:57], v[232:233], v[224:225] op_sel_hi:[0,1,1]
	v_pk_fma_f32 v[226:227], v[56:57], v[234:235], v[226:227] op_sel_hi:[0,1,1]
	v_cvt_pk_f32_fp8_e32 v[236:237], v103
	v_cvt_pk_f32_fp8_sdwa v[238:239], v103 src0_sel:WORD_1
	v_pk_fma_f32 v[228:229], v[56:57], v[236:237], v[228:229] op_sel_hi:[0,1,1]
	v_pk_fma_f32 v[230:231], v[56:57], v[238:239], v[230:231] op_sel_hi:[0,1,1]
	s_waitcnt vmcnt(26)
	v_cvt_pk_f32_fp8_e32 v[232:233], v104
	v_cvt_pk_f32_fp8_sdwa v[234:235], v104 src0_sel:WORD_1
	v_pk_fma_f32 v[216:217], v[56:57], v[232:233], v[216:217] op_sel:[1,0,0]
	v_pk_fma_f32 v[218:219], v[56:57], v[234:235], v[218:219] op_sel:[1,0,0]
	v_cvt_pk_f32_fp8_e32 v[236:237], v105
	v_cvt_pk_f32_fp8_sdwa v[238:239], v105 src0_sel:WORD_1
	v_pk_fma_f32 v[220:221], v[56:57], v[236:237], v[220:221] op_sel:[1,0,0]
	v_pk_fma_f32 v[222:223], v[56:57], v[238:239], v[222:223] op_sel:[1,0,0]
	v_cvt_pk_f32_fp8_e32 v[232:233], v106
	v_cvt_pk_f32_fp8_sdwa v[234:235], v106 src0_sel:WORD_1
	v_pk_fma_f32 v[224:225], v[56:57], v[232:233], v[224:225] op_sel:[1,0,0]
	v_pk_fma_f32 v[226:227], v[56:57], v[234:235], v[226:227] op_sel:[1,0,0]
	v_cvt_pk_f32_fp8_e32 v[236:237], v107
	v_cvt_pk_f32_fp8_sdwa v[238:239], v107 src0_sel:WORD_1
	v_pk_fma_f32 v[228:229], v[56:57], v[236:237], v[228:229] op_sel:[1,0,0]
	v_pk_fma_f32 v[230:231], v[56:57], v[238:239], v[230:231] op_sel:[1,0,0]
	s_waitcnt vmcnt(25)
	v_cvt_pk_f32_fp8_e32 v[232:233], v108
	v_cvt_pk_f32_fp8_sdwa v[234:235], v108 src0_sel:WORD_1
	v_pk_fma_f32 v[216:217], v[58:59], v[232:233], v[216:217] op_sel_hi:[0,1,1]
	v_pk_fma_f32 v[218:219], v[58:59], v[234:235], v[218:219] op_sel_hi:[0,1,1]
	v_cvt_pk_f32_fp8_e32 v[236:237], v109
	v_cvt_pk_f32_fp8_sdwa v[238:239], v109 src0_sel:WORD_1
	v_pk_fma_f32 v[220:221], v[58:59], v[236:237], v[220:221] op_sel_hi:[0,1,1]
	v_pk_fma_f32 v[222:223], v[58:59], v[238:239], v[222:223] op_sel_hi:[0,1,1]
	v_cvt_pk_f32_fp8_e32 v[232:233], v110
	v_cvt_pk_f32_fp8_sdwa v[234:235], v110 src0_sel:WORD_1
	v_pk_fma_f32 v[224:225], v[58:59], v[232:233], v[224:225] op_sel_hi:[0,1,1]
	v_pk_fma_f32 v[226:227], v[58:59], v[234:235], v[226:227] op_sel_hi:[0,1,1]
	v_cvt_pk_f32_fp8_e32 v[236:237], v111
	v_cvt_pk_f32_fp8_sdwa v[238:239], v111 src0_sel:WORD_1
	v_pk_fma_f32 v[228:229], v[58:59], v[236:237], v[228:229] op_sel_hi:[0,1,1]
	v_pk_fma_f32 v[230:231], v[58:59], v[238:239], v[230:231] op_sel_hi:[0,1,1]
	s_waitcnt vmcnt(24)
	v_cvt_pk_f32_fp8_e32 v[232:233], v112
	v_cvt_pk_f32_fp8_sdwa v[234:235], v112 src0_sel:WORD_1
	v_pk_fma_f32 v[216:217], v[58:59], v[232:233], v[216:217] op_sel:[1,0,0]
	v_pk_fma_f32 v[218:219], v[58:59], v[234:235], v[218:219] op_sel:[1,0,0]
	v_cvt_pk_f32_fp8_e32 v[236:237], v113
	v_cvt_pk_f32_fp8_sdwa v[238:239], v113 src0_sel:WORD_1
	v_pk_fma_f32 v[220:221], v[58:59], v[236:237], v[220:221] op_sel:[1,0,0]
	v_pk_fma_f32 v[222:223], v[58:59], v[238:239], v[222:223] op_sel:[1,0,0]
	v_cvt_pk_f32_fp8_e32 v[232:233], v114
	v_cvt_pk_f32_fp8_sdwa v[234:235], v114 src0_sel:WORD_1
	v_pk_fma_f32 v[224:225], v[58:59], v[232:233], v[224:225] op_sel:[1,0,0]
	v_pk_fma_f32 v[226:227], v[58:59], v[234:235], v[226:227] op_sel:[1,0,0]
	v_cvt_pk_f32_fp8_e32 v[236:237], v115
	v_cvt_pk_f32_fp8_sdwa v[238:239], v115 src0_sel:WORD_1
	v_pk_fma_f32 v[228:229], v[58:59], v[236:237], v[228:229] op_sel:[1,0,0]
	v_pk_fma_f32 v[230:231], v[58:59], v[238:239], v[230:231] op_sel:[1,0,0]
	s_waitcnt vmcnt(23)
	v_cvt_pk_f32_fp8_e32 v[232:233], v116
	v_cvt_pk_f32_fp8_sdwa v[234:235], v116 src0_sel:WORD_1
	v_pk_fma_f32 v[216:217], v[60:61], v[232:233], v[216:217] op_sel_hi:[0,1,1]
	v_pk_fma_f32 v[218:219], v[60:61], v[234:235], v[218:219] op_sel_hi:[0,1,1]
	v_cvt_pk_f32_fp8_e32 v[236:237], v117
	v_cvt_pk_f32_fp8_sdwa v[238:239], v117 src0_sel:WORD_1
	v_pk_fma_f32 v[220:221], v[60:61], v[236:237], v[220:221] op_sel_hi:[0,1,1]
	v_pk_fma_f32 v[222:223], v[60:61], v[238:239], v[222:223] op_sel_hi:[0,1,1]
	v_cvt_pk_f32_fp8_e32 v[232:233], v118
	v_cvt_pk_f32_fp8_sdwa v[234:235], v118 src0_sel:WORD_1
	v_pk_fma_f32 v[224:225], v[60:61], v[232:233], v[224:225] op_sel_hi:[0,1,1]
	v_pk_fma_f32 v[226:227], v[60:61], v[234:235], v[226:227] op_sel_hi:[0,1,1]
	v_cvt_pk_f32_fp8_e32 v[236:237], v119
	v_cvt_pk_f32_fp8_sdwa v[238:239], v119 src0_sel:WORD_1
	v_pk_fma_f32 v[228:229], v[60:61], v[236:237], v[228:229] op_sel_hi:[0,1,1]
	v_pk_fma_f32 v[230:231], v[60:61], v[238:239], v[230:231] op_sel_hi:[0,1,1]
	s_waitcnt vmcnt(22)
; DI f2_t cvt8lo(unsigned w) { return __builtin_amdgcn_cvt_pk_f32_fp8(w, false); }
; DI f2_t cvt8hi(unsigned w) { return __builtin_amdgcn_cvt_pk_f32_fp8(w, true); }
; DI void phase11(const Params& p, char* smem, int rep) {
;     ...
; #pragma unroll
;         for (int k = 0; k < 16; ++k) {
;           const f2_t a2 = {aa[k], aa[k]};
; #pragma unroll
;           for (int d = 0; d < 4; ++d) { const unsigned ww = rows[k][d]; o[2 * d] += a2 * cvt8lo(ww); o[2 * d + 1] += a2 * cvt8hi(ww); }
	v_cvt_pk_f32_fp8_e32 v[232:233], v120
	v_cvt_pk_f32_fp8_sdwa v[234:235], v120 src0_sel:WORD_1
	v_pk_fma_f32 v[216:217], v[60:61], v[232:233], v[216:217] op_sel:[1,0,0]
	v_pk_fma_f32 v[218:219], v[60:61], v[234:235], v[218:219] op_sel:[1,0,0]
	v_cvt_pk_f32_fp8_e32 v[236:237], v121
	v_cvt_pk_f32_fp8_sdwa v[238:239], v121 src0_sel:WORD_1
	v_pk_fma_f32 v[220:221], v[60:61], v[236:237], v[220:221] op_sel:[1,0,0]
	v_pk_fma_f32 v[222:223], v[60:61], v[238:239], v[222:223] op_sel:[1,0,0]
	v_cvt_pk_f32_fp8_e32 v[232:233], v122
	v_cvt_pk_f32_fp8_sdwa v[234:235], v122 src0_sel:WORD_1
	v_pk_fma_f32 v[224:225], v[60:61], v[232:233], v[224:225] op_sel:[1,0,0]
	v_pk_fma_f32 v[226:227], v[60:61], v[234:235], v[226:227] op_sel:[1,0,0]
	v_cvt_pk_f32_fp8_e32 v[236:237], v123
	v_cvt_pk_f32_fp8_sdwa v[238:239], v123 src0_sel:WORD_1
	v_pk_fma_f32 v[228:229], v[60:61], v[236:237], v[228:229] op_sel:[1,0,0]
	v_pk_fma_f32 v[230:231], v[60:61], v[238:239], v[230:231] op_sel:[1,0,0]
	s_waitcnt vmcnt(21)
	v_cvt_pk_f32_fp8_e32 v[232:233], v124
	v_cvt_pk_f32_fp8_sdwa v[234:235], v124 src0_sel:WORD_1
	v_pk_fma_f32 v[216:217], v[62:63], v[232:233], v[216:217] op_sel_hi:[0,1,1]
	v_pk_fma_f32 v[218:219], v[62:63], v[234:235], v[218:219] op_sel_hi:[0,1,1]
	v_cvt_pk_f32_fp8_e32 v[236:237], v125
	v_cvt_pk_f32_fp8_sdwa v[238:239], v125 src0_sel:WORD_1
	v_pk_fma_f32 v[220:221], v[62:63], v[236:237], v[220:221] op_sel_hi:[0,1,1]
	v_pk_fma_f32 v[222:223], v[62:63], v[238:239], v[222:223] op_sel_hi:[0,1,1]
	v_cvt_pk_f32_fp8_e32 v[232:233], v126
	v_cvt_pk_f32_fp8_sdwa v[234:235], v126 src0_sel:WORD_1
	v_pk_fma_f32 v[224:225], v[62:63], v[232:233], v[224:225] op_sel_hi:[0,1,1]
	v_pk_fma_f32 v[226:227], v[62:63], v[234:235], v[226:227] op_sel_hi:[0,1,1]
	v_cvt_pk_f32_fp8_e32 v[236:237], v127
	v_cvt_pk_f32_fp8_sdwa v[238:239], v127 src0_sel:WORD_1
	v_pk_fma_f32 v[228:229], v[62:63], v[236:237], v[228:229] op_sel_hi:[0,1,1]
	v_pk_fma_f32 v[230:231], v[62:63], v[238:239], v[230:231] op_sel_hi:[0,1,1]
	s_waitcnt vmcnt(20)
	v_cvt_pk_f32_fp8_e32 v[232:233], v128
	v_cvt_pk_f32_fp8_sdwa v[234:235], v128 src0_sel:WORD_1
	v_pk_fma_f32 v[216:217], v[62:63], v[232:233], v[216:217] op_sel:[1,0,0]
	v_pk_fma_f32 v[218:219], v[62:63], v[234:235], v[218:219] op_sel:[1,0,0]
	v_cvt_pk_f32_fp8_e32 v[236:237], v129
	v_cvt_pk_f32_fp8_sdwa v[238:239], v129 src0_sel:WORD_1
	v_pk_fma_f32 v[220:221], v[62:63], v[236:237], v[220:221] op_sel:[1,0,0]
	v_pk_fma_f32 v[222:223], v[62:63], v[238:239], v[222:223] op_sel:[1,0,0]
	v_cvt_pk_f32_fp8_e32 v[232:233], v130
	v_cvt_pk_f32_fp8_sdwa v[234:235], v130 src0_sel:WORD_1
	v_pk_fma_f32 v[224:225], v[62:63], v[232:233], v[224:225] op_sel:[1,0,0]
	v_pk_fma_f32 v[226:227], v[62:63], v[234:235], v[226:227] op_sel:[1,0,0]
	v_cvt_pk_f32_fp8_e32 v[236:237], v131
	v_cvt_pk_f32_fp8_sdwa v[238:239], v131 src0_sel:WORD_1
	v_pk_fma_f32 v[228:229], v[62:63], v[236:237], v[228:229] op_sel:[1,0,0]
	v_pk_fma_f32 v[230:231], v[62:63], v[238:239], v[230:231] op_sel:[1,0,0]
	s_waitcnt vmcnt(19)
	v_cvt_pk_f32_fp8_e32 v[232:233], v132
	v_cvt_pk_f32_fp8_sdwa v[234:235], v132 src0_sel:WORD_1
	v_pk_fma_f32 v[216:217], v[64:65], v[232:233], v[216:217] op_sel_hi:[0,1,1]
	v_pk_fma_f32 v[218:219], v[64:65], v[234:235], v[218:219] op_sel_hi:[0,1,1]
	v_cvt_pk_f32_fp8_e32 v[236:237], v133
	v_cvt_pk_f32_fp8_sdwa v[238:239], v133 src0_sel:WORD_1
	v_pk_fma_f32 v[220:221], v[64:65], v[236:237], v[220:221] op_sel_hi:[0,1,1]
	v_pk_fma_f32 v[222:223], v[64:65], v[238:239], v[222:223] op_sel_hi:[0,1,1]
	v_cvt_pk_f32_fp8_e32 v[232:233], v134
	v_cvt_pk_f32_fp8_sdwa v[234:235], v134 src0_sel:WORD_1
	v_pk_fma_f32 v[224:225], v[64:65], v[232:233], v[224:225] op_sel_hi:[0,1,1]
	v_pk_fma_f32 v[226:227], v[64:65], v[234:235], v[226:227] op_sel_hi:[0,1,1]
	v_cvt_pk_f32_fp8_e32 v[236:237], v135
	v_cvt_pk_f32_fp8_sdwa v[238:239], v135 src0_sel:WORD_1
	v_pk_fma_f32 v[228:229], v[64:65], v[236:237], v[228:229] op_sel_hi:[0,1,1]
	v_pk_fma_f32 v[230:231], v[64:65], v[238:239], v[230:231] op_sel_hi:[0,1,1]
	s_waitcnt vmcnt(18)
	v_cvt_pk_f32_fp8_e32 v[232:233], v136
	v_cvt_pk_f32_fp8_sdwa v[234:235], v136 src0_sel:WORD_1
	v_pk_fma_f32 v[216:217], v[64:65], v[232:233], v[216:217] op_sel:[1,0,0]
	v_pk_fma_f32 v[218:219], v[64:65], v[234:235], v[218:219] op_sel:[1,0,0]
	v_cvt_pk_f32_fp8_e32 v[236:237], v137
	v_cvt_pk_f32_fp8_sdwa v[238:239], v137 src0_sel:WORD_1
	v_pk_fma_f32 v[220:221], v[64:65], v[236:237], v[220:221] op_sel:[1,0,0]
	v_pk_fma_f32 v[222:223], v[64:65], v[238:239], v[222:223] op_sel:[1,0,0]
	v_cvt_pk_f32_fp8_e32 v[232:233], v138
	v_cvt_pk_f32_fp8_sdwa v[234:235], v138 src0_sel:WORD_1
	v_pk_fma_f32 v[224:225], v[64:65], v[232:233], v[224:225] op_sel:[1,0,0]
	v_pk_fma_f32 v[226:227], v[64:65], v[234:235], v[226:227] op_sel:[1,0,0]
	v_cvt_pk_f32_fp8_e32 v[236:237], v139
	v_cvt_pk_f32_fp8_sdwa v[238:239], v139 src0_sel:WORD_1
	v_pk_fma_f32 v[228:229], v[64:65], v[236:237], v[228:229] op_sel:[1,0,0]
	v_pk_fma_f32 v[230:231], v[64:65], v[238:239], v[230:231] op_sel:[1,0,0]
	s_waitcnt vmcnt(17)
	v_cvt_pk_f32_fp8_e32 v[232:233], v140
	v_cvt_pk_f32_fp8_sdwa v[234:235], v140 src0_sel:WORD_1
	v_pk_fma_f32 v[216:217], v[66:67], v[232:233], v[216:217] op_sel_hi:[0,1,1]
	v_pk_fma_f32 v[218:219], v[66:67], v[234:235], v[218:219] op_sel_hi:[0,1,1]
	v_cvt_pk_f32_fp8_e32 v[236:237], v141
	v_cvt_pk_f32_fp8_sdwa v[238:239], v141 src0_sel:WORD_1
	v_pk_fma_f32 v[220:221], v[66:67], v[236:237], v[220:221] op_sel_hi:[0,1,1]
	v_pk_fma_f32 v[222:223], v[66:67], v[238:239], v[222:223] op_sel_hi:[0,1,1]
	v_cvt_pk_f32_fp8_e32 v[232:233], v142
	v_cvt_pk_f32_fp8_sdwa v[234:235], v142 src0_sel:WORD_1
	v_pk_fma_f32 v[224:225], v[66:67], v[232:233], v[224:225] op_sel_hi:[0,1,1]
	v_pk_fma_f32 v[226:227], v[66:67], v[234:235], v[226:227] op_sel_hi:[0,1,1]
	v_cvt_pk_f32_fp8_e32 v[236:237], v143
	v_cvt_pk_f32_fp8_sdwa v[238:239], v143 src0_sel:WORD_1
	v_pk_fma_f32 v[228:229], v[66:67], v[236:237], v[228:229] op_sel_hi:[0,1,1]
	v_pk_fma_f32 v[230:231], v[66:67], v[238:239], v[230:231] op_sel_hi:[0,1,1]
	s_waitcnt vmcnt(16)
; DI f2_t cvt8lo(unsigned w) { return __builtin_amdgcn_cvt_pk_f32_fp8(w, false); }
; DI f2_t cvt8hi(unsigned w) { return __builtin_amdgcn_cvt_pk_f32_fp8(w, true); }
; DI void wave_lds_sync() { asm volatile("s_waitcnt lgkmcnt(0)" ::: "memory"); __builtin_amdgcn_wave_barrier(); }
; DI void phase11(const Params& p, char* smem, int rep) {
;     ...
;       const int tok = __builtin_amdgcn_readfirstlane(c * 16 + w * 4 + t);
;       const int i0 = IDS[(size_t)tok * 128 + lane], i1 = IDS[(size_t)tok * 128 + 64 + lane];
;       const float a0 = ACT[(size_t)tok * 128 + lane], a1 = ACT[(size_t)tok * 128 + 64 + lane];
;       wave_lds_sync();
;       lw[(lane & 3) * 32 + (lane >> 2)] = i0; lw[(lane & 3) * 32 + 16 + (lane >> 2)] = i1;
;       lf[(lane & 3) * 32 + (lane >> 2)] = a0; lf[(lane & 3) * 32 + 16 + (lane >> 2)] = a1;
;       wave_lds_sync();
;     ...
; #pragma unroll
;         for (int k = 0; k < 16; ++k) {
;           const f2_t a2 = {aa[k], aa[k]};
; #pragma unroll
;           for (int d = 0; d < 4; ++d) { const unsigned ww = rows[k][d]; o[2 * d] += a2 * cvt8lo(ww); o[2 * d + 1] += a2 * cvt8hi(ww); }
	v_cvt_pk_f32_fp8_e32 v[232:233], v144
	v_cvt_pk_f32_fp8_sdwa v[234:235], v144 src0_sel:WORD_1
	v_pk_fma_f32 v[216:217], v[66:67], v[232:233], v[216:217] op_sel:[1,0,0]
	v_pk_fma_f32 v[218:219], v[66:67], v[234:235], v[218:219] op_sel:[1,0,0]
	v_cvt_pk_f32_fp8_e32 v[236:237], v145
	v_cvt_pk_f32_fp8_sdwa v[238:239], v145 src0_sel:WORD_1
	v_pk_fma_f32 v[220:221], v[66:67], v[236:237], v[220:221] op_sel:[1,0,0]
	v_pk_fma_f32 v[222:223], v[66:67], v[238:239], v[222:223] op_sel:[1,0,0]
	v_cvt_pk_f32_fp8_e32 v[232:233], v146
	v_cvt_pk_f32_fp8_sdwa v[234:235], v146 src0_sel:WORD_1
	v_pk_fma_f32 v[224:225], v[66:67], v[232:233], v[224:225] op_sel:[1,0,0]
	v_pk_fma_f32 v[226:227], v[66:67], v[234:235], v[226:227] op_sel:[1,0,0]
	v_cvt_pk_f32_fp8_e32 v[236:237], v147
	v_cvt_pk_f32_fp8_sdwa v[238:239], v147 src0_sel:WORD_1
	v_pk_fma_f32 v[228:229], v[66:67], v[236:237], v[228:229] op_sel:[1,0,0]
	v_pk_fma_f32 v[230:231], v[66:67], v[238:239], v[230:231] op_sel:[1,0,0]
	ds_write2_b32 v5, v10, v11 offset0:4 offset1:20
	ds_write2_b32 v5, v12, v13 offset0:132 offset1:148
	s_waitcnt lgkmcnt(0)
	ds_read_b128 v[20:23], v6 offset:16
	ds_read_b128 v[24:27], v6 offset:32
	ds_read_b128 v[28:31], v6 offset:48
	ds_read_b128 v[32:35], v6 offset:64
	ds_read_b128 v[36:39], v6 offset:80
	ds_read_b128 v[40:43], v6 offset:96
	ds_read_b128 v[44:47], v6 offset:112
	ds_read_b128 v[48:51], v6 offset:128
	s_waitcnt vmcnt(15)
	v_cvt_pk_f32_fp8_e32 v[232:233], v148
	v_cvt_pk_f32_fp8_sdwa v[234:235], v148 src0_sel:WORD_1
	v_pk_fma_f32 v[216:217], v[68:69], v[232:233], v[216:217] op_sel_hi:[0,1,1]
	v_pk_fma_f32 v[218:219], v[68:69], v[234:235], v[218:219] op_sel_hi:[0,1,1]
	v_cvt_pk_f32_fp8_e32 v[236:237], v149
	v_cvt_pk_f32_fp8_sdwa v[238:239], v149 src0_sel:WORD_1
	v_pk_fma_f32 v[220:221], v[68:69], v[236:237], v[220:221] op_sel_hi:[0,1,1]
	v_pk_fma_f32 v[222:223], v[68:69], v[238:239], v[222:223] op_sel_hi:[0,1,1]
	v_cvt_pk_f32_fp8_e32 v[232:233], v150
	v_cvt_pk_f32_fp8_sdwa v[234:235], v150 src0_sel:WORD_1
	v_pk_fma_f32 v[224:225], v[68:69], v[232:233], v[224:225] op_sel_hi:[0,1,1]
	v_pk_fma_f32 v[226:227], v[68:69], v[234:235], v[226:227] op_sel_hi:[0,1,1]
	v_cvt_pk_f32_fp8_e32 v[236:237], v151
	v_cvt_pk_f32_fp8_sdwa v[238:239], v151 src0_sel:WORD_1
	v_pk_fma_f32 v[228:229], v[68:69], v[236:237], v[228:229] op_sel_hi:[0,1,1]
	v_pk_fma_f32 v[230:231], v[68:69], v[238:239], v[230:231] op_sel_hi:[0,1,1]
	s_waitcnt vmcnt(14)
	v_cvt_pk_f32_fp8_e32 v[232:233], v152
	v_cvt_pk_f32_fp8_sdwa v[234:235], v152 src0_sel:WORD_1
	v_pk_fma_f32 v[216:217], v[68:69], v[232:233], v[216:217] op_sel:[1,0,0]
	v_pk_fma_f32 v[218:219], v[68:69], v[234:235], v[218:219] op_sel:[1,0,0]
	v_cvt_pk_f32_fp8_e32 v[236:237], v153
	v_cvt_pk_f32_fp8_sdwa v[238:239], v153 src0_sel:WORD_1
	v_pk_fma_f32 v[220:221], v[68:69], v[236:237], v[220:221] op_sel:[1,0,0]
	v_pk_fma_f32 v[222:223], v[68:69], v[238:239], v[222:223] op_sel:[1,0,0]
	v_cvt_pk_f32_fp8_e32 v[232:233], v154
	v_cvt_pk_f32_fp8_sdwa v[234:235], v154 src0_sel:WORD_1
	v_pk_fma_f32 v[224:225], v[68:69], v[232:233], v[224:225] op_sel:[1,0,0]
	v_pk_fma_f32 v[226:227], v[68:69], v[234:235], v[226:227] op_sel:[1,0,0]
	v_cvt_pk_f32_fp8_e32 v[236:237], v155
	v_cvt_pk_f32_fp8_sdwa v[238:239], v155 src0_sel:WORD_1
	v_pk_fma_f32 v[228:229], v[68:69], v[236:237], v[228:229] op_sel:[1,0,0]
	v_pk_fma_f32 v[230:231], v[68:69], v[238:239], v[230:231] op_sel:[1,0,0]
	s_waitcnt vmcnt(13)
	v_cvt_pk_f32_fp8_e32 v[232:233], v156
	v_cvt_pk_f32_fp8_sdwa v[234:235], v156 src0_sel:WORD_1
	v_pk_fma_f32 v[216:217], v[70:71], v[232:233], v[216:217] op_sel_hi:[0,1,1]
	v_pk_fma_f32 v[218:219], v[70:71], v[234:235], v[218:219] op_sel_hi:[0,1,1]
	v_cvt_pk_f32_fp8_e32 v[236:237], v157
	v_cvt_pk_f32_fp8_sdwa v[238:239], v157 src0_sel:WORD_1
	v_pk_fma_f32 v[220:221], v[70:71], v[236:237], v[220:221] op_sel_hi:[0,1,1]
	v_pk_fma_f32 v[222:223], v[70:71], v[238:239], v[222:223] op_sel_hi:[0,1,1]
	v_cvt_pk_f32_fp8_e32 v[232:233], v158
	v_cvt_pk_f32_fp8_sdwa v[234:235], v158 src0_sel:WORD_1
	v_pk_fma_f32 v[224:225], v[70:71], v[232:233], v[224:225] op_sel_hi:[0,1,1]
	v_pk_fma_f32 v[226:227], v[70:71], v[234:235], v[226:227] op_sel_hi:[0,1,1]
	v_cvt_pk_f32_fp8_e32 v[236:237], v159
	v_cvt_pk_f32_fp8_sdwa v[238:239], v159 src0_sel:WORD_1
	v_pk_fma_f32 v[228:229], v[70:71], v[236:237], v[228:229] op_sel_hi:[0,1,1]
	v_pk_fma_f32 v[230:231], v[70:71], v[238:239], v[230:231] op_sel_hi:[0,1,1]
	s_waitcnt vmcnt(12)
	v_cvt_pk_f32_fp8_e32 v[232:233], v160
	v_cvt_pk_f32_fp8_sdwa v[234:235], v160 src0_sel:WORD_1
	v_pk_fma_f32 v[216:217], v[70:71], v[232:233], v[216:217] op_sel:[1,0,0]
	v_pk_fma_f32 v[218:219], v[70:71], v[234:235], v[218:219] op_sel:[1,0,0]
	v_cvt_pk_f32_fp8_e32 v[236:237], v161
	v_cvt_pk_f32_fp8_sdwa v[238:239], v161 src0_sel:WORD_1
	v_pk_fma_f32 v[220:221], v[70:71], v[236:237], v[220:221] op_sel:[1,0,0]
	v_pk_fma_f32 v[222:223], v[70:71], v[238:239], v[222:223] op_sel:[1,0,0]
	v_cvt_pk_f32_fp8_e32 v[232:233], v162
	v_cvt_pk_f32_fp8_sdwa v[234:235], v162 src0_sel:WORD_1
	v_pk_fma_f32 v[224:225], v[70:71], v[232:233], v[224:225] op_sel:[1,0,0]
	v_pk_fma_f32 v[226:227], v[70:71], v[234:235], v[226:227] op_sel:[1,0,0]
	v_cvt_pk_f32_fp8_e32 v[236:237], v163
	v_cvt_pk_f32_fp8_sdwa v[238:239], v163 src0_sel:WORD_1
	v_pk_fma_f32 v[228:229], v[70:71], v[236:237], v[228:229] op_sel:[1,0,0]
	v_pk_fma_f32 v[230:231], v[70:71], v[238:239], v[230:231] op_sel:[1,0,0]
	s_waitcnt vmcnt(11)
; DI f2_t cvt8lo(unsigned w) { return __builtin_amdgcn_cvt_pk_f32_fp8(w, false); }
; DI f2_t cvt8hi(unsigned w) { return __builtin_amdgcn_cvt_pk_f32_fp8(w, true); }
; DI void phase11(const Params& p, char* smem, int rep) {
;     ...
; #pragma unroll
;         for (int k = 0; k < 16; ++k) {
;           const f2_t a2 = {aa[k], aa[k]};
; #pragma unroll
;           for (int d = 0; d < 4; ++d) { const unsigned ww = rows[k][d]; o[2 * d] += a2 * cvt8lo(ww); o[2 * d + 1] += a2 * cvt8hi(ww); }
	v_cvt_pk_f32_fp8_e32 v[232:233], v164
	v_cvt_pk_f32_fp8_sdwa v[234:235], v164 src0_sel:WORD_1
	v_pk_fma_f32 v[216:217], v[72:73], v[232:233], v[216:217] op_sel_hi:[0,1,1]
	v_pk_fma_f32 v[218:219], v[72:73], v[234:235], v[218:219] op_sel_hi:[0,1,1]
	v_cvt_pk_f32_fp8_e32 v[236:237], v165
	v_cvt_pk_f32_fp8_sdwa v[238:239], v165 src0_sel:WORD_1
	v_pk_fma_f32 v[220:221], v[72:73], v[236:237], v[220:221] op_sel_hi:[0,1,1]
	v_pk_fma_f32 v[222:223], v[72:73], v[238:239], v[222:223] op_sel_hi:[0,1,1]
	v_cvt_pk_f32_fp8_e32 v[232:233], v166
	v_cvt_pk_f32_fp8_sdwa v[234:235], v166 src0_sel:WORD_1
	v_pk_fma_f32 v[224:225], v[72:73], v[232:233], v[224:225] op_sel_hi:[0,1,1]
	v_pk_fma_f32 v[226:227], v[72:73], v[234:235], v[226:227] op_sel_hi:[0,1,1]
	v_cvt_pk_f32_fp8_e32 v[236:237], v167
	v_cvt_pk_f32_fp8_sdwa v[238:239], v167 src0_sel:WORD_1
	v_pk_fma_f32 v[228:229], v[72:73], v[236:237], v[228:229] op_sel_hi:[0,1,1]
	v_pk_fma_f32 v[230:231], v[72:73], v[238:239], v[230:231] op_sel_hi:[0,1,1]
	s_waitcnt vmcnt(10)
	v_cvt_pk_f32_fp8_e32 v[232:233], v168
	v_cvt_pk_f32_fp8_sdwa v[234:235], v168 src0_sel:WORD_1
	v_pk_fma_f32 v[216:217], v[72:73], v[232:233], v[216:217] op_sel:[1,0,0]
	v_pk_fma_f32 v[218:219], v[72:73], v[234:235], v[218:219] op_sel:[1,0,0]
	v_cvt_pk_f32_fp8_e32 v[236:237], v169
	v_cvt_pk_f32_fp8_sdwa v[238:239], v169 src0_sel:WORD_1
	v_pk_fma_f32 v[220:221], v[72:73], v[236:237], v[220:221] op_sel:[1,0,0]
	v_pk_fma_f32 v[222:223], v[72:73], v[238:239], v[222:223] op_sel:[1,0,0]
	v_cvt_pk_f32_fp8_e32 v[232:233], v170
	v_cvt_pk_f32_fp8_sdwa v[234:235], v170 src0_sel:WORD_1
	v_pk_fma_f32 v[224:225], v[72:73], v[232:233], v[224:225] op_sel:[1,0,0]
	v_pk_fma_f32 v[226:227], v[72:73], v[234:235], v[226:227] op_sel:[1,0,0]
	v_cvt_pk_f32_fp8_e32 v[236:237], v171
	v_cvt_pk_f32_fp8_sdwa v[238:239], v171 src0_sel:WORD_1
	v_pk_fma_f32 v[228:229], v[72:73], v[236:237], v[228:229] op_sel:[1,0,0]
	v_pk_fma_f32 v[230:231], v[72:73], v[238:239], v[230:231] op_sel:[1,0,0]
	s_waitcnt vmcnt(9)
	v_cvt_pk_f32_fp8_e32 v[232:233], v172
	v_cvt_pk_f32_fp8_sdwa v[234:235], v172 src0_sel:WORD_1
	v_pk_fma_f32 v[216:217], v[74:75], v[232:233], v[216:217] op_sel_hi:[0,1,1]
	v_pk_fma_f32 v[218:219], v[74:75], v[234:235], v[218:219] op_sel_hi:[0,1,1]
	v_cvt_pk_f32_fp8_e32 v[236:237], v173
	v_cvt_pk_f32_fp8_sdwa v[238:239], v173 src0_sel:WORD_1
	v_pk_fma_f32 v[220:221], v[74:75], v[236:237], v[220:221] op_sel_hi:[0,1,1]
	v_pk_fma_f32 v[222:223], v[74:75], v[238:239], v[222:223] op_sel_hi:[0,1,1]
	v_cvt_pk_f32_fp8_e32 v[232:233], v174
	v_cvt_pk_f32_fp8_sdwa v[234:235], v174 src0_sel:WORD_1
	v_pk_fma_f32 v[224:225], v[74:75], v[232:233], v[224:225] op_sel_hi:[0,1,1]
	v_pk_fma_f32 v[226:227], v[74:75], v[234:235], v[226:227] op_sel_hi:[0,1,1]
	v_cvt_pk_f32_fp8_e32 v[236:237], v175
	v_cvt_pk_f32_fp8_sdwa v[238:239], v175 src0_sel:WORD_1
	v_pk_fma_f32 v[228:229], v[74:75], v[236:237], v[228:229] op_sel_hi:[0,1,1]
	v_pk_fma_f32 v[230:231], v[74:75], v[238:239], v[230:231] op_sel_hi:[0,1,1]
	s_waitcnt vmcnt(8)
	v_cvt_pk_f32_fp8_e32 v[232:233], v176
	v_cvt_pk_f32_fp8_sdwa v[234:235], v176 src0_sel:WORD_1
	v_pk_fma_f32 v[216:217], v[74:75], v[232:233], v[216:217] op_sel:[1,0,0]
	v_pk_fma_f32 v[218:219], v[74:75], v[234:235], v[218:219] op_sel:[1,0,0]
	v_cvt_pk_f32_fp8_e32 v[236:237], v177
	v_cvt_pk_f32_fp8_sdwa v[238:239], v177 src0_sel:WORD_1
	v_pk_fma_f32 v[220:221], v[74:75], v[236:237], v[220:221] op_sel:[1,0,0]
	v_pk_fma_f32 v[222:223], v[74:75], v[238:239], v[222:223] op_sel:[1,0,0]
	v_cvt_pk_f32_fp8_e32 v[232:233], v178
	v_cvt_pk_f32_fp8_sdwa v[234:235], v178 src0_sel:WORD_1
	v_pk_fma_f32 v[224:225], v[74:75], v[232:233], v[224:225] op_sel:[1,0,0]
	v_pk_fma_f32 v[226:227], v[74:75], v[234:235], v[226:227] op_sel:[1,0,0]
	v_cvt_pk_f32_fp8_e32 v[236:237], v179
	v_cvt_pk_f32_fp8_sdwa v[238:239], v179 src0_sel:WORD_1
	v_pk_fma_f32 v[228:229], v[74:75], v[236:237], v[228:229] op_sel:[1,0,0]
	v_pk_fma_f32 v[230:231], v[74:75], v[238:239], v[230:231] op_sel:[1,0,0]
	s_waitcnt vmcnt(7)
	v_cvt_pk_f32_fp8_e32 v[232:233], v180
	v_cvt_pk_f32_fp8_sdwa v[234:235], v180 src0_sel:WORD_1
	v_pk_fma_f32 v[216:217], v[76:77], v[232:233], v[216:217] op_sel_hi:[0,1,1]
	v_pk_fma_f32 v[218:219], v[76:77], v[234:235], v[218:219] op_sel_hi:[0,1,1]
	v_cvt_pk_f32_fp8_e32 v[236:237], v181
	v_cvt_pk_f32_fp8_sdwa v[238:239], v181 src0_sel:WORD_1
	v_pk_fma_f32 v[220:221], v[76:77], v[236:237], v[220:221] op_sel_hi:[0,1,1]
	v_pk_fma_f32 v[222:223], v[76:77], v[238:239], v[222:223] op_sel_hi:[0,1,1]
	v_cvt_pk_f32_fp8_e32 v[232:233], v182
	v_cvt_pk_f32_fp8_sdwa v[234:235], v182 src0_sel:WORD_1
	v_pk_fma_f32 v[224:225], v[76:77], v[232:233], v[224:225] op_sel_hi:[0,1,1]
	v_pk_fma_f32 v[226:227], v[76:77], v[234:235], v[226:227] op_sel_hi:[0,1,1]
	v_cvt_pk_f32_fp8_e32 v[236:237], v183
	v_cvt_pk_f32_fp8_sdwa v[238:239], v183 src0_sel:WORD_1
	v_pk_fma_f32 v[228:229], v[76:77], v[236:237], v[228:229] op_sel_hi:[0,1,1]
	v_pk_fma_f32 v[230:231], v[76:77], v[238:239], v[230:231] op_sel_hi:[0,1,1]
	s_waitcnt vmcnt(6)
	v_cvt_pk_f32_fp8_e32 v[232:233], v184
	v_cvt_pk_f32_fp8_sdwa v[234:235], v184 src0_sel:WORD_1
	v_pk_fma_f32 v[216:217], v[76:77], v[232:233], v[216:217] op_sel:[1,0,0]
	v_pk_fma_f32 v[218:219], v[76:77], v[234:235], v[218:219] op_sel:[1,0,0]
	v_cvt_pk_f32_fp8_e32 v[236:237], v185
	v_cvt_pk_f32_fp8_sdwa v[238:239], v185 src0_sel:WORD_1
	v_pk_fma_f32 v[220:221], v[76:77], v[236:237], v[220:221] op_sel:[1,0,0]
	v_pk_fma_f32 v[222:223], v[76:77], v[238:239], v[222:223] op_sel:[1,0,0]
	v_cvt_pk_f32_fp8_e32 v[232:233], v186
	v_cvt_pk_f32_fp8_sdwa v[234:235], v186 src0_sel:WORD_1
	v_pk_fma_f32 v[224:225], v[76:77], v[232:233], v[224:225] op_sel:[1,0,0]
	v_pk_fma_f32 v[226:227], v[76:77], v[234:235], v[226:227] op_sel:[1,0,0]
	v_cvt_pk_f32_fp8_e32 v[236:237], v187
	v_cvt_pk_f32_fp8_sdwa v[238:239], v187 src0_sel:WORD_1
	v_pk_fma_f32 v[228:229], v[76:77], v[236:237], v[228:229] op_sel:[1,0,0]
	v_pk_fma_f32 v[230:231], v[76:77], v[238:239], v[230:231] op_sel:[1,0,0]
	s_waitcnt vmcnt(5)
; DI f2_t cvt8lo(unsigned w) { return __builtin_amdgcn_cvt_pk_f32_fp8(w, false); }
; DI f2_t cvt8hi(unsigned w) { return __builtin_amdgcn_cvt_pk_f32_fp8(w, true); }
; DI void phase11(const Params& p, char* smem, int rep) {
;     ...
; #pragma unroll
;         for (int k = 0; k < 16; ++k) {
;           const f2_t a2 = {aa[k], aa[k]};
; #pragma unroll
;           for (int d = 0; d < 4; ++d) { const unsigned ww = rows[k][d]; o[2 * d] += a2 * cvt8lo(ww); o[2 * d + 1] += a2 * cvt8hi(ww); }
	v_cvt_pk_f32_fp8_e32 v[232:233], v190
	v_cvt_pk_f32_fp8_sdwa v[234:235], v190 src0_sel:WORD_1
	v_pk_fma_f32 v[216:217], v[78:79], v[232:233], v[216:217] op_sel_hi:[0,1,1]
	v_pk_fma_f32 v[218:219], v[78:79], v[234:235], v[218:219] op_sel_hi:[0,1,1]
	v_cvt_pk_f32_fp8_e32 v[236:237], v191
	v_cvt_pk_f32_fp8_sdwa v[238:239], v191 src0_sel:WORD_1
	v_pk_fma_f32 v[220:221], v[78:79], v[236:237], v[220:221] op_sel_hi:[0,1,1]
	v_pk_fma_f32 v[222:223], v[78:79], v[238:239], v[222:223] op_sel_hi:[0,1,1]
	v_cvt_pk_f32_fp8_e32 v[232:233], v192
	v_cvt_pk_f32_fp8_sdwa v[234:235], v192 src0_sel:WORD_1
	v_pk_fma_f32 v[224:225], v[78:79], v[232:233], v[224:225] op_sel_hi:[0,1,1]
	v_pk_fma_f32 v[226:227], v[78:79], v[234:235], v[226:227] op_sel_hi:[0,1,1]
	v_cvt_pk_f32_fp8_e32 v[236:237], v193
	v_cvt_pk_f32_fp8_sdwa v[238:239], v193 src0_sel:WORD_1
	v_pk_fma_f32 v[228:229], v[78:79], v[236:237], v[228:229] op_sel_hi:[0,1,1]
	v_pk_fma_f32 v[230:231], v[78:79], v[238:239], v[230:231] op_sel_hi:[0,1,1]
	s_waitcnt vmcnt(4)
	v_cvt_pk_f32_fp8_e32 v[232:233], v194
	v_cvt_pk_f32_fp8_sdwa v[234:235], v194 src0_sel:WORD_1
	v_pk_fma_f32 v[216:217], v[78:79], v[232:233], v[216:217] op_sel:[1,0,0]
	v_pk_fma_f32 v[218:219], v[78:79], v[234:235], v[218:219] op_sel:[1,0,0]
	v_cvt_pk_f32_fp8_e32 v[236:237], v195
	v_cvt_pk_f32_fp8_sdwa v[238:239], v195 src0_sel:WORD_1
	v_pk_fma_f32 v[220:221], v[78:79], v[236:237], v[220:221] op_sel:[1,0,0]
	v_pk_fma_f32 v[222:223], v[78:79], v[238:239], v[222:223] op_sel:[1,0,0]
	v_cvt_pk_f32_fp8_e32 v[232:233], v196
	v_cvt_pk_f32_fp8_sdwa v[234:235], v196 src0_sel:WORD_1
	v_pk_fma_f32 v[224:225], v[78:79], v[232:233], v[224:225] op_sel:[1,0,0]
	v_pk_fma_f32 v[226:227], v[78:79], v[234:235], v[226:227] op_sel:[1,0,0]
	v_cvt_pk_f32_fp8_e32 v[236:237], v197
	v_cvt_pk_f32_fp8_sdwa v[238:239], v197 src0_sel:WORD_1
	v_pk_fma_f32 v[228:229], v[78:79], v[236:237], v[228:229] op_sel:[1,0,0]
	v_pk_fma_f32 v[230:231], v[78:79], v[238:239], v[230:231] op_sel:[1,0,0]
	s_waitcnt vmcnt(3)
	v_cvt_pk_f32_fp8_e32 v[232:233], v198
	v_cvt_pk_f32_fp8_sdwa v[234:235], v198 src0_sel:WORD_1
	v_pk_fma_f32 v[216:217], v[80:81], v[232:233], v[216:217] op_sel_hi:[0,1,1]
	v_pk_fma_f32 v[218:219], v[80:81], v[234:235], v[218:219] op_sel_hi:[0,1,1]
	v_cvt_pk_f32_fp8_e32 v[236:237], v199
	v_cvt_pk_f32_fp8_sdwa v[238:239], v199 src0_sel:WORD_1
	v_pk_fma_f32 v[220:221], v[80:81], v[236:237], v[220:221] op_sel_hi:[0,1,1]
	v_pk_fma_f32 v[222:223], v[80:81], v[238:239], v[222:223] op_sel_hi:[0,1,1]
	v_cvt_pk_f32_fp8_e32 v[232:233], v200
	v_cvt_pk_f32_fp8_sdwa v[234:235], v200 src0_sel:WORD_1
	v_pk_fma_f32 v[224:225], v[80:81], v[232:233], v[224:225] op_sel_hi:[0,1,1]
	v_pk_fma_f32 v[226:227], v[80:81], v[234:235], v[226:227] op_sel_hi:[0,1,1]
	v_cvt_pk_f32_fp8_e32 v[236:237], v201
	v_cvt_pk_f32_fp8_sdwa v[238:239], v201 src0_sel:WORD_1
	v_pk_fma_f32 v[228:229], v[80:81], v[236:237], v[228:229] op_sel_hi:[0,1,1]
	v_pk_fma_f32 v[230:231], v[80:81], v[238:239], v[230:231] op_sel_hi:[0,1,1]
	s_waitcnt vmcnt(2)
	v_cvt_pk_f32_fp8_e32 v[232:233], v202
	v_cvt_pk_f32_fp8_sdwa v[234:235], v202 src0_sel:WORD_1
	v_pk_fma_f32 v[216:217], v[80:81], v[232:233], v[216:217] op_sel:[1,0,0]
	v_pk_fma_f32 v[218:219], v[80:81], v[234:235], v[218:219] op_sel:[1,0,0]
	v_cvt_pk_f32_fp8_e32 v[236:237], v203
	v_cvt_pk_f32_fp8_sdwa v[238:239], v203 src0_sel:WORD_1
	v_pk_fma_f32 v[220:221], v[80:81], v[236:237], v[220:221] op_sel:[1,0,0]
	v_pk_fma_f32 v[222:223], v[80:81], v[238:239], v[222:223] op_sel:[1,0,0]
	v_cvt_pk_f32_fp8_e32 v[232:233], v204
	v_cvt_pk_f32_fp8_sdwa v[234:235], v204 src0_sel:WORD_1
	v_pk_fma_f32 v[224:225], v[80:81], v[232:233], v[224:225] op_sel:[1,0,0]
	v_pk_fma_f32 v[226:227], v[80:81], v[234:235], v[226:227] op_sel:[1,0,0]
	v_cvt_pk_f32_fp8_e32 v[236:237], v205
	v_cvt_pk_f32_fp8_sdwa v[238:239], v205 src0_sel:WORD_1
	v_pk_fma_f32 v[228:229], v[80:81], v[236:237], v[228:229] op_sel:[1,0,0]
	v_pk_fma_f32 v[230:231], v[80:81], v[238:239], v[230:231] op_sel:[1,0,0]
	s_waitcnt vmcnt(1)
	v_cvt_pk_f32_fp8_e32 v[232:233], v206
	v_cvt_pk_f32_fp8_sdwa v[234:235], v206 src0_sel:WORD_1
	v_pk_fma_f32 v[216:217], v[82:83], v[232:233], v[216:217] op_sel_hi:[0,1,1]
	v_pk_fma_f32 v[218:219], v[82:83], v[234:235], v[218:219] op_sel_hi:[0,1,1]
	v_cvt_pk_f32_fp8_e32 v[236:237], v207
	v_cvt_pk_f32_fp8_sdwa v[238:239], v207 src0_sel:WORD_1
	v_pk_fma_f32 v[220:221], v[82:83], v[236:237], v[220:221] op_sel_hi:[0,1,1]
	v_pk_fma_f32 v[222:223], v[82:83], v[238:239], v[222:223] op_sel_hi:[0,1,1]
	v_cvt_pk_f32_fp8_e32 v[232:233], v208
	v_cvt_pk_f32_fp8_sdwa v[234:235], v208 src0_sel:WORD_1
	v_pk_fma_f32 v[224:225], v[82:83], v[232:233], v[224:225] op_sel_hi:[0,1,1]
	v_pk_fma_f32 v[226:227], v[82:83], v[234:235], v[226:227] op_sel_hi:[0,1,1]
	v_cvt_pk_f32_fp8_e32 v[236:237], v209
	v_cvt_pk_f32_fp8_sdwa v[238:239], v209 src0_sel:WORD_1
	v_pk_fma_f32 v[228:229], v[82:83], v[236:237], v[228:229] op_sel_hi:[0,1,1]
	v_pk_fma_f32 v[230:231], v[82:83], v[238:239], v[230:231] op_sel_hi:[0,1,1]
	s_waitcnt vmcnt(0)
; DI f2_t cvt8lo(unsigned w) { return __builtin_amdgcn_cvt_pk_f32_fp8(w, false); }
; DI void phase11(const Params& p, char* smem, int rep) {
;     ...
;     for (int t = 0; t < 4; ++t) {
;       const int tok = __builtin_amdgcn_readfirstlane(c * 16 + w * 4 + t);
;       const int i0 = IDS[(size_t)tok * 128 + lane], i1 = IDS[(size_t)tok * 128 + 64 + lane];
;       const float a0 = ACT[(size_t)tok * 128 + lane], a1 = ACT[(size_t)tok * 128 + 64 + lane];
;       wave_lds_sync();
;       lw[(lane & 3) * 32 + (lane >> 2)] = i0; lw[(lane & 3) * 32 + 16 + (lane >> 2)] = i1;
;       lf[(lane & 3) * 32 + (lane >> 2)] = a0; lf[(lane & 3) * 32 + 16 + (lane >> 2)] = a1;
;       wave_lds_sync();
;       f2_t o[8];
; #pragma unroll
;       for (int i = 0; i < 8; ++i) o[i] = f2_t{0.f, 0.f};
;       const unsigned char* vb = V8 + s * 256 + l15 * 16;
; #pragma unroll
;       for (int batch = 0; batch < 2; ++batch) {
;         int ida[16]; float aa[16];
; #pragma unroll
;         for (int q = 0; q < 4; ++q) {
;           const int4 v = *(const int4*)(lw + g * 32 + batch * 16 + q * 4); ida[q * 4] = v.x; ida[q * 4 + 1] = v.y; ida[q * 4 + 2] = v.z; ida[q * 4 + 3] = v.w;
;           const float4 f = *(const float4*)(lf + g * 32 + batch * 16 + q * 4); aa[q * 4] = f.x; aa[q * 4 + 1] = f.y; aa[q * 4 + 2] = f.z; aa[q * 4 + 3] = f.w;
;         }
;         u32x4 rows[16];
; #pragma unroll
;         for (int k = 0; k < 16; ++k) rows[k] = *(const u32x4*)(vb + (size_t)ida[k] * 2048);
; #pragma unroll
;         for (int k = 0; k < 16; ++k) {
;           const f2_t a2 = {aa[k], aa[k]};
; #pragma unroll
;           for (int d = 0; d < 4; ++d) { const unsigned ww = rows[k][d]; o[2 * d] += a2 * cvt8lo(ww); o[2 * d + 1] += a2 * cvt8hi(ww); }
;         }
;       }
;       float ov[16];
; #pragma unroll
;       for (int d = 0; d < 4; ++d) { ov[4 * d] = o[2 * d].x; ov[4 * d + 1] = o[2 * d].y; ov[4 * d + 2] = o[2 * d + 1].x; ov[4 * d + 3] = o[2 * d + 1].y; }
;       float q8[8], q4[4];
; #pragma unroll
;       for (int k = 0; k < 8; ++k) q8[k] = (b5 ? ov[8 + k] : ov[k]) + __shfl_xor(b5 ? ov[k] : ov[8 + k], 32);
; #pragma unroll
;       for (int k = 0; k < 4; ++k) q4[k] = (b4 ? q8[4 + k] : q8[k]) + __shfl_xor(b4 ? q8[k] : q8[4 + k], 16);
;       *(uint2*)(OUTP + (size_t)tok * D_ + s * 256 + l15 * 16 + 8 * b5 + 4 * b4) = make_uint2(pk2(q4[0], q4[1]), pk2(q4[2], q4[3]));
	v_cvt_pk_f32_fp8_e32 v[232:233], v210
	v_cvt_pk_f32_fp8_sdwa v[234:235], v210 src0_sel:WORD_1
	v_pk_fma_f32 v[216:217], v[82:83], v[232:233], v[216:217] op_sel:[1,0,0]
	v_pk_fma_f32 v[218:219], v[82:83], v[234:235], v[218:219] op_sel:[1,0,0]
	v_cvt_pk_f32_fp8_e32 v[236:237], v211
	v_cvt_pk_f32_fp8_sdwa v[238:239], v211 src0_sel:WORD_1
	v_pk_fma_f32 v[220:221], v[82:83], v[236:237], v[220:221] op_sel:[1,0,0]
	v_pk_fma_f32 v[222:223], v[82:83], v[238:239], v[222:223] op_sel:[1,0,0]
	v_cvt_pk_f32_fp8_e32 v[232:233], v212
	v_cvt_pk_f32_fp8_sdwa v[234:235], v212 src0_sel:WORD_1
	v_pk_fma_f32 v[224:225], v[82:83], v[232:233], v[224:225] op_sel:[1,0,0]
	v_pk_fma_f32 v[226:227], v[82:83], v[234:235], v[226:227] op_sel:[1,0,0]
	v_cvt_pk_f32_fp8_e32 v[236:237], v213
	v_cvt_pk_f32_fp8_sdwa v[238:239], v213 src0_sel:WORD_1
	v_pk_fma_f32 v[228:229], v[82:83], v[236:237], v[228:229] op_sel:[1,0,0]
	v_pk_fma_f32 v[230:231], v[82:83], v[238:239], v[230:231] op_sel:[1,0,0]
	ds_read_b128 v[52:55], v6 offset:528
	ds_read_b128 v[56:59], v6 offset:544
	ds_read_b128 v[60:63], v6 offset:560
	ds_read_b128 v[64:67], v6 offset:576
	ds_read_b128 v[68:71], v6 offset:592
	ds_read_b128 v[72:75], v6 offset:608
	ds_read_b128 v[76:79], v6 offset:624
	ds_read_b128 v[80:83], v6 offset:640
	s_add_u32 s56, s14, s46
	s_addc_u32 s57, s15, 0
	s_nop 0
	v_permlane32_swap_b32_e32 v216, v224
	v_permlane32_swap_b32_e32 v217, v225
	v_permlane32_swap_b32_e32 v218, v226
	v_permlane32_swap_b32_e32 v219, v227
	v_permlane32_swap_b32_e32 v220, v228
	v_permlane32_swap_b32_e32 v221, v229
	v_permlane32_swap_b32_e32 v222, v230
	v_permlane32_swap_b32_e32 v223, v231
	v_pk_add_f32 v[216:217], v[216:217], v[224:225]
	v_pk_add_f32 v[218:219], v[218:219], v[226:227]
	v_pk_add_f32 v[220:221], v[220:221], v[228:229]
	v_pk_add_f32 v[222:223], v[222:223], v[230:231]
	s_nop 1
	v_permlane16_swap_b32_e32 v216, v220
	v_permlane16_swap_b32_e32 v217, v221
	v_permlane16_swap_b32_e32 v218, v222
	v_permlane16_swap_b32_e32 v219, v223
	v_pk_add_f32 v[216:217], v[216:217], v[220:221]
	v_pk_add_f32 v[218:219], v[218:219], v[222:223]
	v_cvt_pk_bf16_f32 v232, v216, v217
	v_cvt_pk_bf16_f32 v233, v218, v219
	global_store_dwordx2 v4, v[232:233], s[56:57]
	s_add_i32 s54, s34, 3
	s_lshl_b32 s46, s54, 12
	s_add_i32 s46, s46, s24
	s_add_i32 s55, s34, 4
	s_add_i32 s51, s48, 1
	s_cmp_lt_u32 s51, s49
	s_cselect_b32 s55, s55, 8192
	s_cmp_lt_u32 s55, 8192
	s_cselect_b32 s55, s55, 0
	s_lshl_b32 s47, s55, 9
	s_add_u32 s42, s6, s47
	s_addc_u32 s43, s7, 0
	s_add_u32 s44, s8, s47
	s_addc_u32 s45, s9, 0
	global_load_dword v10, v3, s[42:43]
	global_load_dword v11, v3, s[42:43] offset:256
	global_load_dword v12, v3, s[44:45]
	global_load_dword v13, v3, s[44:45] offset:256
	s_waitcnt lgkmcnt(0)
	v_lshl_add_u32 v20, v20, 11, v2
	v_lshl_add_u32 v21, v21, 11, v2
	v_lshl_add_u32 v22, v22, 11, v2
	v_lshl_add_u32 v23, v23, 11, v2
	v_lshl_add_u32 v24, v24, 11, v2
	v_lshl_add_u32 v25, v25, 11, v2
	v_lshl_add_u32 v26, v26, 11, v2
	v_lshl_add_u32 v27, v27, 11, v2
	v_lshl_add_u32 v28, v28, 11, v2
	v_lshl_add_u32 v29, v29, 11, v2
	v_lshl_add_u32 v30, v30, 11, v2
	v_lshl_add_u32 v31, v31, 11, v2
	v_lshl_add_u32 v32, v32, 11, v2
	v_lshl_add_u32 v33, v33, 11, v2
	v_lshl_add_u32 v34, v34, 11, v2
	v_lshl_add_u32 v35, v35, 11, v2
	v_lshl_add_u32 v36, v36, 11, v2
	v_lshl_add_u32 v37, v37, 11, v2
	v_lshl_add_u32 v38, v38, 11, v2
	v_lshl_add_u32 v39, v39, 11, v2
	v_lshl_add_u32 v40, v40, 11, v2
	v_lshl_add_u32 v41, v41, 11, v2
	v_lshl_add_u32 v42, v42, 11, v2
	v_lshl_add_u32 v43, v43, 11, v2
	v_lshl_add_u32 v44, v44, 11, v2
	v_lshl_add_u32 v45, v45, 11, v2
	v_lshl_add_u32 v46, v46, 11, v2
	v_lshl_add_u32 v47, v47, 11, v2
	v_lshl_add_u32 v48, v48, 11, v2
	v_lshl_add_u32 v49, v49, 11, v2
	v_lshl_add_u32 v50, v50, 11, v2
	v_lshl_add_u32 v51, v51, 11, v2
	global_load_dwordx4 v[84:87], v20, s[20:21]
	global_load_dwordx4 v[88:91], v21, s[20:21]
	global_load_dwordx4 v[92:95], v22, s[20:21]
	global_load_dwordx4 v[96:99], v23, s[20:21]
	global_load_dwordx4 v[100:103], v24, s[20:21]
	global_load_dwordx4 v[104:107], v25, s[20:21]
	global_load_dwordx4 v[108:111], v26, s[20:21]
	global_load_dwordx4 v[112:115], v27, s[20:21]
	global_load_dwordx4 v[116:119], v28, s[20:21]
	global_load_dwordx4 v[120:123], v29, s[20:21]
	global_load_dwordx4 v[124:127], v30, s[20:21]
	global_load_dwordx4 v[128:131], v31, s[20:21]
	global_load_dwordx4 v[132:135], v32, s[20:21]
	global_load_dwordx4 v[136:139], v33, s[20:21]
	global_load_dwordx4 v[140:143], v34, s[20:21]
	global_load_dwordx4 v[144:147], v35, s[20:21]
	global_load_dwordx4 v[148:151], v36, s[20:21]
	global_load_dwordx4 v[152:155], v37, s[20:21]
	global_load_dwordx4 v[156:159], v38, s[20:21]
	global_load_dwordx4 v[160:163], v39, s[20:21]
	global_load_dwordx4 v[164:167], v40, s[20:21]
	global_load_dwordx4 v[168:171], v41, s[20:21]
	global_load_dwordx4 v[172:175], v42, s[20:21]
	global_load_dwordx4 v[176:179], v43, s[20:21]
	global_load_dwordx4 v[180:183], v44, s[20:21]
	global_load_dwordx4 v[184:187], v45, s[20:21]
	global_load_dwordx4 v[190:193], v46, s[20:21]
	global_load_dwordx4 v[194:197], v47, s[20:21]
	global_load_dwordx4 v[198:201], v48, s[20:21]
	global_load_dwordx4 v[202:205], v49, s[20:21]
	global_load_dwordx4 v[206:209], v50, s[20:21]
	global_load_dwordx4 v[210:213], v51, s[20:21]
	s_waitcnt vmcnt(31)
; DI f2_t cvt8lo(unsigned w) { return __builtin_amdgcn_cvt_pk_f32_fp8(w, false); }
; DI f2_t cvt8hi(unsigned w) { return __builtin_amdgcn_cvt_pk_f32_fp8(w, true); }
; DI void phase11(const Params& p, char* smem, int rep) {
;     ...
;         u32x4 rows[16];
; #pragma unroll
;         for (int k = 0; k < 16; ++k) rows[k] = *(const u32x4*)(vb + (size_t)ida[k] * 2048);
; #pragma unroll
;         for (int k = 0; k < 16; ++k) {
;           const f2_t a2 = {aa[k], aa[k]};
; #pragma unroll
;           for (int d = 0; d < 4; ++d) { const unsigned ww = rows[k][d]; o[2 * d] += a2 * cvt8lo(ww); o[2 * d + 1] += a2 * cvt8hi(ww); }
;         }
	v_cvt_pk_f32_fp8_e32 v[232:233], v84
	v_cvt_pk_f32_fp8_sdwa v[234:235], v84 src0_sel:WORD_1
	v_pk_fma_f32 v[216:217], v[52:53], v[232:233], 0 op_sel_hi:[0,1,0]
	v_pk_fma_f32 v[218:219], v[52:53], v[234:235], 0 op_sel_hi:[0,1,0]
	v_cvt_pk_f32_fp8_e32 v[236:237], v85
	v_cvt_pk_f32_fp8_sdwa v[238:239], v85 src0_sel:WORD_1
	v_pk_fma_f32 v[220:221], v[52:53], v[236:237], 0 op_sel_hi:[0,1,0]
	v_pk_fma_f32 v[222:223], v[52:53], v[238:239], 0 op_sel_hi:[0,1,0]
	v_cvt_pk_f32_fp8_e32 v[232:233], v86
	v_cvt_pk_f32_fp8_sdwa v[234:235], v86 src0_sel:WORD_1
	v_pk_fma_f32 v[224:225], v[52:53], v[232:233], 0 op_sel_hi:[0,1,0]
	v_pk_fma_f32 v[226:227], v[52:53], v[234:235], 0 op_sel_hi:[0,1,0]
	v_cvt_pk_f32_fp8_e32 v[236:237], v87
	v_cvt_pk_f32_fp8_sdwa v[238:239], v87 src0_sel:WORD_1
	v_pk_fma_f32 v[228:229], v[52:53], v[236:237], 0 op_sel_hi:[0,1,0]
	v_pk_fma_f32 v[230:231], v[52:53], v[238:239], 0 op_sel_hi:[0,1,0]
	s_waitcnt vmcnt(30)
	v_cvt_pk_f32_fp8_e32 v[232:233], v88
	v_cvt_pk_f32_fp8_sdwa v[234:235], v88 src0_sel:WORD_1
	v_pk_fma_f32 v[216:217], v[52:53], v[232:233], v[216:217] op_sel:[1,0,0]
	v_pk_fma_f32 v[218:219], v[52:53], v[234:235], v[218:219] op_sel:[1,0,0]
	v_cvt_pk_f32_fp8_e32 v[236:237], v89
	v_cvt_pk_f32_fp8_sdwa v[238:239], v89 src0_sel:WORD_1
	v_pk_fma_f32 v[220:221], v[52:53], v[236:237], v[220:221] op_sel:[1,0,0]
	v_pk_fma_f32 v[222:223], v[52:53], v[238:239], v[222:223] op_sel:[1,0,0]
	v_cvt_pk_f32_fp8_e32 v[232:233], v90
	v_cvt_pk_f32_fp8_sdwa v[234:235], v90 src0_sel:WORD_1
	v_pk_fma_f32 v[224:225], v[52:53], v[232:233], v[224:225] op_sel:[1,0,0]
	v_pk_fma_f32 v[226:227], v[52:53], v[234:235], v[226:227] op_sel:[1,0,0]
	v_cvt_pk_f32_fp8_e32 v[236:237], v91
	v_cvt_pk_f32_fp8_sdwa v[238:239], v91 src0_sel:WORD_1
	v_pk_fma_f32 v[228:229], v[52:53], v[236:237], v[228:229] op_sel:[1,0,0]
	v_pk_fma_f32 v[230:231], v[52:53], v[238:239], v[230:231] op_sel:[1,0,0]
	s_waitcnt vmcnt(29)
	v_cvt_pk_f32_fp8_e32 v[232:233], v92
	v_cvt_pk_f32_fp8_sdwa v[234:235], v92 src0_sel:WORD_1
	v_pk_fma_f32 v[216:217], v[54:55], v[232:233], v[216:217] op_sel_hi:[0,1,1]
	v_pk_fma_f32 v[218:219], v[54:55], v[234:235], v[218:219] op_sel_hi:[0,1,1]
	v_cvt_pk_f32_fp8_e32 v[236:237], v93
	v_cvt_pk_f32_fp8_sdwa v[238:239], v93 src0_sel:WORD_1
	v_pk_fma_f32 v[220:221], v[54:55], v[236:237], v[220:221] op_sel_hi:[0,1,1]
	v_pk_fma_f32 v[222:223], v[54:55], v[238:239], v[222:223] op_sel_hi:[0,1,1]
	v_cvt_pk_f32_fp8_e32 v[232:233], v94
	v_cvt_pk_f32_fp8_sdwa v[234:235], v94 src0_sel:WORD_1
	v_pk_fma_f32 v[224:225], v[54:55], v[232:233], v[224:225] op_sel_hi:[0,1,1]
	v_pk_fma_f32 v[226:227], v[54:55], v[234:235], v[226:227] op_sel_hi:[0,1,1]
	v_cvt_pk_f32_fp8_e32 v[236:237], v95
	v_cvt_pk_f32_fp8_sdwa v[238:239], v95 src0_sel:WORD_1
	v_pk_fma_f32 v[228:229], v[54:55], v[236:237], v[228:229] op_sel_hi:[0,1,1]
	v_pk_fma_f32 v[230:231], v[54:55], v[238:239], v[230:231] op_sel_hi:[0,1,1]
	s_waitcnt vmcnt(28)
	v_cvt_pk_f32_fp8_e32 v[232:233], v96
	v_cvt_pk_f32_fp8_sdwa v[234:235], v96 src0_sel:WORD_1
	v_pk_fma_f32 v[216:217], v[54:55], v[232:233], v[216:217] op_sel:[1,0,0]
	v_pk_fma_f32 v[218:219], v[54:55], v[234:235], v[218:219] op_sel:[1,0,0]
	v_cvt_pk_f32_fp8_e32 v[236:237], v97
	v_cvt_pk_f32_fp8_sdwa v[238:239], v97 src0_sel:WORD_1
	v_pk_fma_f32 v[220:221], v[54:55], v[236:237], v[220:221] op_sel:[1,0,0]
	v_pk_fma_f32 v[222:223], v[54:55], v[238:239], v[222:223] op_sel:[1,0,0]
	v_cvt_pk_f32_fp8_e32 v[232:233], v98
	v_cvt_pk_f32_fp8_sdwa v[234:235], v98 src0_sel:WORD_1
	v_pk_fma_f32 v[224:225], v[54:55], v[232:233], v[224:225] op_sel:[1,0,0]
	v_pk_fma_f32 v[226:227], v[54:55], v[234:235], v[226:227] op_sel:[1,0,0]
	v_cvt_pk_f32_fp8_e32 v[236:237], v99
	v_cvt_pk_f32_fp8_sdwa v[238:239], v99 src0_sel:WORD_1
	v_pk_fma_f32 v[228:229], v[54:55], v[236:237], v[228:229] op_sel:[1,0,0]
	v_pk_fma_f32 v[230:231], v[54:55], v[238:239], v[230:231] op_sel:[1,0,0]
	s_waitcnt vmcnt(27)
	v_cvt_pk_f32_fp8_e32 v[232:233], v100
	v_cvt_pk_f32_fp8_sdwa v[234:235], v100 src0_sel:WORD_1
	v_pk_fma_f32 v[216:217], v[56:57], v[232:233], v[216:217] op_sel_hi:[0,1,1]
	v_pk_fma_f32 v[218:219], v[56:57], v[234:235], v[218:219] op_sel_hi:[0,1,1]
	v_cvt_pk_f32_fp8_e32 v[236:237], v101
	v_cvt_pk_f32_fp8_sdwa v[238:239], v101 src0_sel:WORD_1
	v_pk_fma_f32 v[220:221], v[56:57], v[236:237], v[220:221] op_sel_hi:[0,1,1]
	v_pk_fma_f32 v[222:223], v[56:57], v[238:239], v[222:223] op_sel_hi:[0,1,1]
	v_cvt_pk_f32_fp8_e32 v[232:233], v102
	v_cvt_pk_f32_fp8_sdwa v[234:235], v102 src0_sel:WORD_1
	v_pk_fma_f32 v[224:225], v[56:57], v[232:233], v[224:225] op_sel_hi:[0,1,1]
	v_pk_fma_f32 v[226:227], v[56:57], v[234:235], v[226:227] op_sel_hi:[0,1,1]
	v_cvt_pk_f32_fp8_e32 v[236:237], v103
	v_cvt_pk_f32_fp8_sdwa v[238:239], v103 src0_sel:WORD_1
	v_pk_fma_f32 v[228:229], v[56:57], v[236:237], v[228:229] op_sel_hi:[0,1,1]
	v_pk_fma_f32 v[230:231], v[56:57], v[238:239], v[230:231] op_sel_hi:[0,1,1]
	s_waitcnt vmcnt(26)
	v_cvt_pk_f32_fp8_e32 v[232:233], v104
	v_cvt_pk_f32_fp8_sdwa v[234:235], v104 src0_sel:WORD_1
	v_pk_fma_f32 v[216:217], v[56:57], v[232:233], v[216:217] op_sel:[1,0,0]
	v_pk_fma_f32 v[218:219], v[56:57], v[234:235], v[218:219] op_sel:[1,0,0]
	v_cvt_pk_f32_fp8_e32 v[236:237], v105
	v_cvt_pk_f32_fp8_sdwa v[238:239], v105 src0_sel:WORD_1
	v_pk_fma_f32 v[220:221], v[56:57], v[236:237], v[220:221] op_sel:[1,0,0]
	v_pk_fma_f32 v[222:223], v[56:57], v[238:239], v[222:223] op_sel:[1,0,0]
	v_cvt_pk_f32_fp8_e32 v[232:233], v106
	v_cvt_pk_f32_fp8_sdwa v[234:235], v106 src0_sel:WORD_1
	v_pk_fma_f32 v[224:225], v[56:57], v[232:233], v[224:225] op_sel:[1,0,0]
	v_pk_fma_f32 v[226:227], v[56:57], v[234:235], v[226:227] op_sel:[1,0,0]
	v_cvt_pk_f32_fp8_e32 v[236:237], v107
	v_cvt_pk_f32_fp8_sdwa v[238:239], v107 src0_sel:WORD_1
	v_pk_fma_f32 v[228:229], v[56:57], v[236:237], v[228:229] op_sel:[1,0,0]
	v_pk_fma_f32 v[230:231], v[56:57], v[238:239], v[230:231] op_sel:[1,0,0]
	s_waitcnt vmcnt(25)
; DI f2_t cvt8lo(unsigned w) { return __builtin_amdgcn_cvt_pk_f32_fp8(w, false); }
; DI f2_t cvt8hi(unsigned w) { return __builtin_amdgcn_cvt_pk_f32_fp8(w, true); }
; DI void phase11(const Params& p, char* smem, int rep) {
;     ...
;         u32x4 rows[16];
; #pragma unroll
;         for (int k = 0; k < 16; ++k) rows[k] = *(const u32x4*)(vb + (size_t)ida[k] * 2048);
; #pragma unroll
;         for (int k = 0; k < 16; ++k) {
;           const f2_t a2 = {aa[k], aa[k]};
; #pragma unroll
;           for (int d = 0; d < 4; ++d) { const unsigned ww = rows[k][d]; o[2 * d] += a2 * cvt8lo(ww); o[2 * d + 1] += a2 * cvt8hi(ww); }
;         }
	v_cvt_pk_f32_fp8_e32 v[232:233], v108
	v_cvt_pk_f32_fp8_sdwa v[234:235], v108 src0_sel:WORD_1
	v_pk_fma_f32 v[216:217], v[58:59], v[232:233], v[216:217] op_sel_hi:[0,1,1]
	v_pk_fma_f32 v[218:219], v[58:59], v[234:235], v[218:219] op_sel_hi:[0,1,1]
	v_cvt_pk_f32_fp8_e32 v[236:237], v109
	v_cvt_pk_f32_fp8_sdwa v[238:239], v109 src0_sel:WORD_1
	v_pk_fma_f32 v[220:221], v[58:59], v[236:237], v[220:221] op_sel_hi:[0,1,1]
	v_pk_fma_f32 v[222:223], v[58:59], v[238:239], v[222:223] op_sel_hi:[0,1,1]
	v_cvt_pk_f32_fp8_e32 v[232:233], v110
	v_cvt_pk_f32_fp8_sdwa v[234:235], v110 src0_sel:WORD_1
	v_pk_fma_f32 v[224:225], v[58:59], v[232:233], v[224:225] op_sel_hi:[0,1,1]
	v_pk_fma_f32 v[226:227], v[58:59], v[234:235], v[226:227] op_sel_hi:[0,1,1]
	v_cvt_pk_f32_fp8_e32 v[236:237], v111
	v_cvt_pk_f32_fp8_sdwa v[238:239], v111 src0_sel:WORD_1
	v_pk_fma_f32 v[228:229], v[58:59], v[236:237], v[228:229] op_sel_hi:[0,1,1]
	v_pk_fma_f32 v[230:231], v[58:59], v[238:239], v[230:231] op_sel_hi:[0,1,1]
	s_waitcnt vmcnt(24)
	v_cvt_pk_f32_fp8_e32 v[232:233], v112
	v_cvt_pk_f32_fp8_sdwa v[234:235], v112 src0_sel:WORD_1
	v_pk_fma_f32 v[216:217], v[58:59], v[232:233], v[216:217] op_sel:[1,0,0]
	v_pk_fma_f32 v[218:219], v[58:59], v[234:235], v[218:219] op_sel:[1,0,0]
	v_cvt_pk_f32_fp8_e32 v[236:237], v113
	v_cvt_pk_f32_fp8_sdwa v[238:239], v113 src0_sel:WORD_1
	v_pk_fma_f32 v[220:221], v[58:59], v[236:237], v[220:221] op_sel:[1,0,0]
	v_pk_fma_f32 v[222:223], v[58:59], v[238:239], v[222:223] op_sel:[1,0,0]
	v_cvt_pk_f32_fp8_e32 v[232:233], v114
	v_cvt_pk_f32_fp8_sdwa v[234:235], v114 src0_sel:WORD_1
	v_pk_fma_f32 v[224:225], v[58:59], v[232:233], v[224:225] op_sel:[1,0,0]
	v_pk_fma_f32 v[226:227], v[58:59], v[234:235], v[226:227] op_sel:[1,0,0]
	v_cvt_pk_f32_fp8_e32 v[236:237], v115
	v_cvt_pk_f32_fp8_sdwa v[238:239], v115 src0_sel:WORD_1
	v_pk_fma_f32 v[228:229], v[58:59], v[236:237], v[228:229] op_sel:[1,0,0]
	v_pk_fma_f32 v[230:231], v[58:59], v[238:239], v[230:231] op_sel:[1,0,0]
	s_waitcnt vmcnt(23)
	v_cvt_pk_f32_fp8_e32 v[232:233], v116
	v_cvt_pk_f32_fp8_sdwa v[234:235], v116 src0_sel:WORD_1
	v_pk_fma_f32 v[216:217], v[60:61], v[232:233], v[216:217] op_sel_hi:[0,1,1]
	v_pk_fma_f32 v[218:219], v[60:61], v[234:235], v[218:219] op_sel_hi:[0,1,1]
	v_cvt_pk_f32_fp8_e32 v[236:237], v117
	v_cvt_pk_f32_fp8_sdwa v[238:239], v117 src0_sel:WORD_1
	v_pk_fma_f32 v[220:221], v[60:61], v[236:237], v[220:221] op_sel_hi:[0,1,1]
	v_pk_fma_f32 v[222:223], v[60:61], v[238:239], v[222:223] op_sel_hi:[0,1,1]
	v_cvt_pk_f32_fp8_e32 v[232:233], v118
	v_cvt_pk_f32_fp8_sdwa v[234:235], v118 src0_sel:WORD_1
	v_pk_fma_f32 v[224:225], v[60:61], v[232:233], v[224:225] op_sel_hi:[0,1,1]
	v_pk_fma_f32 v[226:227], v[60:61], v[234:235], v[226:227] op_sel_hi:[0,1,1]
	v_cvt_pk_f32_fp8_e32 v[236:237], v119
	v_cvt_pk_f32_fp8_sdwa v[238:239], v119 src0_sel:WORD_1
	v_pk_fma_f32 v[228:229], v[60:61], v[236:237], v[228:229] op_sel_hi:[0,1,1]
	v_pk_fma_f32 v[230:231], v[60:61], v[238:239], v[230:231] op_sel_hi:[0,1,1]
	s_waitcnt vmcnt(22)
	v_cvt_pk_f32_fp8_e32 v[232:233], v120
	v_cvt_pk_f32_fp8_sdwa v[234:235], v120 src0_sel:WORD_1
	v_pk_fma_f32 v[216:217], v[60:61], v[232:233], v[216:217] op_sel:[1,0,0]
	v_pk_fma_f32 v[218:219], v[60:61], v[234:235], v[218:219] op_sel:[1,0,0]
	v_cvt_pk_f32_fp8_e32 v[236:237], v121
	v_cvt_pk_f32_fp8_sdwa v[238:239], v121 src0_sel:WORD_1
	v_pk_fma_f32 v[220:221], v[60:61], v[236:237], v[220:221] op_sel:[1,0,0]
	v_pk_fma_f32 v[222:223], v[60:61], v[238:239], v[222:223] op_sel:[1,0,0]
	v_cvt_pk_f32_fp8_e32 v[232:233], v122
	v_cvt_pk_f32_fp8_sdwa v[234:235], v122 src0_sel:WORD_1
	v_pk_fma_f32 v[224:225], v[60:61], v[232:233], v[224:225] op_sel:[1,0,0]
	v_pk_fma_f32 v[226:227], v[60:61], v[234:235], v[226:227] op_sel:[1,0,0]
	v_cvt_pk_f32_fp8_e32 v[236:237], v123
	v_cvt_pk_f32_fp8_sdwa v[238:239], v123 src0_sel:WORD_1
	v_pk_fma_f32 v[228:229], v[60:61], v[236:237], v[228:229] op_sel:[1,0,0]
	v_pk_fma_f32 v[230:231], v[60:61], v[238:239], v[230:231] op_sel:[1,0,0]
	s_waitcnt vmcnt(21)
	v_cvt_pk_f32_fp8_e32 v[232:233], v124
	v_cvt_pk_f32_fp8_sdwa v[234:235], v124 src0_sel:WORD_1
	v_pk_fma_f32 v[216:217], v[62:63], v[232:233], v[216:217] op_sel_hi:[0,1,1]
	v_pk_fma_f32 v[218:219], v[62:63], v[234:235], v[218:219] op_sel_hi:[0,1,1]
	v_cvt_pk_f32_fp8_e32 v[236:237], v125
	v_cvt_pk_f32_fp8_sdwa v[238:239], v125 src0_sel:WORD_1
	v_pk_fma_f32 v[220:221], v[62:63], v[236:237], v[220:221] op_sel_hi:[0,1,1]
	v_pk_fma_f32 v[222:223], v[62:63], v[238:239], v[222:223] op_sel_hi:[0,1,1]
	v_cvt_pk_f32_fp8_e32 v[232:233], v126
	v_cvt_pk_f32_fp8_sdwa v[234:235], v126 src0_sel:WORD_1
	v_pk_fma_f32 v[224:225], v[62:63], v[232:233], v[224:225] op_sel_hi:[0,1,1]
	v_pk_fma_f32 v[226:227], v[62:63], v[234:235], v[226:227] op_sel_hi:[0,1,1]
	v_cvt_pk_f32_fp8_e32 v[236:237], v127
	v_cvt_pk_f32_fp8_sdwa v[238:239], v127 src0_sel:WORD_1
	v_pk_fma_f32 v[228:229], v[62:63], v[236:237], v[228:229] op_sel_hi:[0,1,1]
	v_pk_fma_f32 v[230:231], v[62:63], v[238:239], v[230:231] op_sel_hi:[0,1,1]
	s_waitcnt vmcnt(20)
	v_cvt_pk_f32_fp8_e32 v[232:233], v128
	v_cvt_pk_f32_fp8_sdwa v[234:235], v128 src0_sel:WORD_1
	v_pk_fma_f32 v[216:217], v[62:63], v[232:233], v[216:217] op_sel:[1,0,0]
	v_pk_fma_f32 v[218:219], v[62:63], v[234:235], v[218:219] op_sel:[1,0,0]
	v_cvt_pk_f32_fp8_e32 v[236:237], v129
	v_cvt_pk_f32_fp8_sdwa v[238:239], v129 src0_sel:WORD_1
	v_pk_fma_f32 v[220:221], v[62:63], v[236:237], v[220:221] op_sel:[1,0,0]
	v_pk_fma_f32 v[222:223], v[62:63], v[238:239], v[222:223] op_sel:[1,0,0]
	v_cvt_pk_f32_fp8_e32 v[232:233], v130
	v_cvt_pk_f32_fp8_sdwa v[234:235], v130 src0_sel:WORD_1
	v_pk_fma_f32 v[224:225], v[62:63], v[232:233], v[224:225] op_sel:[1,0,0]
	v_pk_fma_f32 v[226:227], v[62:63], v[234:235], v[226:227] op_sel:[1,0,0]
	v_cvt_pk_f32_fp8_e32 v[236:237], v131
	v_cvt_pk_f32_fp8_sdwa v[238:239], v131 src0_sel:WORD_1
	v_pk_fma_f32 v[228:229], v[62:63], v[236:237], v[228:229] op_sel:[1,0,0]
	v_pk_fma_f32 v[230:231], v[62:63], v[238:239], v[230:231] op_sel:[1,0,0]
	s_waitcnt vmcnt(19)
; DI f2_t cvt8lo(unsigned w) { return __builtin_amdgcn_cvt_pk_f32_fp8(w, false); }
; DI f2_t cvt8hi(unsigned w) { return __builtin_amdgcn_cvt_pk_f32_fp8(w, true); }
; DI void wave_lds_sync() { asm volatile("s_waitcnt lgkmcnt(0)" ::: "memory"); __builtin_amdgcn_wave_barrier(); }
; DI void phase11(const Params& p, char* smem, int rep) {
;     ...
;       wave_lds_sync();
;       lw[(lane & 3) * 32 + (lane >> 2)] = i0; lw[(lane & 3) * 32 + 16 + (lane >> 2)] = i1;
;       lf[(lane & 3) * 32 + (lane >> 2)] = a0; lf[(lane & 3) * 32 + 16 + (lane >> 2)] = a1;
;       wave_lds_sync();
;       f2_t o[8];
; #pragma unroll
;       for (int i = 0; i < 8; ++i) o[i] = f2_t{0.f, 0.f};
;       const unsigned char* vb = V8 + s * 256 + l15 * 16;
; #pragma unroll
;       for (int batch = 0; batch < 2; ++batch) {
;         int ida[16]; float aa[16];
; #pragma unroll
;         for (int q = 0; q < 4; ++q) {
;           const int4 v = *(const int4*)(lw + g * 32 + batch * 16 + q * 4); ida[q * 4] = v.x; ida[q * 4 + 1] = v.y; ida[q * 4 + 2] = v.z; ida[q * 4 + 3] = v.w;
;           const float4 f = *(const float4*)(lf + g * 32 + batch * 16 + q * 4); aa[q * 4] = f.x; aa[q * 4 + 1] = f.y; aa[q * 4 + 2] = f.z; aa[q * 4 + 3] = f.w;
;     ...
;         u32x4 rows[16];
; #pragma unroll
;         for (int k = 0; k < 16; ++k) rows[k] = *(const u32x4*)(vb + (size_t)ida[k] * 2048);
; #pragma unroll
;         for (int k = 0; k < 16; ++k) {
;           const f2_t a2 = {aa[k], aa[k]};
; #pragma unroll
;           for (int d = 0; d < 4; ++d) { const unsigned ww = rows[k][d]; o[2 * d] += a2 * cvt8lo(ww); o[2 * d + 1] += a2 * cvt8hi(ww); }
;         }
	v_cvt_pk_f32_fp8_e32 v[232:233], v132
	v_cvt_pk_f32_fp8_sdwa v[234:235], v132 src0_sel:WORD_1
	v_pk_fma_f32 v[216:217], v[64:65], v[232:233], v[216:217] op_sel_hi:[0,1,1]
	v_pk_fma_f32 v[218:219], v[64:65], v[234:235], v[218:219] op_sel_hi:[0,1,1]
	v_cvt_pk_f32_fp8_e32 v[236:237], v133
	v_cvt_pk_f32_fp8_sdwa v[238:239], v133 src0_sel:WORD_1
	v_pk_fma_f32 v[220:221], v[64:65], v[236:237], v[220:221] op_sel_hi:[0,1,1]
	v_pk_fma_f32 v[222:223], v[64:65], v[238:239], v[222:223] op_sel_hi:[0,1,1]
	v_cvt_pk_f32_fp8_e32 v[232:233], v134
	v_cvt_pk_f32_fp8_sdwa v[234:235], v134 src0_sel:WORD_1
	v_pk_fma_f32 v[224:225], v[64:65], v[232:233], v[224:225] op_sel_hi:[0,1,1]
	v_pk_fma_f32 v[226:227], v[64:65], v[234:235], v[226:227] op_sel_hi:[0,1,1]
	v_cvt_pk_f32_fp8_e32 v[236:237], v135
	v_cvt_pk_f32_fp8_sdwa v[238:239], v135 src0_sel:WORD_1
	v_pk_fma_f32 v[228:229], v[64:65], v[236:237], v[228:229] op_sel_hi:[0,1,1]
	v_pk_fma_f32 v[230:231], v[64:65], v[238:239], v[230:231] op_sel_hi:[0,1,1]
	s_waitcnt vmcnt(18)
	v_cvt_pk_f32_fp8_e32 v[232:233], v136
	v_cvt_pk_f32_fp8_sdwa v[234:235], v136 src0_sel:WORD_1
	v_pk_fma_f32 v[216:217], v[64:65], v[232:233], v[216:217] op_sel:[1,0,0]
	v_pk_fma_f32 v[218:219], v[64:65], v[234:235], v[218:219] op_sel:[1,0,0]
	v_cvt_pk_f32_fp8_e32 v[236:237], v137
	v_cvt_pk_f32_fp8_sdwa v[238:239], v137 src0_sel:WORD_1
	v_pk_fma_f32 v[220:221], v[64:65], v[236:237], v[220:221] op_sel:[1,0,0]
	v_pk_fma_f32 v[222:223], v[64:65], v[238:239], v[222:223] op_sel:[1,0,0]
	v_cvt_pk_f32_fp8_e32 v[232:233], v138
	v_cvt_pk_f32_fp8_sdwa v[234:235], v138 src0_sel:WORD_1
	v_pk_fma_f32 v[224:225], v[64:65], v[232:233], v[224:225] op_sel:[1,0,0]
	v_pk_fma_f32 v[226:227], v[64:65], v[234:235], v[226:227] op_sel:[1,0,0]
	v_cvt_pk_f32_fp8_e32 v[236:237], v139
	v_cvt_pk_f32_fp8_sdwa v[238:239], v139 src0_sel:WORD_1
	v_pk_fma_f32 v[228:229], v[64:65], v[236:237], v[228:229] op_sel:[1,0,0]
	v_pk_fma_f32 v[230:231], v[64:65], v[238:239], v[230:231] op_sel:[1,0,0]
	s_waitcnt vmcnt(17)
	v_cvt_pk_f32_fp8_e32 v[232:233], v140
	v_cvt_pk_f32_fp8_sdwa v[234:235], v140 src0_sel:WORD_1
	v_pk_fma_f32 v[216:217], v[66:67], v[232:233], v[216:217] op_sel_hi:[0,1,1]
	v_pk_fma_f32 v[218:219], v[66:67], v[234:235], v[218:219] op_sel_hi:[0,1,1]
	v_cvt_pk_f32_fp8_e32 v[236:237], v141
	v_cvt_pk_f32_fp8_sdwa v[238:239], v141 src0_sel:WORD_1
	v_pk_fma_f32 v[220:221], v[66:67], v[236:237], v[220:221] op_sel_hi:[0,1,1]
	v_pk_fma_f32 v[222:223], v[66:67], v[238:239], v[222:223] op_sel_hi:[0,1,1]
	v_cvt_pk_f32_fp8_e32 v[232:233], v142
	v_cvt_pk_f32_fp8_sdwa v[234:235], v142 src0_sel:WORD_1
	v_pk_fma_f32 v[224:225], v[66:67], v[232:233], v[224:225] op_sel_hi:[0,1,1]
	v_pk_fma_f32 v[226:227], v[66:67], v[234:235], v[226:227] op_sel_hi:[0,1,1]
	v_cvt_pk_f32_fp8_e32 v[236:237], v143
	v_cvt_pk_f32_fp8_sdwa v[238:239], v143 src0_sel:WORD_1
	v_pk_fma_f32 v[228:229], v[66:67], v[236:237], v[228:229] op_sel_hi:[0,1,1]
	v_pk_fma_f32 v[230:231], v[66:67], v[238:239], v[230:231] op_sel_hi:[0,1,1]
	s_waitcnt vmcnt(16)
	v_cvt_pk_f32_fp8_e32 v[232:233], v144
	v_cvt_pk_f32_fp8_sdwa v[234:235], v144 src0_sel:WORD_1
	v_pk_fma_f32 v[216:217], v[66:67], v[232:233], v[216:217] op_sel:[1,0,0]
	v_pk_fma_f32 v[218:219], v[66:67], v[234:235], v[218:219] op_sel:[1,0,0]
	v_cvt_pk_f32_fp8_e32 v[236:237], v145
	v_cvt_pk_f32_fp8_sdwa v[238:239], v145 src0_sel:WORD_1
	v_pk_fma_f32 v[220:221], v[66:67], v[236:237], v[220:221] op_sel:[1,0,0]
	v_pk_fma_f32 v[222:223], v[66:67], v[238:239], v[222:223] op_sel:[1,0,0]
	v_cvt_pk_f32_fp8_e32 v[232:233], v146
	v_cvt_pk_f32_fp8_sdwa v[234:235], v146 src0_sel:WORD_1
	v_pk_fma_f32 v[224:225], v[66:67], v[232:233], v[224:225] op_sel:[1,0,0]
	v_pk_fma_f32 v[226:227], v[66:67], v[234:235], v[226:227] op_sel:[1,0,0]
	v_cvt_pk_f32_fp8_e32 v[236:237], v147
	v_cvt_pk_f32_fp8_sdwa v[238:239], v147 src0_sel:WORD_1
	v_pk_fma_f32 v[228:229], v[66:67], v[236:237], v[228:229] op_sel:[1,0,0]
	v_pk_fma_f32 v[230:231], v[66:67], v[238:239], v[230:231] op_sel:[1,0,0]
	ds_write2_b32 v5, v10, v11 offset0:4 offset1:20
	ds_write2_b32 v5, v12, v13 offset0:132 offset1:148
	s_waitcnt lgkmcnt(0)
	ds_read_b128 v[20:23], v6 offset:16
	ds_read_b128 v[24:27], v6 offset:32
	ds_read_b128 v[28:31], v6 offset:48
	ds_read_b128 v[32:35], v6 offset:64
	ds_read_b128 v[36:39], v6 offset:80
	ds_read_b128 v[40:43], v6 offset:96
	ds_read_b128 v[44:47], v6 offset:112
	ds_read_b128 v[48:51], v6 offset:128
	s_waitcnt vmcnt(15)
	v_cvt_pk_f32_fp8_e32 v[232:233], v148
	v_cvt_pk_f32_fp8_sdwa v[234:235], v148 src0_sel:WORD_1
	v_pk_fma_f32 v[216:217], v[68:69], v[232:233], v[216:217] op_sel_hi:[0,1,1]
	v_pk_fma_f32 v[218:219], v[68:69], v[234:235], v[218:219] op_sel_hi:[0,1,1]
	v_cvt_pk_f32_fp8_e32 v[236:237], v149
	v_cvt_pk_f32_fp8_sdwa v[238:239], v149 src0_sel:WORD_1
	v_pk_fma_f32 v[220:221], v[68:69], v[236:237], v[220:221] op_sel_hi:[0,1,1]
	v_pk_fma_f32 v[222:223], v[68:69], v[238:239], v[222:223] op_sel_hi:[0,1,1]
	v_cvt_pk_f32_fp8_e32 v[232:233], v150
	v_cvt_pk_f32_fp8_sdwa v[234:235], v150 src0_sel:WORD_1
	v_pk_fma_f32 v[224:225], v[68:69], v[232:233], v[224:225] op_sel_hi:[0,1,1]
	v_pk_fma_f32 v[226:227], v[68:69], v[234:235], v[226:227] op_sel_hi:[0,1,1]
	v_cvt_pk_f32_fp8_e32 v[236:237], v151
	v_cvt_pk_f32_fp8_sdwa v[238:239], v151 src0_sel:WORD_1
	v_pk_fma_f32 v[228:229], v[68:69], v[236:237], v[228:229] op_sel_hi:[0,1,1]
	v_pk_fma_f32 v[230:231], v[68:69], v[238:239], v[230:231] op_sel_hi:[0,1,1]
	s_waitcnt vmcnt(14)
; DI f2_t cvt8lo(unsigned w) { return __builtin_amdgcn_cvt_pk_f32_fp8(w, false); }
; DI f2_t cvt8hi(unsigned w) { return __builtin_amdgcn_cvt_pk_f32_fp8(w, true); }
; DI void phase11(const Params& p, char* smem, int rep) {
;     ...
;         u32x4 rows[16];
; #pragma unroll
;         for (int k = 0; k < 16; ++k) rows[k] = *(const u32x4*)(vb + (size_t)ida[k] * 2048);
; #pragma unroll
;         for (int k = 0; k < 16; ++k) {
;           const f2_t a2 = {aa[k], aa[k]};
; #pragma unroll
;           for (int d = 0; d < 4; ++d) { const unsigned ww = rows[k][d]; o[2 * d] += a2 * cvt8lo(ww); o[2 * d + 1] += a2 * cvt8hi(ww); }
;         }
	v_cvt_pk_f32_fp8_e32 v[232:233], v152
	v_cvt_pk_f32_fp8_sdwa v[234:235], v152 src0_sel:WORD_1
	v_pk_fma_f32 v[216:217], v[68:69], v[232:233], v[216:217] op_sel:[1,0,0]
	v_pk_fma_f32 v[218:219], v[68:69], v[234:235], v[218:219] op_sel:[1,0,0]
	v_cvt_pk_f32_fp8_e32 v[236:237], v153
	v_cvt_pk_f32_fp8_sdwa v[238:239], v153 src0_sel:WORD_1
	v_pk_fma_f32 v[220:221], v[68:69], v[236:237], v[220:221] op_sel:[1,0,0]
	v_pk_fma_f32 v[222:223], v[68:69], v[238:239], v[222:223] op_sel:[1,0,0]
	v_cvt_pk_f32_fp8_e32 v[232:233], v154
	v_cvt_pk_f32_fp8_sdwa v[234:235], v154 src0_sel:WORD_1
	v_pk_fma_f32 v[224:225], v[68:69], v[232:233], v[224:225] op_sel:[1,0,0]
	v_pk_fma_f32 v[226:227], v[68:69], v[234:235], v[226:227] op_sel:[1,0,0]
	v_cvt_pk_f32_fp8_e32 v[236:237], v155
	v_cvt_pk_f32_fp8_sdwa v[238:239], v155 src0_sel:WORD_1
	v_pk_fma_f32 v[228:229], v[68:69], v[236:237], v[228:229] op_sel:[1,0,0]
	v_pk_fma_f32 v[230:231], v[68:69], v[238:239], v[230:231] op_sel:[1,0,0]
	s_waitcnt vmcnt(13)
	v_cvt_pk_f32_fp8_e32 v[232:233], v156
	v_cvt_pk_f32_fp8_sdwa v[234:235], v156 src0_sel:WORD_1
	v_pk_fma_f32 v[216:217], v[70:71], v[232:233], v[216:217] op_sel_hi:[0,1,1]
	v_pk_fma_f32 v[218:219], v[70:71], v[234:235], v[218:219] op_sel_hi:[0,1,1]
	v_cvt_pk_f32_fp8_e32 v[236:237], v157
	v_cvt_pk_f32_fp8_sdwa v[238:239], v157 src0_sel:WORD_1
	v_pk_fma_f32 v[220:221], v[70:71], v[236:237], v[220:221] op_sel_hi:[0,1,1]
	v_pk_fma_f32 v[222:223], v[70:71], v[238:239], v[222:223] op_sel_hi:[0,1,1]
	v_cvt_pk_f32_fp8_e32 v[232:233], v158
	v_cvt_pk_f32_fp8_sdwa v[234:235], v158 src0_sel:WORD_1
	v_pk_fma_f32 v[224:225], v[70:71], v[232:233], v[224:225] op_sel_hi:[0,1,1]
	v_pk_fma_f32 v[226:227], v[70:71], v[234:235], v[226:227] op_sel_hi:[0,1,1]
	v_cvt_pk_f32_fp8_e32 v[236:237], v159
	v_cvt_pk_f32_fp8_sdwa v[238:239], v159 src0_sel:WORD_1
	v_pk_fma_f32 v[228:229], v[70:71], v[236:237], v[228:229] op_sel_hi:[0,1,1]
	v_pk_fma_f32 v[230:231], v[70:71], v[238:239], v[230:231] op_sel_hi:[0,1,1]
	s_waitcnt vmcnt(12)
	v_cvt_pk_f32_fp8_e32 v[232:233], v160
	v_cvt_pk_f32_fp8_sdwa v[234:235], v160 src0_sel:WORD_1
	v_pk_fma_f32 v[216:217], v[70:71], v[232:233], v[216:217] op_sel:[1,0,0]
	v_pk_fma_f32 v[218:219], v[70:71], v[234:235], v[218:219] op_sel:[1,0,0]
	v_cvt_pk_f32_fp8_e32 v[236:237], v161
	v_cvt_pk_f32_fp8_sdwa v[238:239], v161 src0_sel:WORD_1
	v_pk_fma_f32 v[220:221], v[70:71], v[236:237], v[220:221] op_sel:[1,0,0]
	v_pk_fma_f32 v[222:223], v[70:71], v[238:239], v[222:223] op_sel:[1,0,0]
	v_cvt_pk_f32_fp8_e32 v[232:233], v162
	v_cvt_pk_f32_fp8_sdwa v[234:235], v162 src0_sel:WORD_1
	v_pk_fma_f32 v[224:225], v[70:71], v[232:233], v[224:225] op_sel:[1,0,0]
	v_pk_fma_f32 v[226:227], v[70:71], v[234:235], v[226:227] op_sel:[1,0,0]
	v_cvt_pk_f32_fp8_e32 v[236:237], v163
	v_cvt_pk_f32_fp8_sdwa v[238:239], v163 src0_sel:WORD_1
	v_pk_fma_f32 v[228:229], v[70:71], v[236:237], v[228:229] op_sel:[1,0,0]
	v_pk_fma_f32 v[230:231], v[70:71], v[238:239], v[230:231] op_sel:[1,0,0]
	s_waitcnt vmcnt(11)
	v_cvt_pk_f32_fp8_e32 v[232:233], v164
	v_cvt_pk_f32_fp8_sdwa v[234:235], v164 src0_sel:WORD_1
	v_pk_fma_f32 v[216:217], v[72:73], v[232:233], v[216:217] op_sel_hi:[0,1,1]
	v_pk_fma_f32 v[218:219], v[72:73], v[234:235], v[218:219] op_sel_hi:[0,1,1]
	v_cvt_pk_f32_fp8_e32 v[236:237], v165
	v_cvt_pk_f32_fp8_sdwa v[238:239], v165 src0_sel:WORD_1
	v_pk_fma_f32 v[220:221], v[72:73], v[236:237], v[220:221] op_sel_hi:[0,1,1]
	v_pk_fma_f32 v[222:223], v[72:73], v[238:239], v[222:223] op_sel_hi:[0,1,1]
	v_cvt_pk_f32_fp8_e32 v[232:233], v166
	v_cvt_pk_f32_fp8_sdwa v[234:235], v166 src0_sel:WORD_1
	v_pk_fma_f32 v[224:225], v[72:73], v[232:233], v[224:225] op_sel_hi:[0,1,1]
	v_pk_fma_f32 v[226:227], v[72:73], v[234:235], v[226:227] op_sel_hi:[0,1,1]
	v_cvt_pk_f32_fp8_e32 v[236:237], v167
	v_cvt_pk_f32_fp8_sdwa v[238:239], v167 src0_sel:WORD_1
	v_pk_fma_f32 v[228:229], v[72:73], v[236:237], v[228:229] op_sel_hi:[0,1,1]
	v_pk_fma_f32 v[230:231], v[72:73], v[238:239], v[230:231] op_sel_hi:[0,1,1]
	s_waitcnt vmcnt(10)
	v_cvt_pk_f32_fp8_e32 v[232:233], v168
	v_cvt_pk_f32_fp8_sdwa v[234:235], v168 src0_sel:WORD_1
	v_pk_fma_f32 v[216:217], v[72:73], v[232:233], v[216:217] op_sel:[1,0,0]
	v_pk_fma_f32 v[218:219], v[72:73], v[234:235], v[218:219] op_sel:[1,0,0]
	v_cvt_pk_f32_fp8_e32 v[236:237], v169
	v_cvt_pk_f32_fp8_sdwa v[238:239], v169 src0_sel:WORD_1
	v_pk_fma_f32 v[220:221], v[72:73], v[236:237], v[220:221] op_sel:[1,0,0]
	v_pk_fma_f32 v[222:223], v[72:73], v[238:239], v[222:223] op_sel:[1,0,0]
	v_cvt_pk_f32_fp8_e32 v[232:233], v170
	v_cvt_pk_f32_fp8_sdwa v[234:235], v170 src0_sel:WORD_1
	v_pk_fma_f32 v[224:225], v[72:73], v[232:233], v[224:225] op_sel:[1,0,0]
	v_pk_fma_f32 v[226:227], v[72:73], v[234:235], v[226:227] op_sel:[1,0,0]
	v_cvt_pk_f32_fp8_e32 v[236:237], v171
	v_cvt_pk_f32_fp8_sdwa v[238:239], v171 src0_sel:WORD_1
	v_pk_fma_f32 v[228:229], v[72:73], v[236:237], v[228:229] op_sel:[1,0,0]
	v_pk_fma_f32 v[230:231], v[72:73], v[238:239], v[230:231] op_sel:[1,0,0]
	s_waitcnt vmcnt(9)
	v_cvt_pk_f32_fp8_e32 v[232:233], v172
	v_cvt_pk_f32_fp8_sdwa v[234:235], v172 src0_sel:WORD_1
	v_pk_fma_f32 v[216:217], v[74:75], v[232:233], v[216:217] op_sel_hi:[0,1,1]
	v_pk_fma_f32 v[218:219], v[74:75], v[234:235], v[218:219] op_sel_hi:[0,1,1]
	v_cvt_pk_f32_fp8_e32 v[236:237], v173
	v_cvt_pk_f32_fp8_sdwa v[238:239], v173 src0_sel:WORD_1
	v_pk_fma_f32 v[220:221], v[74:75], v[236:237], v[220:221] op_sel_hi:[0,1,1]
	v_pk_fma_f32 v[222:223], v[74:75], v[238:239], v[222:223] op_sel_hi:[0,1,1]
	v_cvt_pk_f32_fp8_e32 v[232:233], v174
	v_cvt_pk_f32_fp8_sdwa v[234:235], v174 src0_sel:WORD_1
	v_pk_fma_f32 v[224:225], v[74:75], v[232:233], v[224:225] op_sel_hi:[0,1,1]
	v_pk_fma_f32 v[226:227], v[74:75], v[234:235], v[226:227] op_sel_hi:[0,1,1]
	v_cvt_pk_f32_fp8_e32 v[236:237], v175
	v_cvt_pk_f32_fp8_sdwa v[238:239], v175 src0_sel:WORD_1
	v_pk_fma_f32 v[228:229], v[74:75], v[236:237], v[228:229] op_sel_hi:[0,1,1]
	v_pk_fma_f32 v[230:231], v[74:75], v[238:239], v[230:231] op_sel_hi:[0,1,1]
	s_waitcnt vmcnt(8)
; DI f2_t cvt8lo(unsigned w) { return __builtin_amdgcn_cvt_pk_f32_fp8(w, false); }
; DI f2_t cvt8hi(unsigned w) { return __builtin_amdgcn_cvt_pk_f32_fp8(w, true); }
; DI void phase11(const Params& p, char* smem, int rep) {
;     ...
;         u32x4 rows[16];
; #pragma unroll
;         for (int k = 0; k < 16; ++k) rows[k] = *(const u32x4*)(vb + (size_t)ida[k] * 2048);
; #pragma unroll
;         for (int k = 0; k < 16; ++k) {
;           const f2_t a2 = {aa[k], aa[k]};
; #pragma unroll
;           for (int d = 0; d < 4; ++d) { const unsigned ww = rows[k][d]; o[2 * d] += a2 * cvt8lo(ww); o[2 * d + 1] += a2 * cvt8hi(ww); }
;         }
	v_cvt_pk_f32_fp8_e32 v[232:233], v176
	v_cvt_pk_f32_fp8_sdwa v[234:235], v176 src0_sel:WORD_1
	v_pk_fma_f32 v[216:217], v[74:75], v[232:233], v[216:217] op_sel:[1,0,0]
	v_pk_fma_f32 v[218:219], v[74:75], v[234:235], v[218:219] op_sel:[1,0,0]
	v_cvt_pk_f32_fp8_e32 v[236:237], v177
	v_cvt_pk_f32_fp8_sdwa v[238:239], v177 src0_sel:WORD_1
	v_pk_fma_f32 v[220:221], v[74:75], v[236:237], v[220:221] op_sel:[1,0,0]
	v_pk_fma_f32 v[222:223], v[74:75], v[238:239], v[222:223] op_sel:[1,0,0]
	v_cvt_pk_f32_fp8_e32 v[232:233], v178
	v_cvt_pk_f32_fp8_sdwa v[234:235], v178 src0_sel:WORD_1
	v_pk_fma_f32 v[224:225], v[74:75], v[232:233], v[224:225] op_sel:[1,0,0]
	v_pk_fma_f32 v[226:227], v[74:75], v[234:235], v[226:227] op_sel:[1,0,0]
	v_cvt_pk_f32_fp8_e32 v[236:237], v179
	v_cvt_pk_f32_fp8_sdwa v[238:239], v179 src0_sel:WORD_1
	v_pk_fma_f32 v[228:229], v[74:75], v[236:237], v[228:229] op_sel:[1,0,0]
	v_pk_fma_f32 v[230:231], v[74:75], v[238:239], v[230:231] op_sel:[1,0,0]
	s_waitcnt vmcnt(7)
	v_cvt_pk_f32_fp8_e32 v[232:233], v180
	v_cvt_pk_f32_fp8_sdwa v[234:235], v180 src0_sel:WORD_1
	v_pk_fma_f32 v[216:217], v[76:77], v[232:233], v[216:217] op_sel_hi:[0,1,1]
	v_pk_fma_f32 v[218:219], v[76:77], v[234:235], v[218:219] op_sel_hi:[0,1,1]
	v_cvt_pk_f32_fp8_e32 v[236:237], v181
	v_cvt_pk_f32_fp8_sdwa v[238:239], v181 src0_sel:WORD_1
	v_pk_fma_f32 v[220:221], v[76:77], v[236:237], v[220:221] op_sel_hi:[0,1,1]
	v_pk_fma_f32 v[222:223], v[76:77], v[238:239], v[222:223] op_sel_hi:[0,1,1]
	v_cvt_pk_f32_fp8_e32 v[232:233], v182
	v_cvt_pk_f32_fp8_sdwa v[234:235], v182 src0_sel:WORD_1
	v_pk_fma_f32 v[224:225], v[76:77], v[232:233], v[224:225] op_sel_hi:[0,1,1]
	v_pk_fma_f32 v[226:227], v[76:77], v[234:235], v[226:227] op_sel_hi:[0,1,1]
	v_cvt_pk_f32_fp8_e32 v[236:237], v183
	v_cvt_pk_f32_fp8_sdwa v[238:239], v183 src0_sel:WORD_1
	v_pk_fma_f32 v[228:229], v[76:77], v[236:237], v[228:229] op_sel_hi:[0,1,1]
	v_pk_fma_f32 v[230:231], v[76:77], v[238:239], v[230:231] op_sel_hi:[0,1,1]
	s_waitcnt vmcnt(6)
	v_cvt_pk_f32_fp8_e32 v[232:233], v184
	v_cvt_pk_f32_fp8_sdwa v[234:235], v184 src0_sel:WORD_1
	v_pk_fma_f32 v[216:217], v[76:77], v[232:233], v[216:217] op_sel:[1,0,0]
	v_pk_fma_f32 v[218:219], v[76:77], v[234:235], v[218:219] op_sel:[1,0,0]
	v_cvt_pk_f32_fp8_e32 v[236:237], v185
	v_cvt_pk_f32_fp8_sdwa v[238:239], v185 src0_sel:WORD_1
	v_pk_fma_f32 v[220:221], v[76:77], v[236:237], v[220:221] op_sel:[1,0,0]
	v_pk_fma_f32 v[222:223], v[76:77], v[238:239], v[222:223] op_sel:[1,0,0]
	v_cvt_pk_f32_fp8_e32 v[232:233], v186
	v_cvt_pk_f32_fp8_sdwa v[234:235], v186 src0_sel:WORD_1
	v_pk_fma_f32 v[224:225], v[76:77], v[232:233], v[224:225] op_sel:[1,0,0]
	v_pk_fma_f32 v[226:227], v[76:77], v[234:235], v[226:227] op_sel:[1,0,0]
	v_cvt_pk_f32_fp8_e32 v[236:237], v187
	v_cvt_pk_f32_fp8_sdwa v[238:239], v187 src0_sel:WORD_1
	v_pk_fma_f32 v[228:229], v[76:77], v[236:237], v[228:229] op_sel:[1,0,0]
	v_pk_fma_f32 v[230:231], v[76:77], v[238:239], v[230:231] op_sel:[1,0,0]
	s_waitcnt vmcnt(5)
	v_cvt_pk_f32_fp8_e32 v[232:233], v190
	v_cvt_pk_f32_fp8_sdwa v[234:235], v190 src0_sel:WORD_1
	v_pk_fma_f32 v[216:217], v[78:79], v[232:233], v[216:217] op_sel_hi:[0,1,1]
	v_pk_fma_f32 v[218:219], v[78:79], v[234:235], v[218:219] op_sel_hi:[0,1,1]
	v_cvt_pk_f32_fp8_e32 v[236:237], v191
	v_cvt_pk_f32_fp8_sdwa v[238:239], v191 src0_sel:WORD_1
	v_pk_fma_f32 v[220:221], v[78:79], v[236:237], v[220:221] op_sel_hi:[0,1,1]
	v_pk_fma_f32 v[222:223], v[78:79], v[238:239], v[222:223] op_sel_hi:[0,1,1]
	v_cvt_pk_f32_fp8_e32 v[232:233], v192
	v_cvt_pk_f32_fp8_sdwa v[234:235], v192 src0_sel:WORD_1
	v_pk_fma_f32 v[224:225], v[78:79], v[232:233], v[224:225] op_sel_hi:[0,1,1]
	v_pk_fma_f32 v[226:227], v[78:79], v[234:235], v[226:227] op_sel_hi:[0,1,1]
	v_cvt_pk_f32_fp8_e32 v[236:237], v193
	v_cvt_pk_f32_fp8_sdwa v[238:239], v193 src0_sel:WORD_1
	v_pk_fma_f32 v[228:229], v[78:79], v[236:237], v[228:229] op_sel_hi:[0,1,1]
	v_pk_fma_f32 v[230:231], v[78:79], v[238:239], v[230:231] op_sel_hi:[0,1,1]
	s_waitcnt vmcnt(4)
	v_cvt_pk_f32_fp8_e32 v[232:233], v194
	v_cvt_pk_f32_fp8_sdwa v[234:235], v194 src0_sel:WORD_1
	v_pk_fma_f32 v[216:217], v[78:79], v[232:233], v[216:217] op_sel:[1,0,0]
	v_pk_fma_f32 v[218:219], v[78:79], v[234:235], v[218:219] op_sel:[1,0,0]
	v_cvt_pk_f32_fp8_e32 v[236:237], v195
	v_cvt_pk_f32_fp8_sdwa v[238:239], v195 src0_sel:WORD_1
	v_pk_fma_f32 v[220:221], v[78:79], v[236:237], v[220:221] op_sel:[1,0,0]
	v_pk_fma_f32 v[222:223], v[78:79], v[238:239], v[222:223] op_sel:[1,0,0]
	v_cvt_pk_f32_fp8_e32 v[232:233], v196
	v_cvt_pk_f32_fp8_sdwa v[234:235], v196 src0_sel:WORD_1
	v_pk_fma_f32 v[224:225], v[78:79], v[232:233], v[224:225] op_sel:[1,0,0]
	v_pk_fma_f32 v[226:227], v[78:79], v[234:235], v[226:227] op_sel:[1,0,0]
	v_cvt_pk_f32_fp8_e32 v[236:237], v197
	v_cvt_pk_f32_fp8_sdwa v[238:239], v197 src0_sel:WORD_1
	v_pk_fma_f32 v[228:229], v[78:79], v[236:237], v[228:229] op_sel:[1,0,0]
	v_pk_fma_f32 v[230:231], v[78:79], v[238:239], v[230:231] op_sel:[1,0,0]
	s_waitcnt vmcnt(3)
; DI unsigned pk2(float a, float b) { f2_t v = {a, b}; bf2_t r = __builtin_convertvector(v, bf2_t); return __builtin_bit_cast(unsigned, r); }
; DI f2_t cvt8lo(unsigned w) { return __builtin_amdgcn_cvt_pk_f32_fp8(w, false); }
; DI f2_t cvt8hi(unsigned w) { return __builtin_amdgcn_cvt_pk_f32_fp8(w, true); }
; DI void phase11(const Params& p, char* smem, int rep) {
;     ...
;         u32x4 rows[16];
; #pragma unroll
;         for (int k = 0; k < 16; ++k) rows[k] = *(const u32x4*)(vb + (size_t)ida[k] * 2048);
; #pragma unroll
;         for (int k = 0; k < 16; ++k) {
;           const f2_t a2 = {aa[k], aa[k]};
; #pragma unroll
;           for (int d = 0; d < 4; ++d) { const unsigned ww = rows[k][d]; o[2 * d] += a2 * cvt8lo(ww); o[2 * d + 1] += a2 * cvt8hi(ww); }
;         }
;       }
;       float ov[16];
; #pragma unroll
;       for (int d = 0; d < 4; ++d) { ov[4 * d] = o[2 * d].x; ov[4 * d + 1] = o[2 * d].y; ov[4 * d + 2] = o[2 * d + 1].x; ov[4 * d + 3] = o[2 * d + 1].y; }
;       float q8[8], q4[4];
; #pragma unroll
;       for (int k = 0; k < 8; ++k) q8[k] = (b5 ? ov[8 + k] : ov[k]) + __shfl_xor(b5 ? ov[k] : ov[8 + k], 32);
; #pragma unroll
;       for (int k = 0; k < 4; ++k) q4[k] = (b4 ? q8[4 + k] : q8[k]) + __shfl_xor(b4 ? q8[k] : q8[4 + k], 16);
;       *(uint2*)(OUTP + (size_t)tok * D_ + s * 256 + l15 * 16 + 8 * b5 + 4 * b4) = make_uint2(pk2(q4[0], q4[1]), pk2(q4[2], q4[3]));
;     }
;   });
; }
	v_cvt_pk_f32_fp8_e32 v[232:233], v198
	v_cvt_pk_f32_fp8_sdwa v[234:235], v198 src0_sel:WORD_1
	v_pk_fma_f32 v[216:217], v[80:81], v[232:233], v[216:217] op_sel_hi:[0,1,1]
	v_pk_fma_f32 v[218:219], v[80:81], v[234:235], v[218:219] op_sel_hi:[0,1,1]
	v_cvt_pk_f32_fp8_e32 v[236:237], v199
	v_cvt_pk_f32_fp8_sdwa v[238:239], v199 src0_sel:WORD_1
	v_pk_fma_f32 v[220:221], v[80:81], v[236:237], v[220:221] op_sel_hi:[0,1,1]
	v_pk_fma_f32 v[222:223], v[80:81], v[238:239], v[222:223] op_sel_hi:[0,1,1]
	v_cvt_pk_f32_fp8_e32 v[232:233], v200
	v_cvt_pk_f32_fp8_sdwa v[234:235], v200 src0_sel:WORD_1
	v_pk_fma_f32 v[224:225], v[80:81], v[232:233], v[224:225] op_sel_hi:[0,1,1]
	v_pk_fma_f32 v[226:227], v[80:81], v[234:235], v[226:227] op_sel_hi:[0,1,1]
	v_cvt_pk_f32_fp8_e32 v[236:237], v201
	v_cvt_pk_f32_fp8_sdwa v[238:239], v201 src0_sel:WORD_1
	v_pk_fma_f32 v[228:229], v[80:81], v[236:237], v[228:229] op_sel_hi:[0,1,1]
	v_pk_fma_f32 v[230:231], v[80:81], v[238:239], v[230:231] op_sel_hi:[0,1,1]
	s_waitcnt vmcnt(2)
	v_cvt_pk_f32_fp8_e32 v[232:233], v202
	v_cvt_pk_f32_fp8_sdwa v[234:235], v202 src0_sel:WORD_1
	v_pk_fma_f32 v[216:217], v[80:81], v[232:233], v[216:217] op_sel:[1,0,0]
	v_pk_fma_f32 v[218:219], v[80:81], v[234:235], v[218:219] op_sel:[1,0,0]
	v_cvt_pk_f32_fp8_e32 v[236:237], v203
	v_cvt_pk_f32_fp8_sdwa v[238:239], v203 src0_sel:WORD_1
	v_pk_fma_f32 v[220:221], v[80:81], v[236:237], v[220:221] op_sel:[1,0,0]
	v_pk_fma_f32 v[222:223], v[80:81], v[238:239], v[222:223] op_sel:[1,0,0]
	v_cvt_pk_f32_fp8_e32 v[232:233], v204
	v_cvt_pk_f32_fp8_sdwa v[234:235], v204 src0_sel:WORD_1
	v_pk_fma_f32 v[224:225], v[80:81], v[232:233], v[224:225] op_sel:[1,0,0]
	v_pk_fma_f32 v[226:227], v[80:81], v[234:235], v[226:227] op_sel:[1,0,0]
	v_cvt_pk_f32_fp8_e32 v[236:237], v205
	v_cvt_pk_f32_fp8_sdwa v[238:239], v205 src0_sel:WORD_1
	v_pk_fma_f32 v[228:229], v[80:81], v[236:237], v[228:229] op_sel:[1,0,0]
	v_pk_fma_f32 v[230:231], v[80:81], v[238:239], v[230:231] op_sel:[1,0,0]
	s_waitcnt vmcnt(1)
	v_cvt_pk_f32_fp8_e32 v[232:233], v206
	v_cvt_pk_f32_fp8_sdwa v[234:235], v206 src0_sel:WORD_1
	v_pk_fma_f32 v[216:217], v[82:83], v[232:233], v[216:217] op_sel_hi:[0,1,1]
	v_pk_fma_f32 v[218:219], v[82:83], v[234:235], v[218:219] op_sel_hi:[0,1,1]
	v_cvt_pk_f32_fp8_e32 v[236:237], v207
	v_cvt_pk_f32_fp8_sdwa v[238:239], v207 src0_sel:WORD_1
	v_pk_fma_f32 v[220:221], v[82:83], v[236:237], v[220:221] op_sel_hi:[0,1,1]
	v_pk_fma_f32 v[222:223], v[82:83], v[238:239], v[222:223] op_sel_hi:[0,1,1]
	v_cvt_pk_f32_fp8_e32 v[232:233], v208
	v_cvt_pk_f32_fp8_sdwa v[234:235], v208 src0_sel:WORD_1
	v_pk_fma_f32 v[224:225], v[82:83], v[232:233], v[224:225] op_sel_hi:[0,1,1]
	v_pk_fma_f32 v[226:227], v[82:83], v[234:235], v[226:227] op_sel_hi:[0,1,1]
	v_cvt_pk_f32_fp8_e32 v[236:237], v209
	v_cvt_pk_f32_fp8_sdwa v[238:239], v209 src0_sel:WORD_1
	v_pk_fma_f32 v[228:229], v[82:83], v[236:237], v[228:229] op_sel_hi:[0,1,1]
	v_pk_fma_f32 v[230:231], v[82:83], v[238:239], v[230:231] op_sel_hi:[0,1,1]
	s_waitcnt vmcnt(0)
	v_cvt_pk_f32_fp8_e32 v[232:233], v210
	v_cvt_pk_f32_fp8_sdwa v[234:235], v210 src0_sel:WORD_1
	v_pk_fma_f32 v[216:217], v[82:83], v[232:233], v[216:217] op_sel:[1,0,0]
	v_pk_fma_f32 v[218:219], v[82:83], v[234:235], v[218:219] op_sel:[1,0,0]
	v_cvt_pk_f32_fp8_e32 v[236:237], v211
	v_cvt_pk_f32_fp8_sdwa v[238:239], v211 src0_sel:WORD_1
	v_pk_fma_f32 v[220:221], v[82:83], v[236:237], v[220:221] op_sel:[1,0,0]
	v_pk_fma_f32 v[222:223], v[82:83], v[238:239], v[222:223] op_sel:[1,0,0]
	v_cvt_pk_f32_fp8_e32 v[232:233], v212
	v_cvt_pk_f32_fp8_sdwa v[234:235], v212 src0_sel:WORD_1
	v_pk_fma_f32 v[224:225], v[82:83], v[232:233], v[224:225] op_sel:[1,0,0]
	v_pk_fma_f32 v[226:227], v[82:83], v[234:235], v[226:227] op_sel:[1,0,0]
	v_cvt_pk_f32_fp8_e32 v[236:237], v213
	v_cvt_pk_f32_fp8_sdwa v[238:239], v213 src0_sel:WORD_1
	v_pk_fma_f32 v[228:229], v[82:83], v[236:237], v[228:229] op_sel:[1,0,0]
	v_pk_fma_f32 v[230:231], v[82:83], v[238:239], v[230:231] op_sel:[1,0,0]
	ds_read_b128 v[52:55], v6 offset:528
	ds_read_b128 v[56:59], v6 offset:544
	ds_read_b128 v[60:63], v6 offset:560
	ds_read_b128 v[64:67], v6 offset:576
	ds_read_b128 v[68:71], v6 offset:592
	ds_read_b128 v[72:75], v6 offset:608
	ds_read_b128 v[76:79], v6 offset:624
	ds_read_b128 v[80:83], v6 offset:640
	s_add_u32 s56, s14, s46
	s_addc_u32 s57, s15, 0
	s_nop 0
	v_permlane32_swap_b32_e32 v216, v224
	v_permlane32_swap_b32_e32 v217, v225
	v_permlane32_swap_b32_e32 v218, v226
	v_permlane32_swap_b32_e32 v219, v227
	v_permlane32_swap_b32_e32 v220, v228
	v_permlane32_swap_b32_e32 v221, v229
	v_permlane32_swap_b32_e32 v222, v230
	v_permlane32_swap_b32_e32 v223, v231
	v_pk_add_f32 v[216:217], v[216:217], v[224:225]
	v_pk_add_f32 v[218:219], v[218:219], v[226:227]
	v_pk_add_f32 v[220:221], v[220:221], v[228:229]
	v_pk_add_f32 v[222:223], v[222:223], v[230:231]
	s_nop 1
	v_permlane16_swap_b32_e32 v216, v220
	v_permlane16_swap_b32_e32 v217, v221
	v_permlane16_swap_b32_e32 v218, v222
	v_permlane16_swap_b32_e32 v219, v223
	v_pk_add_f32 v[216:217], v[216:217], v[220:221]
	v_pk_add_f32 v[218:219], v[218:219], v[222:223]
	v_cvt_pk_bf16_f32 v232, v216, v217
	v_cvt_pk_bf16_f32 v233, v218, v219
	global_store_dwordx2 v4, v[232:233], s[56:57]
	s_add_i32 s48, s48, 1
	s_add_i32 s34, s34, 4
	s_cmp_lt_u32 s48, s49
	s_cbranch_scc0 .Lp11_chunk_done
	s_cmp_lt_u32 s34, 8192
	s_cbranch_scc1 .Lp11_body
	s_branch .Lp11_slice_next
